# E20 + back-edge rotation in 11 GEMM K-loops: loop-control SALU (counter, pointer bumps, s_cmp) moved in front of the loop-back s_barrier instead of after it
# baseline (speedup 1.0000x reference)
; #define PG8_STAGE(bufoff, gbase, voff) do { _Pragma("unroll") for (int _i = 0; _i < 2; ++_i) \
;         __builtin_amdgcn_global_load_lds((const unsigned*)((const char*)(gbase) + (voff)[_i]), (PG8_LAS unsigned*)(lds + (bufoff) + ldsw + _i * 8192), 16, 0, 0); } while (0)
; #define PG8_LDA(dst, b, h) do { _Pragma("unroll") for (int m = 0; m < 4; ++m) _Pragma("unroll") for (int k = 0; k < 2; ++k) dst[m][k] = *(const PG8_LAS bf16x8*)(lds + PG8_SA(b, h) + aoff + m * 2048 + k * 1024); } while (0)
; #define PG8_LDB(dst, b, h) do { _Pragma("unroll") for (int n = 0; n < 2; ++n) _Pragma("unroll") for (int k = 0; k < 2; ++k) dst[n][k] = *(const PG8_LAS bf16x8*)(lds + PG8_SB(b, h) + boff + n * 2048 + k * 1024); } while (0)
; #define PG8_MMA(ai, bj, At, Bt) do { __builtin_amdgcn_s_setprio(1); _Pragma("unroll") for (int m = 0; m < 4; ++m) _Pragma("unroll") for (int n = 0; n < 2; ++n) _Pragma("unroll") for (int k = 0; k < 2; ++k) \
;         acc[ai][bj][m][n] = __builtin_amdgcn_mfma_f32_16x16x32_bf16(Bt[n][k], At[m][k], acc[ai][bj][m][n], 0, 0, 0); __builtin_amdgcn_s_setprio(0); } while (0)
; #define PG8_WAIT_V(n) asm volatile("s_waitcnt vmcnt(" #n ")" ::: "memory")
; #define PG8_BAR __builtin_amdgcn_s_barrier()
; template <class Epi, class Sched, bool ALIGN_EPI = false, bool SP2 = false>
; __device__ __forceinline__ void gemm_phase(PG8_LAS unsigned char* lds, const Gemm g, const Sched& S, const Epi& E) {
;     ...
;         for (int t = 0; t < nt; t += 2) {
;             const bool last = (t == nt - 2);
;             const char* a1 = cA + (size_t)(t + 1) * kstep;
;             const char* a2 = last ? nA : cA + (size_t)(t + 2) * kstep; const char* b2 = last ? nB : cB + (size_t)(t + 2) * kstep;
;             const char* a3 = a2 + kstep; const char* b3 = b2 + kstep;
;             if (last && has_next) S.a_ready(nxt);
;             if constexpr (SP2) {
;             PG8_LDB(B0, 0, 0); PG8_LDB(B1, 0, 1); PG8_SCHED; PG8_LDA(At, 0, 0); PG8_STAGE(PG8_SA(1, 1), a1 + hstep, voffA);
;             PG8_WAIT_V(8); PG8_WAIT_L(0); PG8_BAR; PG8_MMA(0, 0, At, B0); PG8_MMA(0, 1, At, B1); PG8_BAR; PG8_SCHED;
;             PG8_LDA(At, 0, 1); PG8_STAGE(PG8_SB(0, 0), b2, voffB); PG8_STAGE(PG8_SB(0, 1), b2 + hstep, voffB); PG8_STAGE(PG8_SA(0, 0), a2, voffA);
;             PG8_WAIT_V(8); PG8_WAIT_L(0); PG8_BAR; PG8_MMA(1, 0, At, B0); PG8_MMA(1, 1, At, B1); PG8_BAR; PG8_SCHED;
.LBB0_124:
	ds_read_b128 v[144:147], v151
	ds_read_b128 v[154:157], v151 offset:1024
	ds_read_b128 v[158:161], v151 offset:2048
	ds_read_b128 v[162:165], v151 offset:3072
	ds_read_b128 v[166:169], v152
	ds_read_b128 v[170:173], v152 offset:1024
	ds_read_b128 v[174:177], v152 offset:2048
	ds_read_b128 v[178:181], v152 offset:3072
	s_add_u32 s22, s20, 0xfffc0080
	s_addc_u32 s23, s21, -1
	s_cmp_eq_u32 s49, 12
	s_cselect_b32 s25, s13, s23
	s_cselect_b32 s24, s45, s22
	s_cselect_b32 s23, s11, s48
	s_cselect_b32 s22, s46, s47
	v_lshl_add_u64 v[182:183], s[20:21], 0, v[138:139]
	s_add_i32 m0, s19, 0xc000
	ds_read_b128 v[186:189], v153
	ds_read_b128 v[190:193], v153 offset:1024
	ds_read_b128 v[194:197], v153 offset:2048
	ds_read_b128 v[198:201], v153 offset:3072
	ds_read_b128 v[202:205], v153 offset:4096
	ds_read_b128 v[206:209], v153 offset:5120
	ds_read_b128 v[210:213], v153 offset:6144
	ds_read_b128 v[214:217], v153 offset:7168
	global_load_lds_dwordx4 v[182:183], off
	v_lshl_add_u64 v[182:183], s[20:21], 0, v[136:137]
	s_add_i32 m0, s19, 0xe000
	s_nop 0
	global_load_lds_dwordx4 v[182:183], off
	s_waitcnt vmcnt(8)
	s_waitcnt lgkmcnt(0)
	s_barrier
	s_setprio 1
	s_waitcnt lgkmcnt(0)
	v_mfma_f32_16x16x32_bf16 v[124:127], v[144:147], v[186:189], v[124:127]
	v_mfma_f32_16x16x32_bf16 v[116:119], v[158:161], v[186:189], v[116:119]
	v_mfma_f32_16x16x32_bf16 v[108:111], v[144:147], v[194:197], v[108:111]
	v_mfma_f32_16x16x32_bf16 v[100:103], v[158:161], v[194:197], v[100:103]
	v_mfma_f32_16x16x32_bf16 v[92:95], v[144:147], v[202:205], v[92:95]
	v_mfma_f32_16x16x32_bf16 v[84:87], v[158:161], v[202:205], v[84:87]
	v_mfma_f32_16x16x32_bf16 v[76:79], v[144:147], v[210:213], v[76:79]
	v_mfma_f32_16x16x32_bf16 v[68:71], v[158:161], v[210:213], v[68:71]
	v_mfma_f32_16x16x32_bf16 v[124:127], v[154:157], v[190:193], v[124:127]
	v_mfma_f32_16x16x32_bf16 v[116:119], v[162:165], v[190:193], v[116:119]
	v_mfma_f32_16x16x32_bf16 v[108:111], v[154:157], v[198:201], v[108:111]
	v_mfma_f32_16x16x32_bf16 v[100:103], v[162:165], v[198:201], v[100:103]
	v_mfma_f32_16x16x32_bf16 v[92:95], v[154:157], v[206:209], v[92:95]
	v_mfma_f32_16x16x32_bf16 v[84:87], v[162:165], v[206:209], v[84:87]
	v_mfma_f32_16x16x32_bf16 v[76:79], v[154:157], v[214:217], v[76:79]
	v_mfma_f32_16x16x32_bf16 v[68:71], v[162:165], v[214:217], v[68:71]
	s_setprio 0
	s_setprio 1
	v_mfma_f32_16x16x32_bf16 v[120:123], v[166:169], v[186:189], v[120:123]
	v_mfma_f32_16x16x32_bf16 v[112:115], v[174:177], v[186:189], v[112:115]
	v_mfma_f32_16x16x32_bf16 v[104:107], v[166:169], v[194:197], v[104:107]
	v_mfma_f32_16x16x32_bf16 v[96:99], v[174:177], v[194:197], v[96:99]
	v_mfma_f32_16x16x32_bf16 v[88:91], v[166:169], v[202:205], v[88:91]
	v_mfma_f32_16x16x32_bf16 v[80:83], v[174:177], v[202:205], v[80:83]
	v_mfma_f32_16x16x32_bf16 v[72:75], v[166:169], v[210:213], v[72:75]
	v_mfma_f32_16x16x32_bf16 v[64:67], v[174:177], v[210:213], v[64:67]
	v_mfma_f32_16x16x32_bf16 v[120:123], v[170:173], v[190:193], v[120:123]
	v_mfma_f32_16x16x32_bf16 v[112:115], v[178:181], v[190:193], v[112:115]
	v_mfma_f32_16x16x32_bf16 v[104:107], v[170:173], v[198:201], v[104:107]
	v_mfma_f32_16x16x32_bf16 v[96:99], v[178:181], v[198:201], v[96:99]
	v_mfma_f32_16x16x32_bf16 v[88:91], v[170:173], v[206:209], v[88:91]
	v_mfma_f32_16x16x32_bf16 v[80:83], v[178:181], v[206:209], v[80:83]
	v_mfma_f32_16x16x32_bf16 v[72:75], v[170:173], v[214:217], v[72:75]
	v_mfma_f32_16x16x32_bf16 v[64:67], v[178:181], v[214:217], v[64:67]
	s_setprio 0
	s_barrier
	s_add_i32 s50, s41, s31
	v_lshl_add_u64 v[182:183], s[22:23], 0, v[130:131]
	s_mov_b32 m0, s50
	ds_read_b128 v[186:189], v153 offset:16384
	ds_read_b128 v[190:193], v153 offset:17408
	ds_read_b128 v[194:197], v153 offset:18432
	ds_read_b128 v[198:201], v153 offset:19456
	ds_read_b128 v[202:205], v153 offset:20480
	ds_read_b128 v[206:209], v153 offset:21504
	ds_read_b128 v[210:213], v153 offset:22528
	ds_read_b128 v[214:217], v153 offset:23552
	global_load_lds_dwordx4 v[182:183], off
	s_add_i32 m0, s50, 0x2000
	s_add_u32 s50, s22, 0x40000
	v_lshl_add_u64 v[218:219], s[22:23], 0, v[134:135]
	s_addc_u32 s51, s23, 0
	s_add_i32 s52, s42, s31
	global_load_lds_dwordx4 v[218:219], off
	v_lshl_add_u64 v[220:221], s[50:51], 0, v[130:131]
	s_mov_b32 m0, s52
	v_lshl_add_u64 v[222:223], s[24:25], 0, v[132:133]
	global_load_lds_dwordx4 v[220:221], off
	v_lshl_add_u64 v[220:221], s[50:51], 0, v[134:135]
	s_add_i32 m0, s52, 0x2000
	s_nop 0
	global_load_lds_dwordx4 v[220:221], off
	v_lshl_add_u64 v[220:221], s[24:25], 0, v[128:129]
	s_mov_b32 m0, s19
	s_nop 0
	global_load_lds_dwordx4 v[220:221], off
	s_mov_b32 m0, s33
	s_nop 0
	global_load_lds_dwordx4 v[222:223], off
	s_waitcnt vmcnt(8)
	s_waitcnt lgkmcnt(0)
	s_barrier
; #define PG8_STAGE(bufoff, gbase, voff) do { _Pragma("unroll") for (int _i = 0; _i < 2; ++_i) \
;         __builtin_amdgcn_global_load_lds((const unsigned*)((const char*)(gbase) + (voff)[_i]), (PG8_LAS unsigned*)(lds + (bufoff) + ldsw + _i * 8192), 16, 0, 0); } while (0)
; #define PG8_LDA(dst, b, h) do { _Pragma("unroll") for (int m = 0; m < 4; ++m) _Pragma("unroll") for (int k = 0; k < 2; ++k) dst[m][k] = *(const PG8_LAS bf16x8*)(lds + PG8_SA(b, h) + aoff + m * 2048 + k * 1024); } while (0)
; #define PG8_LDB(dst, b, h) do { _Pragma("unroll") for (int n = 0; n < 2; ++n) _Pragma("unroll") for (int k = 0; k < 2; ++k) dst[n][k] = *(const PG8_LAS bf16x8*)(lds + PG8_SB(b, h) + boff + n * 2048 + k * 1024); } while (0)
; #define PG8_MMA(ai, bj, At, Bt) do { __builtin_amdgcn_s_setprio(1); _Pragma("unroll") for (int m = 0; m < 4; ++m) _Pragma("unroll") for (int n = 0; n < 2; ++n) _Pragma("unroll") for (int k = 0; k < 2; ++k) \
;         acc[ai][bj][m][n] = __builtin_amdgcn_mfma_f32_16x16x32_bf16(Bt[n][k], At[m][k], acc[ai][bj][m][n], 0, 0, 0); __builtin_amdgcn_s_setprio(0); } while (0)
; #define PG8_WAIT_V(n) asm volatile("s_waitcnt vmcnt(" #n ")" ::: "memory")
; #define PG8_WAIT_L(n) asm volatile("s_waitcnt lgkmcnt(" #n ")" ::: "memory")
; #define PG8_BAR __builtin_amdgcn_s_barrier()
; #define PG8_SCHED __builtin_amdgcn_sched_barrier(0)
; template <class Epi, class Sched, bool ALIGN_EPI = false, bool SP2 = false>
; __device__ __forceinline__ void gemm_phase(PG8_LAS unsigned char* lds, const Gemm g, const Sched& S, const Epi& E) {
;     ...
;             PG8_WAIT_V(8); PG8_WAIT_L(0); PG8_BAR; PG8_MMA(1, 0, At, B0); PG8_MMA(1, 1, At, B1); PG8_BAR; PG8_SCHED;
;             PG8_LDB(B0, 1, 0); PG8_LDB(B1, 1, 1); PG8_SCHED; PG8_LDA(At, 1, 0); PG8_STAGE(PG8_SA(0, 1), a2 + hstep, voffA);
;             PG8_WAIT_V(8); PG8_WAIT_L(0); PG8_BAR; PG8_MMA(0, 0, At, B0); PG8_MMA(0, 1, At, B1); PG8_BAR; PG8_SCHED;
	s_setprio 1
	s_waitcnt lgkmcnt(0)
	v_mfma_f32_16x16x32_bf16 v[60:63], v[144:147], v[186:189], v[60:63]
	v_mfma_f32_16x16x32_bf16 v[52:55], v[158:161], v[186:189], v[52:55]
	v_mfma_f32_16x16x32_bf16 v[44:47], v[144:147], v[194:197], v[44:47]
	v_mfma_f32_16x16x32_bf16 v[36:39], v[158:161], v[194:197], v[36:39]
	v_mfma_f32_16x16x32_bf16 v[28:31], v[144:147], v[202:205], v[28:31]
	v_mfma_f32_16x16x32_bf16 v[20:23], v[158:161], v[202:205], v[20:23]
	v_mfma_f32_16x16x32_bf16 v[12:15], v[144:147], v[210:213], v[12:15]
	v_mfma_f32_16x16x32_bf16 v[4:7], v[158:161], v[210:213], v[4:7]
	v_mfma_f32_16x16x32_bf16 v[60:63], v[154:157], v[190:193], v[60:63]
	v_mfma_f32_16x16x32_bf16 v[52:55], v[162:165], v[190:193], v[52:55]
	v_mfma_f32_16x16x32_bf16 v[44:47], v[154:157], v[198:201], v[44:47]
	v_mfma_f32_16x16x32_bf16 v[36:39], v[162:165], v[198:201], v[36:39]
	v_mfma_f32_16x16x32_bf16 v[28:31], v[154:157], v[206:209], v[28:31]
	v_mfma_f32_16x16x32_bf16 v[20:23], v[162:165], v[206:209], v[20:23]
	v_mfma_f32_16x16x32_bf16 v[12:15], v[154:157], v[214:217], v[12:15]
	v_mfma_f32_16x16x32_bf16 v[4:7], v[162:165], v[214:217], v[4:7]
	s_setprio 0
	s_setprio 1
	v_mfma_f32_16x16x32_bf16 v[56:59], v[166:169], v[186:189], v[56:59]
	v_mfma_f32_16x16x32_bf16 v[48:51], v[174:177], v[186:189], v[48:51]
	v_mfma_f32_16x16x32_bf16 v[40:43], v[166:169], v[194:197], v[40:43]
	v_mfma_f32_16x16x32_bf16 v[32:35], v[174:177], v[194:197], v[32:35]
	v_mfma_f32_16x16x32_bf16 v[24:27], v[166:169], v[202:205], v[24:27]
	v_mfma_f32_16x16x32_bf16 v[16:19], v[174:177], v[202:205], v[16:19]
	v_mfma_f32_16x16x32_bf16 v[8:11], v[166:169], v[210:213], v[8:11]
	v_mfma_f32_16x16x32_bf16 v[0:3], v[174:177], v[210:213], v[0:3]
	v_mfma_f32_16x16x32_bf16 v[56:59], v[170:173], v[190:193], v[56:59]
	v_mfma_f32_16x16x32_bf16 v[48:51], v[178:181], v[190:193], v[48:51]
	v_mfma_f32_16x16x32_bf16 v[40:43], v[170:173], v[198:201], v[40:43]
	v_mfma_f32_16x16x32_bf16 v[32:35], v[178:181], v[198:201], v[32:35]
	v_mfma_f32_16x16x32_bf16 v[24:27], v[170:173], v[206:209], v[24:27]
	v_mfma_f32_16x16x32_bf16 v[16:19], v[178:181], v[206:209], v[16:19]
	v_mfma_f32_16x16x32_bf16 v[8:11], v[170:173], v[214:217], v[8:11]
	v_mfma_f32_16x16x32_bf16 v[0:3], v[178:181], v[214:217], v[0:3]
	s_setprio 0
	s_barrier
	s_add_i32 s50, 0, 0x18000
	s_add_i32 s51, 0, 0x1c000
	v_add_u32_e32 v162, s50, v149
	v_add_u32_e32 v178, s51, v149
	ds_read_b128 v[144:147], v162
	ds_read_b128 v[154:157], v162 offset:1024
	ds_read_b128 v[158:161], v162 offset:2048
	ds_read_b128 v[162:165], v162 offset:3072
	ds_read_b128 v[166:169], v178
	ds_read_b128 v[170:173], v178 offset:1024
	ds_read_b128 v[174:177], v178 offset:2048
	ds_read_b128 v[178:181], v178 offset:3072
	s_add_u32 s24, s24, 0x40000
	s_addc_u32 s25, s25, 0
	s_mov_b32 m0, s34
	v_lshl_add_u64 v[224:225], s[24:25], 0, v[128:129]
	ds_read_b128 v[186:189], v153 offset:32768
	ds_read_b128 v[190:193], v153 offset:33792
	ds_read_b128 v[194:197], v153 offset:34816
	ds_read_b128 v[198:201], v153 offset:35840
	ds_read_b128 v[202:205], v153 offset:36864
	ds_read_b128 v[206:209], v153 offset:37888
	ds_read_b128 v[210:213], v153 offset:38912
	ds_read_b128 v[214:217], v153 offset:39936
	global_load_lds_dwordx4 v[224:225], off
	v_lshl_add_u64 v[224:225], s[24:25], 0, v[132:133]
	s_mov_b32 m0, s35
	s_nop 0
	global_load_lds_dwordx4 v[224:225], off
	s_waitcnt vmcnt(8)
	s_waitcnt lgkmcnt(0)
	s_barrier
	s_setprio 1
	s_waitcnt lgkmcnt(0)
	v_mfma_f32_16x16x32_bf16 v[124:127], v[144:147], v[186:189], v[124:127]
	v_mfma_f32_16x16x32_bf16 v[116:119], v[158:161], v[186:189], v[116:119]
	v_mfma_f32_16x16x32_bf16 v[108:111], v[144:147], v[194:197], v[108:111]
	v_mfma_f32_16x16x32_bf16 v[100:103], v[158:161], v[194:197], v[100:103]
	v_mfma_f32_16x16x32_bf16 v[92:95], v[144:147], v[202:205], v[92:95]
	v_mfma_f32_16x16x32_bf16 v[84:87], v[158:161], v[202:205], v[84:87]
	v_mfma_f32_16x16x32_bf16 v[76:79], v[144:147], v[210:213], v[76:79]
	v_mfma_f32_16x16x32_bf16 v[68:71], v[158:161], v[210:213], v[68:71]
	v_mfma_f32_16x16x32_bf16 v[124:127], v[154:157], v[190:193], v[124:127]
	v_mfma_f32_16x16x32_bf16 v[116:119], v[162:165], v[190:193], v[116:119]
	v_mfma_f32_16x16x32_bf16 v[108:111], v[154:157], v[198:201], v[108:111]
	v_mfma_f32_16x16x32_bf16 v[100:103], v[162:165], v[198:201], v[100:103]
	v_mfma_f32_16x16x32_bf16 v[92:95], v[154:157], v[206:209], v[92:95]
	v_mfma_f32_16x16x32_bf16 v[84:87], v[162:165], v[206:209], v[84:87]
	v_mfma_f32_16x16x32_bf16 v[76:79], v[154:157], v[214:217], v[76:79]
	v_mfma_f32_16x16x32_bf16 v[68:71], v[162:165], v[214:217], v[68:71]
	s_setprio 0
	s_setprio 1
	v_mfma_f32_16x16x32_bf16 v[120:123], v[166:169], v[186:189], v[120:123]
	v_mfma_f32_16x16x32_bf16 v[112:115], v[174:177], v[186:189], v[112:115]
	v_mfma_f32_16x16x32_bf16 v[104:107], v[166:169], v[194:197], v[104:107]
	v_mfma_f32_16x16x32_bf16 v[96:99], v[174:177], v[194:197], v[96:99]
	v_mfma_f32_16x16x32_bf16 v[88:91], v[166:169], v[202:205], v[88:91]
	v_mfma_f32_16x16x32_bf16 v[80:83], v[174:177], v[202:205], v[80:83]
	v_mfma_f32_16x16x32_bf16 v[72:75], v[166:169], v[210:213], v[72:75]
	v_mfma_f32_16x16x32_bf16 v[64:67], v[174:177], v[210:213], v[64:67]
	v_mfma_f32_16x16x32_bf16 v[120:123], v[170:173], v[190:193], v[120:123]
	v_mfma_f32_16x16x32_bf16 v[112:115], v[178:181], v[190:193], v[112:115]
	v_mfma_f32_16x16x32_bf16 v[104:107], v[170:173], v[198:201], v[104:107]
	v_mfma_f32_16x16x32_bf16 v[96:99], v[178:181], v[198:201], v[96:99]
	v_mfma_f32_16x16x32_bf16 v[88:91], v[170:173], v[206:209], v[88:91]
	v_mfma_f32_16x16x32_bf16 v[80:83], v[178:181], v[206:209], v[80:83]
	v_mfma_f32_16x16x32_bf16 v[72:75], v[170:173], v[214:217], v[72:75]
	v_mfma_f32_16x16x32_bf16 v[64:67], v[178:181], v[214:217], v[64:67]
	s_setprio 0
	s_barrier
; #define PG8_STAGE(bufoff, gbase, voff) do { _Pragma("unroll") for (int _i = 0; _i < 2; ++_i) \
;         __builtin_amdgcn_global_load_lds((const unsigned*)((const char*)(gbase) + (voff)[_i]), (PG8_LAS unsigned*)(lds + (bufoff) + ldsw + _i * 8192), 16, 0, 0); } while (0)
; #define PG8_LDA(dst, b, h) do { _Pragma("unroll") for (int m = 0; m < 4; ++m) _Pragma("unroll") for (int k = 0; k < 2; ++k) dst[m][k] = *(const PG8_LAS bf16x8*)(lds + PG8_SA(b, h) + aoff + m * 2048 + k * 1024); } while (0)
; #define PG8_MMA(ai, bj, At, Bt) do { __builtin_amdgcn_s_setprio(1); _Pragma("unroll") for (int m = 0; m < 4; ++m) _Pragma("unroll") for (int n = 0; n < 2; ++n) _Pragma("unroll") for (int k = 0; k < 2; ++k) \
;         acc[ai][bj][m][n] = __builtin_amdgcn_mfma_f32_16x16x32_bf16(Bt[n][k], At[m][k], acc[ai][bj][m][n], 0, 0, 0); __builtin_amdgcn_s_setprio(0); } while (0)
; #define PG8_WAIT_V(n) asm volatile("s_waitcnt vmcnt(" #n ")" ::: "memory")
; #define PG8_WAIT_L(n) asm volatile("s_waitcnt lgkmcnt(" #n ")" ::: "memory")
; #define PG8_BAR __builtin_amdgcn_s_barrier()
; #define PG8_SCHED __builtin_amdgcn_sched_barrier(0)
; template <class Epi, class Sched, bool ALIGN_EPI = false, bool SP2 = false>
; __device__ __forceinline__ void gemm_phase(PG8_LAS unsigned char* lds, const Gemm g, const Sched& S, const Epi& E) {
;     ...
;         for (int t = 0; t < nt; t += 2) {
;             const bool last = (t == nt - 2);
;             const char* a1 = cA + (size_t)(t + 1) * kstep;
;             const char* a2 = last ? nA : cA + (size_t)(t + 2) * kstep; const char* b2 = last ? nB : cB + (size_t)(t + 2) * kstep;
;             const char* a3 = a2 + kstep; const char* b3 = b2 + kstep;
;     ...
;             PG8_LDA(At, 1, 1); PG8_STAGE(PG8_SB(1, 0), b3, voffB); PG8_STAGE(PG8_SB(1, 1), b3 + hstep, voffB); PG8_STAGE(PG8_SA(1, 0), a3, voffA);
;             PG8_WAIT_V(8); PG8_WAIT_L(0); PG8_BAR; PG8_MMA(1, 0, At, B0); PG8_MMA(1, 1, At, B1); PG8_BAR; PG8_SCHED;
	s_add_i32 s24, s50, s31
	v_lshl_add_u64 v[182:183], v[182:183], 0, s[6:7]
	s_mov_b32 m0, s24
	ds_read_b128 v[186:189], v153 offset:49152
	ds_read_b128 v[190:193], v153 offset:50176
	ds_read_b128 v[194:197], v153 offset:51200
	ds_read_b128 v[198:201], v153 offset:52224
	ds_read_b128 v[202:205], v153 offset:53248
	ds_read_b128 v[206:209], v153 offset:54272
	ds_read_b128 v[210:213], v153 offset:55296
	ds_read_b128 v[214:217], v153 offset:56320
	global_load_lds_dwordx4 v[182:183], off
	s_add_i32 m0, s24, 0x2000
	s_add_u32 s22, s22, 0x40080
	v_lshl_add_u64 v[182:183], v[218:219], 0, s[6:7]
	s_addc_u32 s23, s23, 0
	s_add_i32 s24, s51, s31
	global_load_lds_dwordx4 v[182:183], off
	v_lshl_add_u64 v[182:183], s[22:23], 0, v[130:131]
	s_mov_b32 m0, s24
	s_nop 0
	global_load_lds_dwordx4 v[182:183], off
	v_lshl_add_u64 v[182:183], s[22:23], 0, v[134:135]
	s_add_i32 m0, s24, 0x2000
	s_nop 0
	global_load_lds_dwordx4 v[182:183], off
	v_lshl_add_u64 v[182:183], v[220:221], 0, s[6:7]
	s_mov_b32 m0, s37
	s_nop 0
	global_load_lds_dwordx4 v[182:183], off
	v_lshl_add_u64 v[182:183], v[222:223], 0, s[6:7]
	s_mov_b32 m0, s38
	s_nop 0
	global_load_lds_dwordx4 v[182:183], off
	s_waitcnt vmcnt(8)
	s_waitcnt lgkmcnt(0)
	s_barrier
	s_setprio 1
	s_waitcnt lgkmcnt(0)
	v_mfma_f32_16x16x32_bf16 v[60:63], v[144:147], v[186:189], v[60:63]
	v_mfma_f32_16x16x32_bf16 v[52:55], v[158:161], v[186:189], v[52:55]
	v_mfma_f32_16x16x32_bf16 v[44:47], v[144:147], v[194:197], v[44:47]
	v_mfma_f32_16x16x32_bf16 v[36:39], v[158:161], v[194:197], v[36:39]
	v_mfma_f32_16x16x32_bf16 v[28:31], v[144:147], v[202:205], v[28:31]
	v_mfma_f32_16x16x32_bf16 v[20:23], v[158:161], v[202:205], v[20:23]
	v_mfma_f32_16x16x32_bf16 v[12:15], v[144:147], v[210:213], v[12:15]
	v_mfma_f32_16x16x32_bf16 v[4:7], v[158:161], v[210:213], v[4:7]
	v_mfma_f32_16x16x32_bf16 v[60:63], v[154:157], v[190:193], v[60:63]
	v_mfma_f32_16x16x32_bf16 v[52:55], v[162:165], v[190:193], v[52:55]
	v_mfma_f32_16x16x32_bf16 v[44:47], v[154:157], v[198:201], v[44:47]
	v_mfma_f32_16x16x32_bf16 v[36:39], v[162:165], v[198:201], v[36:39]
	v_mfma_f32_16x16x32_bf16 v[28:31], v[154:157], v[206:209], v[28:31]
	v_mfma_f32_16x16x32_bf16 v[20:23], v[162:165], v[206:209], v[20:23]
	v_mfma_f32_16x16x32_bf16 v[12:15], v[154:157], v[214:217], v[12:15]
	v_mfma_f32_16x16x32_bf16 v[4:7], v[162:165], v[214:217], v[4:7]
	s_setprio 0
	s_setprio 1
	v_mfma_f32_16x16x32_bf16 v[56:59], v[166:169], v[186:189], v[56:59]
	v_mfma_f32_16x16x32_bf16 v[48:51], v[174:177], v[186:189], v[48:51]
	v_mfma_f32_16x16x32_bf16 v[40:43], v[166:169], v[194:197], v[40:43]
	v_mfma_f32_16x16x32_bf16 v[32:35], v[174:177], v[194:197], v[32:35]
	v_mfma_f32_16x16x32_bf16 v[24:27], v[166:169], v[202:205], v[24:27]
	v_mfma_f32_16x16x32_bf16 v[16:19], v[174:177], v[202:205], v[16:19]
	v_mfma_f32_16x16x32_bf16 v[8:11], v[166:169], v[210:213], v[8:11]
	v_mfma_f32_16x16x32_bf16 v[0:3], v[174:177], v[210:213], v[0:3]
	v_mfma_f32_16x16x32_bf16 v[56:59], v[170:173], v[190:193], v[56:59]
	v_mfma_f32_16x16x32_bf16 v[48:51], v[178:181], v[190:193], v[48:51]
	v_mfma_f32_16x16x32_bf16 v[40:43], v[170:173], v[198:201], v[40:43]
	v_mfma_f32_16x16x32_bf16 v[32:35], v[178:181], v[198:201], v[32:35]
	v_mfma_f32_16x16x32_bf16 v[24:27], v[170:173], v[206:209], v[24:27]
	v_mfma_f32_16x16x32_bf16 v[16:19], v[178:181], v[206:209], v[16:19]
	v_mfma_f32_16x16x32_bf16 v[8:11], v[170:173], v[214:217], v[8:11]
	v_mfma_f32_16x16x32_bf16 v[0:3], v[178:181], v[214:217], v[0:3]
	s_setprio 0
	s_add_i32 s49, s49, 2
	s_add_u32 s47, s47, 0x100
	s_addc_u32 s48, s48, 0
	s_add_u32 s20, s20, 0x100
	s_addc_u32 s21, s21, 0
	s_cmp_gt_u32 s49, 13
	s_barrier
	s_cbranch_scc0 .LBB0_124
	s_and_b64 vcc, exec, s[8:9]
	s_cbranch_vccz .LBB0_127
	s_barrier

; #define PG8_STAGE(bufoff, gbase, voff) do { _Pragma("unroll") for (int _i = 0; _i < 2; ++_i) \
;         __builtin_amdgcn_global_load_lds((const unsigned*)((const char*)(gbase) + (voff)[_i]), (PG8_LAS unsigned*)(lds + (bufoff) + ldsw + _i * 8192), 16, 0, 0); } while (0)
; #define PG8_LDA(dst, b, h) do { _Pragma("unroll") for (int m = 0; m < 4; ++m) _Pragma("unroll") for (int k = 0; k < 2; ++k) dst[m][k] = *(const PG8_LAS bf16x8*)(lds + PG8_SA(b, h) + aoff + m * 2048 + k * 1024); } while (0)
; #define PG8_LDB(dst, b, h) do { _Pragma("unroll") for (int n = 0; n < 2; ++n) _Pragma("unroll") for (int k = 0; k < 2; ++k) dst[n][k] = *(const PG8_LAS bf16x8*)(lds + PG8_SB(b, h) + boff + n * 2048 + k * 1024); } while (0)
; #define PG8_MMA(ai, bj, At, Bt) do { __builtin_amdgcn_s_setprio(1); _Pragma("unroll") for (int m = 0; m < 4; ++m) _Pragma("unroll") for (int n = 0; n < 2; ++n) _Pragma("unroll") for (int k = 0; k < 2; ++k) \
;         acc[ai][bj][m][n] = __builtin_amdgcn_mfma_f32_16x16x32_bf16(Bt[n][k], At[m][k], acc[ai][bj][m][n], 0, 0, 0); __builtin_amdgcn_s_setprio(0); } while (0)
; #define PG8_WAIT_V(n) asm volatile("s_waitcnt vmcnt(" #n ")" ::: "memory")
; #define PG8_BAR __builtin_amdgcn_s_barrier()
; template <class Epi, class Sched, bool ALIGN_EPI = false, bool SP2 = false>
; __device__ __forceinline__ void gemm_phase(PG8_LAS unsigned char* lds, const Gemm g, const Sched& S, const Epi& E) {
;     ...
;         for (int t = 0; t < nt; t += 2) {
;             const bool last = (t == nt - 2);
;             const char* a1 = cA + (size_t)(t + 1) * kstep;
;             const char* a2 = last ? nA : cA + (size_t)(t + 2) * kstep; const char* b2 = last ? nB : cB + (size_t)(t + 2) * kstep;
;             const char* a3 = a2 + kstep; const char* b3 = b2 + kstep;
;             if (last && has_next) S.a_ready(nxt);
;             if constexpr (SP2) {
;             PG8_LDB(B0, 0, 0); PG8_LDB(B1, 0, 1); PG8_SCHED; PG8_LDA(At, 0, 0); PG8_STAGE(PG8_SA(1, 1), a1 + hstep, voffA);
;             PG8_WAIT_V(8); PG8_WAIT_L(0); PG8_BAR; PG8_MMA(0, 0, At, B0); PG8_MMA(0, 1, At, B1); PG8_BAR; PG8_SCHED;
;             PG8_LDA(At, 0, 1); PG8_STAGE(PG8_SB(0, 0), b2, voffB); PG8_STAGE(PG8_SB(0, 1), b2 + hstep, voffB); PG8_STAGE(PG8_SA(0, 0), a2, voffA);
;             PG8_WAIT_V(8); PG8_WAIT_L(0); PG8_BAR; PG8_MMA(1, 0, At, B0); PG8_MMA(1, 1, At, B1); PG8_BAR; PG8_SCHED;
.LBB0_196:
	ds_read_b128 v[152:155], v149
	ds_read_b128 v[156:159], v149 offset:1024
	ds_read_b128 v[160:163], v149 offset:2048
	ds_read_b128 v[164:167], v149 offset:3072
	ds_read_b128 v[168:171], v150
	ds_read_b128 v[172:175], v150 offset:1024
	ds_read_b128 v[176:179], v150 offset:2048
	ds_read_b128 v[180:183], v150 offset:3072
	s_add_u32 s24, s22, 0x100
	s_addc_u32 s25, s23, 0
	s_cmp_eq_u32 s58, 40
	s_cselect_b32 s29, s5, s25
	s_cselect_b32 s28, s4, s24
	s_cselect_b32 s27, s21, s57
	s_cselect_b32 s26, s20, s56
	v_lshl_add_u64 v[144:145], s[22:23], 0, v[138:139]
	s_add_i32 m0, s37, 0xc000
	ds_read_b128 v[186:189], v151
	ds_read_b128 v[190:193], v151 offset:1024
	ds_read_b128 v[194:197], v151 offset:2048
	ds_read_b128 v[198:201], v151 offset:3072
	ds_read_b128 v[202:205], v151 offset:4096
	ds_read_b128 v[206:209], v151 offset:5120
	ds_read_b128 v[210:213], v151 offset:6144
	ds_read_b128 v[214:217], v151 offset:7168
	global_load_lds_dwordx4 v[144:145], off
	v_lshl_add_u64 v[144:145], s[22:23], 0, v[136:137]
	s_add_i32 m0, s37, 0xe000
	s_nop 0
	global_load_lds_dwordx4 v[144:145], off
	s_waitcnt vmcnt(8)
	s_waitcnt lgkmcnt(0)
	s_barrier
	s_setprio 1
	s_waitcnt lgkmcnt(0)
	v_mfma_f32_16x16x32_bf16 v[124:127], v[152:155], v[186:189], v[124:127]
	v_mfma_f32_16x16x32_bf16 v[120:123], v[160:163], v[186:189], v[120:123]
	v_mfma_f32_16x16x32_bf16 v[116:119], v[152:155], v[194:197], v[116:119]
	v_mfma_f32_16x16x32_bf16 v[108:111], v[160:163], v[194:197], v[108:111]
	v_mfma_f32_16x16x32_bf16 v[100:103], v[152:155], v[202:205], v[100:103]
	v_mfma_f32_16x16x32_bf16 v[92:95], v[160:163], v[202:205], v[92:95]
	v_mfma_f32_16x16x32_bf16 v[84:87], v[152:155], v[210:213], v[84:87]
	v_mfma_f32_16x16x32_bf16 v[76:79], v[160:163], v[210:213], v[76:79]
	v_mfma_f32_16x16x32_bf16 v[124:127], v[156:159], v[190:193], v[124:127]
	v_mfma_f32_16x16x32_bf16 v[120:123], v[164:167], v[190:193], v[120:123]
	v_mfma_f32_16x16x32_bf16 v[116:119], v[156:159], v[198:201], v[116:119]
	v_mfma_f32_16x16x32_bf16 v[108:111], v[164:167], v[198:201], v[108:111]
	v_mfma_f32_16x16x32_bf16 v[100:103], v[156:159], v[206:209], v[100:103]
	v_mfma_f32_16x16x32_bf16 v[92:95], v[164:167], v[206:209], v[92:95]
	v_mfma_f32_16x16x32_bf16 v[84:87], v[156:159], v[214:217], v[84:87]
	v_mfma_f32_16x16x32_bf16 v[76:79], v[164:167], v[214:217], v[76:79]
	s_setprio 0
	s_setprio 1
	v_mfma_f32_16x16x32_bf16 v[112:115], v[168:171], v[186:189], v[112:115]
	v_mfma_f32_16x16x32_bf16 v[104:107], v[176:179], v[186:189], v[104:107]
	v_mfma_f32_16x16x32_bf16 v[96:99], v[168:171], v[194:197], v[96:99]
	v_mfma_f32_16x16x32_bf16 v[88:91], v[176:179], v[194:197], v[88:91]
	v_mfma_f32_16x16x32_bf16 v[80:83], v[168:171], v[202:205], v[80:83]
	v_mfma_f32_16x16x32_bf16 v[72:75], v[176:179], v[202:205], v[72:75]
	v_mfma_f32_16x16x32_bf16 v[68:71], v[168:171], v[210:213], v[68:71]
	v_mfma_f32_16x16x32_bf16 v[64:67], v[176:179], v[210:213], v[64:67]
	v_mfma_f32_16x16x32_bf16 v[112:115], v[172:175], v[190:193], v[112:115]
	v_mfma_f32_16x16x32_bf16 v[104:107], v[180:183], v[190:193], v[104:107]
	v_mfma_f32_16x16x32_bf16 v[96:99], v[172:175], v[198:201], v[96:99]
	v_mfma_f32_16x16x32_bf16 v[88:91], v[180:183], v[198:201], v[88:91]
	v_mfma_f32_16x16x32_bf16 v[80:83], v[172:175], v[206:209], v[80:83]
	v_mfma_f32_16x16x32_bf16 v[72:75], v[180:183], v[206:209], v[72:75]
	v_mfma_f32_16x16x32_bf16 v[68:71], v[172:175], v[214:217], v[68:71]
	v_mfma_f32_16x16x32_bf16 v[64:67], v[180:183], v[214:217], v[64:67]
	s_setprio 0
	s_barrier
	s_add_i32 s22, s46, s36
	v_lshl_add_u64 v[144:145], s[26:27], 0, v[130:131]
	s_mov_b32 m0, s22
	ds_read_b128 v[186:189], v151 offset:16384
	ds_read_b128 v[190:193], v151 offset:17408
	ds_read_b128 v[194:197], v151 offset:18432
	ds_read_b128 v[198:201], v151 offset:19456
	ds_read_b128 v[202:205], v151 offset:20480
	ds_read_b128 v[206:209], v151 offset:21504
	ds_read_b128 v[210:213], v151 offset:22528
	ds_read_b128 v[214:217], v151 offset:23552
	global_load_lds_dwordx4 v[144:145], off
	s_add_i32 m0, s22, 0x2000
	s_add_u32 s22, s26, 0xb0000
	v_lshl_add_u64 v[218:219], s[26:27], 0, v[134:135]
	s_addc_u32 s23, s27, 0
	s_add_i32 s59, s47, s36
	global_load_lds_dwordx4 v[218:219], off
	v_lshl_add_u64 v[220:221], s[22:23], 0, v[130:131]
	s_mov_b32 m0, s59
	v_lshl_add_u64 v[222:223], s[28:29], 0, v[132:133]
	global_load_lds_dwordx4 v[220:221], off
	v_lshl_add_u64 v[220:221], s[22:23], 0, v[134:135]
	s_add_i32 m0, s59, 0x2000
	s_nop 0
	global_load_lds_dwordx4 v[220:221], off
	v_lshl_add_u64 v[220:221], s[28:29], 0, v[128:129]
	s_mov_b32 m0, s37
	s_nop 0
	global_load_lds_dwordx4 v[220:221], off
	s_mov_b32 m0, s38
	s_nop 0
	global_load_lds_dwordx4 v[222:223], off
	s_waitcnt vmcnt(8)
	s_waitcnt lgkmcnt(0)
	s_barrier
; #define PG8_STAGE(bufoff, gbase, voff) do { _Pragma("unroll") for (int _i = 0; _i < 2; ++_i) \
;         __builtin_amdgcn_global_load_lds((const unsigned*)((const char*)(gbase) + (voff)[_i]), (PG8_LAS unsigned*)(lds + (bufoff) + ldsw + _i * 8192), 16, 0, 0); } while (0)
; #define PG8_LDA(dst, b, h) do { _Pragma("unroll") for (int m = 0; m < 4; ++m) _Pragma("unroll") for (int k = 0; k < 2; ++k) dst[m][k] = *(const PG8_LAS bf16x8*)(lds + PG8_SA(b, h) + aoff + m * 2048 + k * 1024); } while (0)
; #define PG8_LDB(dst, b, h) do { _Pragma("unroll") for (int n = 0; n < 2; ++n) _Pragma("unroll") for (int k = 0; k < 2; ++k) dst[n][k] = *(const PG8_LAS bf16x8*)(lds + PG8_SB(b, h) + boff + n * 2048 + k * 1024); } while (0)
; #define PG8_MMA(ai, bj, At, Bt) do { __builtin_amdgcn_s_setprio(1); _Pragma("unroll") for (int m = 0; m < 4; ++m) _Pragma("unroll") for (int n = 0; n < 2; ++n) _Pragma("unroll") for (int k = 0; k < 2; ++k) \
;         acc[ai][bj][m][n] = __builtin_amdgcn_mfma_f32_16x16x32_bf16(Bt[n][k], At[m][k], acc[ai][bj][m][n], 0, 0, 0); __builtin_amdgcn_s_setprio(0); } while (0)
; #define PG8_WAIT_V(n) asm volatile("s_waitcnt vmcnt(" #n ")" ::: "memory")
; #define PG8_WAIT_L(n) asm volatile("s_waitcnt lgkmcnt(" #n ")" ::: "memory")
; #define PG8_BAR __builtin_amdgcn_s_barrier()
; #define PG8_SCHED __builtin_amdgcn_sched_barrier(0)
; template <class Epi, class Sched, bool ALIGN_EPI = false, bool SP2 = false>
; __device__ __forceinline__ void gemm_phase(PG8_LAS unsigned char* lds, const Gemm g, const Sched& S, const Epi& E) {
;     ...
;             PG8_WAIT_V(8); PG8_WAIT_L(0); PG8_BAR; PG8_MMA(1, 0, At, B0); PG8_MMA(1, 1, At, B1); PG8_BAR; PG8_SCHED;
;             PG8_LDB(B0, 1, 0); PG8_LDB(B1, 1, 1); PG8_SCHED; PG8_LDA(At, 1, 0); PG8_STAGE(PG8_SA(0, 1), a2 + hstep, voffA);
;             PG8_WAIT_V(8); PG8_WAIT_L(0); PG8_BAR; PG8_MMA(0, 0, At, B0); PG8_MMA(0, 1, At, B1); PG8_BAR; PG8_SCHED;
	s_setprio 1
	s_waitcnt lgkmcnt(0)
	v_mfma_f32_16x16x32_bf16 v[60:63], v[152:155], v[186:189], v[60:63]
	v_mfma_f32_16x16x32_bf16 v[56:59], v[160:163], v[186:189], v[56:59]
	v_mfma_f32_16x16x32_bf16 v[52:55], v[152:155], v[194:197], v[52:55]
	v_mfma_f32_16x16x32_bf16 v[44:47], v[160:163], v[194:197], v[44:47]
	v_mfma_f32_16x16x32_bf16 v[36:39], v[152:155], v[202:205], v[36:39]
	v_mfma_f32_16x16x32_bf16 v[28:31], v[160:163], v[202:205], v[28:31]
	v_mfma_f32_16x16x32_bf16 v[20:23], v[152:155], v[210:213], v[20:23]
	v_mfma_f32_16x16x32_bf16 v[12:15], v[160:163], v[210:213], v[12:15]
	v_mfma_f32_16x16x32_bf16 v[60:63], v[156:159], v[190:193], v[60:63]
	v_mfma_f32_16x16x32_bf16 v[56:59], v[164:167], v[190:193], v[56:59]
	v_mfma_f32_16x16x32_bf16 v[52:55], v[156:159], v[198:201], v[52:55]
	v_mfma_f32_16x16x32_bf16 v[44:47], v[164:167], v[198:201], v[44:47]
	v_mfma_f32_16x16x32_bf16 v[36:39], v[156:159], v[206:209], v[36:39]
	v_mfma_f32_16x16x32_bf16 v[28:31], v[164:167], v[206:209], v[28:31]
	v_mfma_f32_16x16x32_bf16 v[20:23], v[156:159], v[214:217], v[20:23]
	v_mfma_f32_16x16x32_bf16 v[12:15], v[164:167], v[214:217], v[12:15]
	s_setprio 0
	s_setprio 1
	v_mfma_f32_16x16x32_bf16 v[48:51], v[168:171], v[186:189], v[48:51]
	v_mfma_f32_16x16x32_bf16 v[40:43], v[176:179], v[186:189], v[40:43]
	v_mfma_f32_16x16x32_bf16 v[32:35], v[168:171], v[194:197], v[32:35]
	v_mfma_f32_16x16x32_bf16 v[24:27], v[176:179], v[194:197], v[24:27]
	v_mfma_f32_16x16x32_bf16 v[16:19], v[168:171], v[202:205], v[16:19]
	v_mfma_f32_16x16x32_bf16 v[8:11], v[176:179], v[202:205], v[8:11]
	v_mfma_f32_16x16x32_bf16 v[4:7], v[168:171], v[210:213], v[4:7]
	v_mfma_f32_16x16x32_bf16 v[0:3], v[176:179], v[210:213], v[0:3]
	v_mfma_f32_16x16x32_bf16 v[48:51], v[172:175], v[190:193], v[48:51]
	v_mfma_f32_16x16x32_bf16 v[40:43], v[180:183], v[190:193], v[40:43]
	v_mfma_f32_16x16x32_bf16 v[32:35], v[172:175], v[198:201], v[32:35]
	v_mfma_f32_16x16x32_bf16 v[24:27], v[180:183], v[198:201], v[24:27]
	v_mfma_f32_16x16x32_bf16 v[16:19], v[172:175], v[206:209], v[16:19]
	v_mfma_f32_16x16x32_bf16 v[8:11], v[180:183], v[206:209], v[8:11]
	v_mfma_f32_16x16x32_bf16 v[4:7], v[172:175], v[214:217], v[4:7]
	v_mfma_f32_16x16x32_bf16 v[0:3], v[180:183], v[214:217], v[0:3]
	s_setprio 0
	s_barrier
	s_add_i32 s59, 0, 0x18000
	s_add_i32 s60, 0, 0x1c000
	v_add_u32_e32 v164, s59, v147
	v_add_u32_e32 v180, s60, v147
	ds_read_b128 v[152:155], v164
	ds_read_b128 v[156:159], v164 offset:1024
	ds_read_b128 v[160:163], v164 offset:2048
	ds_read_b128 v[164:167], v164 offset:3072
	ds_read_b128 v[168:171], v180
	ds_read_b128 v[172:175], v180 offset:1024
	ds_read_b128 v[176:179], v180 offset:2048
	ds_read_b128 v[180:183], v180 offset:3072
	s_add_u32 s22, s28, 0xb0000
	s_addc_u32 s23, s29, 0
	s_mov_b32 m0, s39
	v_lshl_add_u64 v[224:225], s[22:23], 0, v[128:129]
	ds_read_b128 v[186:189], v151 offset:32768
	ds_read_b128 v[190:193], v151 offset:33792
	ds_read_b128 v[194:197], v151 offset:34816
	ds_read_b128 v[198:201], v151 offset:35840
	ds_read_b128 v[202:205], v151 offset:36864
	ds_read_b128 v[206:209], v151 offset:37888
	ds_read_b128 v[210:213], v151 offset:38912
	ds_read_b128 v[214:217], v151 offset:39936
	global_load_lds_dwordx4 v[224:225], off
	v_lshl_add_u64 v[224:225], s[22:23], 0, v[132:133]
	s_mov_b32 m0, s40
	s_nop 0
	global_load_lds_dwordx4 v[224:225], off
	s_waitcnt vmcnt(8)
	s_waitcnt lgkmcnt(0)
	s_barrier
	s_setprio 1
	s_waitcnt lgkmcnt(0)
	v_mfma_f32_16x16x32_bf16 v[124:127], v[152:155], v[186:189], v[124:127]
	v_mfma_f32_16x16x32_bf16 v[120:123], v[160:163], v[186:189], v[120:123]
	v_mfma_f32_16x16x32_bf16 v[116:119], v[152:155], v[194:197], v[116:119]
	v_mfma_f32_16x16x32_bf16 v[108:111], v[160:163], v[194:197], v[108:111]
	v_mfma_f32_16x16x32_bf16 v[100:103], v[152:155], v[202:205], v[100:103]
	v_mfma_f32_16x16x32_bf16 v[92:95], v[160:163], v[202:205], v[92:95]
	v_mfma_f32_16x16x32_bf16 v[84:87], v[152:155], v[210:213], v[84:87]
	v_mfma_f32_16x16x32_bf16 v[76:79], v[160:163], v[210:213], v[76:79]
	v_mfma_f32_16x16x32_bf16 v[124:127], v[156:159], v[190:193], v[124:127]
	v_mfma_f32_16x16x32_bf16 v[120:123], v[164:167], v[190:193], v[120:123]
	v_mfma_f32_16x16x32_bf16 v[116:119], v[156:159], v[198:201], v[116:119]
	v_mfma_f32_16x16x32_bf16 v[108:111], v[164:167], v[198:201], v[108:111]
	v_mfma_f32_16x16x32_bf16 v[100:103], v[156:159], v[206:209], v[100:103]
	v_mfma_f32_16x16x32_bf16 v[92:95], v[164:167], v[206:209], v[92:95]
	v_mfma_f32_16x16x32_bf16 v[84:87], v[156:159], v[214:217], v[84:87]
	v_mfma_f32_16x16x32_bf16 v[76:79], v[164:167], v[214:217], v[76:79]
	s_setprio 0
	s_setprio 1
	v_mfma_f32_16x16x32_bf16 v[112:115], v[168:171], v[186:189], v[112:115]
	v_mfma_f32_16x16x32_bf16 v[104:107], v[176:179], v[186:189], v[104:107]
	v_mfma_f32_16x16x32_bf16 v[96:99], v[168:171], v[194:197], v[96:99]
	v_mfma_f32_16x16x32_bf16 v[88:91], v[176:179], v[194:197], v[88:91]
	v_mfma_f32_16x16x32_bf16 v[80:83], v[168:171], v[202:205], v[80:83]
	v_mfma_f32_16x16x32_bf16 v[72:75], v[176:179], v[202:205], v[72:75]
	v_mfma_f32_16x16x32_bf16 v[68:71], v[168:171], v[210:213], v[68:71]
	v_mfma_f32_16x16x32_bf16 v[64:67], v[176:179], v[210:213], v[64:67]
	v_mfma_f32_16x16x32_bf16 v[112:115], v[172:175], v[190:193], v[112:115]
	v_mfma_f32_16x16x32_bf16 v[104:107], v[180:183], v[190:193], v[104:107]
	v_mfma_f32_16x16x32_bf16 v[96:99], v[172:175], v[198:201], v[96:99]
	v_mfma_f32_16x16x32_bf16 v[88:91], v[180:183], v[198:201], v[88:91]
	v_mfma_f32_16x16x32_bf16 v[80:83], v[172:175], v[206:209], v[80:83]
	v_mfma_f32_16x16x32_bf16 v[72:75], v[180:183], v[206:209], v[72:75]
	v_mfma_f32_16x16x32_bf16 v[68:71], v[172:175], v[214:217], v[68:71]
	v_mfma_f32_16x16x32_bf16 v[64:67], v[180:183], v[214:217], v[64:67]
	s_setprio 0
	s_barrier
; #define PG8_STAGE(bufoff, gbase, voff) do { _Pragma("unroll") for (int _i = 0; _i < 2; ++_i) \
;         __builtin_amdgcn_global_load_lds((const unsigned*)((const char*)(gbase) + (voff)[_i]), (PG8_LAS unsigned*)(lds + (bufoff) + ldsw + _i * 8192), 16, 0, 0); } while (0)
; #define PG8_LDA(dst, b, h) do { _Pragma("unroll") for (int m = 0; m < 4; ++m) _Pragma("unroll") for (int k = 0; k < 2; ++k) dst[m][k] = *(const PG8_LAS bf16x8*)(lds + PG8_SA(b, h) + aoff + m * 2048 + k * 1024); } while (0)
; #define PG8_MMA(ai, bj, At, Bt) do { __builtin_amdgcn_s_setprio(1); _Pragma("unroll") for (int m = 0; m < 4; ++m) _Pragma("unroll") for (int n = 0; n < 2; ++n) _Pragma("unroll") for (int k = 0; k < 2; ++k) \
;         acc[ai][bj][m][n] = __builtin_amdgcn_mfma_f32_16x16x32_bf16(Bt[n][k], At[m][k], acc[ai][bj][m][n], 0, 0, 0); __builtin_amdgcn_s_setprio(0); } while (0)
; #define PG8_WAIT_V(n) asm volatile("s_waitcnt vmcnt(" #n ")" ::: "memory")
; #define PG8_WAIT_L(n) asm volatile("s_waitcnt lgkmcnt(" #n ")" ::: "memory")
; #define PG8_BAR __builtin_amdgcn_s_barrier()
; #define PG8_SCHED __builtin_amdgcn_sched_barrier(0)
; template <class Epi, class Sched, bool ALIGN_EPI = false, bool SP2 = false>
; __device__ __forceinline__ void gemm_phase(PG8_LAS unsigned char* lds, const Gemm g, const Sched& S, const Epi& E) {
;     ...
;         for (int t = 0; t < nt; t += 2) {
;             const bool last = (t == nt - 2);
;             const char* a1 = cA + (size_t)(t + 1) * kstep;
;             const char* a2 = last ? nA : cA + (size_t)(t + 2) * kstep; const char* b2 = last ? nB : cB + (size_t)(t + 2) * kstep;
;             const char* a3 = a2 + kstep; const char* b3 = b2 + kstep;
;     ...
;             PG8_LDA(At, 1, 1); PG8_STAGE(PG8_SB(1, 0), b3, voffB); PG8_STAGE(PG8_SB(1, 1), b3 + hstep, voffB); PG8_STAGE(PG8_SA(1, 0), a3, voffA);
;             PG8_WAIT_V(8); PG8_WAIT_L(0); PG8_BAR; PG8_MMA(1, 0, At, B0); PG8_MMA(1, 1, At, B1); PG8_BAR; PG8_SCHED;
	s_add_i32 s22, s59, s36
	v_lshl_add_u64 v[144:145], v[144:145], 0, s[8:9]
	s_mov_b32 m0, s22
	ds_read_b128 v[186:189], v151 offset:49152
	ds_read_b128 v[190:193], v151 offset:50176
	ds_read_b128 v[194:197], v151 offset:51200
	ds_read_b128 v[198:201], v151 offset:52224
	ds_read_b128 v[202:205], v151 offset:53248
	ds_read_b128 v[206:209], v151 offset:54272
	ds_read_b128 v[210:213], v151 offset:55296
	ds_read_b128 v[214:217], v151 offset:56320
	global_load_lds_dwordx4 v[144:145], off
	s_add_i32 m0, s22, 0x2000
	s_add_u32 s22, s26, 0xb0080
	v_lshl_add_u64 v[144:145], v[218:219], 0, s[8:9]
	s_addc_u32 s23, s27, 0
	s_add_i32 s26, s60, s36
	global_load_lds_dwordx4 v[144:145], off
	v_lshl_add_u64 v[144:145], s[22:23], 0, v[130:131]
	s_mov_b32 m0, s26
	s_nop 0
	global_load_lds_dwordx4 v[144:145], off
	v_lshl_add_u64 v[144:145], s[22:23], 0, v[134:135]
	s_add_i32 m0, s26, 0x2000
	s_nop 0
	global_load_lds_dwordx4 v[144:145], off
	v_lshl_add_u64 v[144:145], v[220:221], 0, s[8:9]
	s_mov_b32 m0, s42
	s_nop 0
	global_load_lds_dwordx4 v[144:145], off
	v_lshl_add_u64 v[144:145], v[222:223], 0, s[8:9]
	s_mov_b32 m0, s43
	s_nop 0
	global_load_lds_dwordx4 v[144:145], off
	s_waitcnt vmcnt(8)
	s_waitcnt lgkmcnt(0)
	s_barrier
	s_setprio 1
	s_waitcnt lgkmcnt(0)
	v_mfma_f32_16x16x32_bf16 v[60:63], v[152:155], v[186:189], v[60:63]
	v_mfma_f32_16x16x32_bf16 v[56:59], v[160:163], v[186:189], v[56:59]
	v_mfma_f32_16x16x32_bf16 v[52:55], v[152:155], v[194:197], v[52:55]
	v_mfma_f32_16x16x32_bf16 v[44:47], v[160:163], v[194:197], v[44:47]
	v_mfma_f32_16x16x32_bf16 v[36:39], v[152:155], v[202:205], v[36:39]
	v_mfma_f32_16x16x32_bf16 v[28:31], v[160:163], v[202:205], v[28:31]
	v_mfma_f32_16x16x32_bf16 v[20:23], v[152:155], v[210:213], v[20:23]
	v_mfma_f32_16x16x32_bf16 v[12:15], v[160:163], v[210:213], v[12:15]
	v_mfma_f32_16x16x32_bf16 v[60:63], v[156:159], v[190:193], v[60:63]
	v_mfma_f32_16x16x32_bf16 v[56:59], v[164:167], v[190:193], v[56:59]
	v_mfma_f32_16x16x32_bf16 v[52:55], v[156:159], v[198:201], v[52:55]
	v_mfma_f32_16x16x32_bf16 v[44:47], v[164:167], v[198:201], v[44:47]
	v_mfma_f32_16x16x32_bf16 v[36:39], v[156:159], v[206:209], v[36:39]
	v_mfma_f32_16x16x32_bf16 v[28:31], v[164:167], v[206:209], v[28:31]
	v_mfma_f32_16x16x32_bf16 v[20:23], v[156:159], v[214:217], v[20:23]
	v_mfma_f32_16x16x32_bf16 v[12:15], v[164:167], v[214:217], v[12:15]
	s_setprio 0
	s_setprio 1
	v_mfma_f32_16x16x32_bf16 v[48:51], v[168:171], v[186:189], v[48:51]
	v_mfma_f32_16x16x32_bf16 v[40:43], v[176:179], v[186:189], v[40:43]
	v_mfma_f32_16x16x32_bf16 v[32:35], v[168:171], v[194:197], v[32:35]
	v_mfma_f32_16x16x32_bf16 v[24:27], v[176:179], v[194:197], v[24:27]
	v_mfma_f32_16x16x32_bf16 v[16:19], v[168:171], v[202:205], v[16:19]
	v_mfma_f32_16x16x32_bf16 v[8:11], v[176:179], v[202:205], v[8:11]
	v_mfma_f32_16x16x32_bf16 v[4:7], v[168:171], v[210:213], v[4:7]
	v_mfma_f32_16x16x32_bf16 v[0:3], v[176:179], v[210:213], v[0:3]
	v_mfma_f32_16x16x32_bf16 v[48:51], v[172:175], v[190:193], v[48:51]
	v_mfma_f32_16x16x32_bf16 v[40:43], v[180:183], v[190:193], v[40:43]
	v_mfma_f32_16x16x32_bf16 v[32:35], v[172:175], v[198:201], v[32:35]
	v_mfma_f32_16x16x32_bf16 v[24:27], v[180:183], v[198:201], v[24:27]
	v_mfma_f32_16x16x32_bf16 v[16:19], v[172:175], v[206:209], v[16:19]
	v_mfma_f32_16x16x32_bf16 v[8:11], v[180:183], v[206:209], v[8:11]
	v_mfma_f32_16x16x32_bf16 v[4:7], v[172:175], v[214:217], v[4:7]
	v_mfma_f32_16x16x32_bf16 v[0:3], v[180:183], v[214:217], v[0:3]
	s_setprio 0
	s_add_i32 s58, s58, 2
	s_add_u32 s56, s56, 0x100
	s_addc_u32 s57, s57, 0
	s_cmp_gt_u32 s58, 41
	s_mov_b64 s[22:23], s[24:25]
	s_barrier
	s_cbranch_scc0 .LBB0_196
	s_and_b64 vcc, exec, s[10:11]
	s_cbranch_vccz .LBB0_199
	s_barrier

; #define PG8_STAGE(bufoff, gbase, voff) do { _Pragma("unroll") for (int _i = 0; _i < 2; ++_i) \
;         __builtin_amdgcn_global_load_lds((const unsigned*)((const char*)(gbase) + (voff)[_i]), (PG8_LAS unsigned*)(lds + (bufoff) + ldsw + _i * 8192), 16, 0, 0); } while (0)
; #define PG8_LDA(dst, b, h) do { _Pragma("unroll") for (int m = 0; m < 4; ++m) _Pragma("unroll") for (int k = 0; k < 2; ++k) dst[m][k] = *(const PG8_LAS bf16x8*)(lds + PG8_SA(b, h) + aoff + m * 2048 + k * 1024); } while (0)
; #define PG8_LDB(dst, b, h) do { _Pragma("unroll") for (int n = 0; n < 2; ++n) _Pragma("unroll") for (int k = 0; k < 2; ++k) dst[n][k] = *(const PG8_LAS bf16x8*)(lds + PG8_SB(b, h) + boff + n * 2048 + k * 1024); } while (0)
; #define PG8_MMA(ai, bj, At, Bt) do { __builtin_amdgcn_s_setprio(1); _Pragma("unroll") for (int m = 0; m < 4; ++m) _Pragma("unroll") for (int n = 0; n < 2; ++n) _Pragma("unroll") for (int k = 0; k < 2; ++k) \
;         acc[ai][bj][m][n] = __builtin_amdgcn_mfma_f32_16x16x32_bf16(Bt[n][k], At[m][k], acc[ai][bj][m][n], 0, 0, 0); __builtin_amdgcn_s_setprio(0); } while (0)
; #define PG8_WAIT_V(n) asm volatile("s_waitcnt vmcnt(" #n ")" ::: "memory")
; #define PG8_BAR __builtin_amdgcn_s_barrier()
; template <class Epi, class Sched, bool ALIGN_EPI = false, bool SP2 = false>
; __device__ __forceinline__ void gemm_phase(PG8_LAS unsigned char* lds, const Gemm g, const Sched& S, const Epi& E) {
;     ...
;         for (int t = 0; t < nt; t += 2) {
;             const bool last = (t == nt - 2);
;             const char* a1 = cA + (size_t)(t + 1) * kstep;
;             const char* a2 = last ? nA : cA + (size_t)(t + 2) * kstep; const char* b2 = last ? nB : cB + (size_t)(t + 2) * kstep;
;             const char* a3 = a2 + kstep; const char* b3 = b2 + kstep;
;             if (last && has_next) S.a_ready(nxt);
;             if constexpr (SP2) {
;             PG8_LDB(B0, 0, 0); PG8_LDB(B1, 0, 1); PG8_SCHED; PG8_LDA(At, 0, 0); PG8_STAGE(PG8_SA(1, 1), a1 + hstep, voffA);
;             PG8_WAIT_V(8); PG8_WAIT_L(0); PG8_BAR; PG8_MMA(0, 0, At, B0); PG8_MMA(0, 1, At, B1); PG8_BAR; PG8_SCHED;
;             PG8_LDA(At, 0, 1); PG8_STAGE(PG8_SB(0, 0), b2, voffB); PG8_STAGE(PG8_SB(0, 1), b2 + hstep, voffB); PG8_STAGE(PG8_SA(0, 0), a2, voffA);
;             PG8_WAIT_V(8); PG8_WAIT_L(0); PG8_BAR; PG8_MMA(1, 0, At, B0); PG8_MMA(1, 1, At, B1); PG8_BAR; PG8_SCHED;
.LBB0_269:
	ds_read_b128 v[148:151], v145
	ds_read_b128 v[152:155], v145 offset:1024
	ds_read_b128 v[156:159], v145 offset:2048
	ds_read_b128 v[160:163], v145 offset:3072
	ds_read_b128 v[164:167], v146
	ds_read_b128 v[168:171], v146 offset:1024
	ds_read_b128 v[172:175], v146 offset:2048
	ds_read_b128 v[176:179], v146 offset:3072
	s_add_u32 s26, s24, 0x100
	s_addc_u32 s27, s25, 0
	s_cmp_eq_u32 s57, 40
	s_cselect_b32 s31, s21, s27
	s_cselect_b32 s30, s20, s26
	s_cselect_b32 s29, s23, s56
	s_cselect_b32 s28, s22, s55
	v_lshl_add_u64 v[140:141], s[24:25], 0, v[138:139]
	s_add_i32 m0, s36, 0xc000
	ds_read_b128 v[180:183], v147
	ds_read_b128 v[186:189], v147 offset:1024
	ds_read_b128 v[190:193], v147 offset:2048
	ds_read_b128 v[194:197], v147 offset:3072
	ds_read_b128 v[198:201], v147 offset:4096
	ds_read_b128 v[202:205], v147 offset:5120
	ds_read_b128 v[206:209], v147 offset:6144
	ds_read_b128 v[210:213], v147 offset:7168
	global_load_lds_dwordx4 v[140:141], off
	v_lshl_add_u64 v[140:141], s[24:25], 0, v[136:137]
	s_add_i32 m0, s36, 0xe000
	s_nop 0
	global_load_lds_dwordx4 v[140:141], off
	s_waitcnt vmcnt(8)
	s_waitcnt lgkmcnt(0)
	s_barrier
	s_setprio 1
	s_waitcnt lgkmcnt(0)
	v_mfma_f32_16x16x32_bf16 v[124:127], v[148:151], v[180:183], v[124:127]
	v_mfma_f32_16x16x32_bf16 v[120:123], v[156:159], v[180:183], v[120:123]
	v_mfma_f32_16x16x32_bf16 v[116:119], v[148:151], v[190:193], v[116:119]
	v_mfma_f32_16x16x32_bf16 v[108:111], v[156:159], v[190:193], v[108:111]
	v_mfma_f32_16x16x32_bf16 v[100:103], v[148:151], v[198:201], v[100:103]
	v_mfma_f32_16x16x32_bf16 v[92:95], v[156:159], v[198:201], v[92:95]
	v_mfma_f32_16x16x32_bf16 v[84:87], v[148:151], v[206:209], v[84:87]
	v_mfma_f32_16x16x32_bf16 v[76:79], v[156:159], v[206:209], v[76:79]
	v_mfma_f32_16x16x32_bf16 v[124:127], v[152:155], v[186:189], v[124:127]
	v_mfma_f32_16x16x32_bf16 v[120:123], v[160:163], v[186:189], v[120:123]
	v_mfma_f32_16x16x32_bf16 v[116:119], v[152:155], v[194:197], v[116:119]
	v_mfma_f32_16x16x32_bf16 v[108:111], v[160:163], v[194:197], v[108:111]
	v_mfma_f32_16x16x32_bf16 v[100:103], v[152:155], v[202:205], v[100:103]
	v_mfma_f32_16x16x32_bf16 v[92:95], v[160:163], v[202:205], v[92:95]
	v_mfma_f32_16x16x32_bf16 v[84:87], v[152:155], v[210:213], v[84:87]
	v_mfma_f32_16x16x32_bf16 v[76:79], v[160:163], v[210:213], v[76:79]
	s_setprio 0
	s_setprio 1
	v_mfma_f32_16x16x32_bf16 v[112:115], v[164:167], v[180:183], v[112:115]
	v_mfma_f32_16x16x32_bf16 v[104:107], v[172:175], v[180:183], v[104:107]
	v_mfma_f32_16x16x32_bf16 v[96:99], v[164:167], v[190:193], v[96:99]
	v_mfma_f32_16x16x32_bf16 v[88:91], v[172:175], v[190:193], v[88:91]
	v_mfma_f32_16x16x32_bf16 v[80:83], v[164:167], v[198:201], v[80:83]
	v_mfma_f32_16x16x32_bf16 v[72:75], v[172:175], v[198:201], v[72:75]
	v_mfma_f32_16x16x32_bf16 v[68:71], v[164:167], v[206:209], v[68:71]
	v_mfma_f32_16x16x32_bf16 v[64:67], v[172:175], v[206:209], v[64:67]
	v_mfma_f32_16x16x32_bf16 v[112:115], v[168:171], v[186:189], v[112:115]
	v_mfma_f32_16x16x32_bf16 v[104:107], v[176:179], v[186:189], v[104:107]
	v_mfma_f32_16x16x32_bf16 v[96:99], v[168:171], v[194:197], v[96:99]
	v_mfma_f32_16x16x32_bf16 v[88:91], v[176:179], v[194:197], v[88:91]
	v_mfma_f32_16x16x32_bf16 v[80:83], v[168:171], v[202:205], v[80:83]
	v_mfma_f32_16x16x32_bf16 v[72:75], v[176:179], v[202:205], v[72:75]
	v_mfma_f32_16x16x32_bf16 v[68:71], v[168:171], v[210:213], v[68:71]
	v_mfma_f32_16x16x32_bf16 v[64:67], v[176:179], v[210:213], v[64:67]
	s_setprio 0
	s_barrier
	s_add_i32 s24, s44, s35
	v_lshl_add_u64 v[140:141], s[28:29], 0, v[130:131]
	s_mov_b32 m0, s24
	ds_read_b128 v[180:183], v147 offset:16384
	ds_read_b128 v[186:189], v147 offset:17408
	ds_read_b128 v[190:193], v147 offset:18432
	ds_read_b128 v[194:197], v147 offset:19456
	ds_read_b128 v[198:201], v147 offset:20480
	ds_read_b128 v[202:205], v147 offset:21504
	ds_read_b128 v[206:209], v147 offset:22528
	ds_read_b128 v[210:213], v147 offset:23552
	global_load_lds_dwordx4 v[140:141], off
	s_add_i32 m0, s24, 0x2000
	s_add_u32 s24, s28, 0xb0000
	v_lshl_add_u64 v[214:215], s[28:29], 0, v[134:135]
	s_addc_u32 s25, s29, 0
	s_add_i32 s58, s45, s35
	global_load_lds_dwordx4 v[214:215], off
	v_lshl_add_u64 v[216:217], s[24:25], 0, v[130:131]
	s_mov_b32 m0, s58
	v_lshl_add_u64 v[218:219], s[30:31], 0, v[132:133]
	global_load_lds_dwordx4 v[216:217], off
	v_lshl_add_u64 v[216:217], s[24:25], 0, v[134:135]
	s_add_i32 m0, s58, 0x2000
	s_nop 0
	global_load_lds_dwordx4 v[216:217], off
	v_lshl_add_u64 v[216:217], s[30:31], 0, v[128:129]
	s_mov_b32 m0, s36
	s_nop 0
	global_load_lds_dwordx4 v[216:217], off
	s_mov_b32 m0, s37
	s_nop 0
	global_load_lds_dwordx4 v[218:219], off
	s_waitcnt vmcnt(8)
	s_waitcnt lgkmcnt(0)
	s_barrier
; #define PG8_STAGE(bufoff, gbase, voff) do { _Pragma("unroll") for (int _i = 0; _i < 2; ++_i) \
;         __builtin_amdgcn_global_load_lds((const unsigned*)((const char*)(gbase) + (voff)[_i]), (PG8_LAS unsigned*)(lds + (bufoff) + ldsw + _i * 8192), 16, 0, 0); } while (0)
; #define PG8_LDA(dst, b, h) do { _Pragma("unroll") for (int m = 0; m < 4; ++m) _Pragma("unroll") for (int k = 0; k < 2; ++k) dst[m][k] = *(const PG8_LAS bf16x8*)(lds + PG8_SA(b, h) + aoff + m * 2048 + k * 1024); } while (0)
; #define PG8_LDB(dst, b, h) do { _Pragma("unroll") for (int n = 0; n < 2; ++n) _Pragma("unroll") for (int k = 0; k < 2; ++k) dst[n][k] = *(const PG8_LAS bf16x8*)(lds + PG8_SB(b, h) + boff + n * 2048 + k * 1024); } while (0)
; #define PG8_MMA(ai, bj, At, Bt) do { __builtin_amdgcn_s_setprio(1); _Pragma("unroll") for (int m = 0; m < 4; ++m) _Pragma("unroll") for (int n = 0; n < 2; ++n) _Pragma("unroll") for (int k = 0; k < 2; ++k) \
;         acc[ai][bj][m][n] = __builtin_amdgcn_mfma_f32_16x16x32_bf16(Bt[n][k], At[m][k], acc[ai][bj][m][n], 0, 0, 0); __builtin_amdgcn_s_setprio(0); } while (0)
; #define PG8_WAIT_V(n) asm volatile("s_waitcnt vmcnt(" #n ")" ::: "memory")
; #define PG8_WAIT_L(n) asm volatile("s_waitcnt lgkmcnt(" #n ")" ::: "memory")
; #define PG8_BAR __builtin_amdgcn_s_barrier()
; #define PG8_SCHED __builtin_amdgcn_sched_barrier(0)
; template <class Epi, class Sched, bool ALIGN_EPI = false, bool SP2 = false>
; __device__ __forceinline__ void gemm_phase(PG8_LAS unsigned char* lds, const Gemm g, const Sched& S, const Epi& E) {
;     ...
;             PG8_WAIT_V(8); PG8_WAIT_L(0); PG8_BAR; PG8_MMA(1, 0, At, B0); PG8_MMA(1, 1, At, B1); PG8_BAR; PG8_SCHED;
;             PG8_LDB(B0, 1, 0); PG8_LDB(B1, 1, 1); PG8_SCHED; PG8_LDA(At, 1, 0); PG8_STAGE(PG8_SA(0, 1), a2 + hstep, voffA);
;             PG8_WAIT_V(8); PG8_WAIT_L(0); PG8_BAR; PG8_MMA(0, 0, At, B0); PG8_MMA(0, 1, At, B1); PG8_BAR; PG8_SCHED;
	s_setprio 1
	s_waitcnt lgkmcnt(0)
	v_mfma_f32_16x16x32_bf16 v[60:63], v[148:151], v[180:183], v[60:63]
	v_mfma_f32_16x16x32_bf16 v[56:59], v[156:159], v[180:183], v[56:59]
	v_mfma_f32_16x16x32_bf16 v[52:55], v[148:151], v[190:193], v[52:55]
	v_mfma_f32_16x16x32_bf16 v[44:47], v[156:159], v[190:193], v[44:47]
	v_mfma_f32_16x16x32_bf16 v[36:39], v[148:151], v[198:201], v[36:39]
	v_mfma_f32_16x16x32_bf16 v[28:31], v[156:159], v[198:201], v[28:31]
	v_mfma_f32_16x16x32_bf16 v[20:23], v[148:151], v[206:209], v[20:23]
	v_mfma_f32_16x16x32_bf16 v[12:15], v[156:159], v[206:209], v[12:15]
	v_mfma_f32_16x16x32_bf16 v[60:63], v[152:155], v[186:189], v[60:63]
	v_mfma_f32_16x16x32_bf16 v[56:59], v[160:163], v[186:189], v[56:59]
	v_mfma_f32_16x16x32_bf16 v[52:55], v[152:155], v[194:197], v[52:55]
	v_mfma_f32_16x16x32_bf16 v[44:47], v[160:163], v[194:197], v[44:47]
	v_mfma_f32_16x16x32_bf16 v[36:39], v[152:155], v[202:205], v[36:39]
	v_mfma_f32_16x16x32_bf16 v[28:31], v[160:163], v[202:205], v[28:31]
	v_mfma_f32_16x16x32_bf16 v[20:23], v[152:155], v[210:213], v[20:23]
	v_mfma_f32_16x16x32_bf16 v[12:15], v[160:163], v[210:213], v[12:15]
	s_setprio 0
	s_setprio 1
	v_mfma_f32_16x16x32_bf16 v[48:51], v[164:167], v[180:183], v[48:51]
	v_mfma_f32_16x16x32_bf16 v[40:43], v[172:175], v[180:183], v[40:43]
	v_mfma_f32_16x16x32_bf16 v[32:35], v[164:167], v[190:193], v[32:35]
	v_mfma_f32_16x16x32_bf16 v[24:27], v[172:175], v[190:193], v[24:27]
	v_mfma_f32_16x16x32_bf16 v[16:19], v[164:167], v[198:201], v[16:19]
	v_mfma_f32_16x16x32_bf16 v[8:11], v[172:175], v[198:201], v[8:11]
	v_mfma_f32_16x16x32_bf16 v[4:7], v[164:167], v[206:209], v[4:7]
	v_mfma_f32_16x16x32_bf16 v[0:3], v[172:175], v[206:209], v[0:3]
	v_mfma_f32_16x16x32_bf16 v[48:51], v[168:171], v[186:189], v[48:51]
	v_mfma_f32_16x16x32_bf16 v[40:43], v[176:179], v[186:189], v[40:43]
	v_mfma_f32_16x16x32_bf16 v[32:35], v[168:171], v[194:197], v[32:35]
	v_mfma_f32_16x16x32_bf16 v[24:27], v[176:179], v[194:197], v[24:27]
	v_mfma_f32_16x16x32_bf16 v[16:19], v[168:171], v[202:205], v[16:19]
	v_mfma_f32_16x16x32_bf16 v[8:11], v[176:179], v[202:205], v[8:11]
	v_mfma_f32_16x16x32_bf16 v[4:7], v[168:171], v[210:213], v[4:7]
	v_mfma_f32_16x16x32_bf16 v[0:3], v[176:179], v[210:213], v[0:3]
	s_setprio 0
	s_barrier
	s_add_i32 s58, 0, 0x18000
	s_add_i32 s59, 0, 0x1c000
	v_add_u32_e32 v160, s58, v143
	v_add_u32_e32 v176, s59, v143
	ds_read_b128 v[148:151], v160
	ds_read_b128 v[152:155], v160 offset:1024
	ds_read_b128 v[156:159], v160 offset:2048
	ds_read_b128 v[160:163], v160 offset:3072
	ds_read_b128 v[164:167], v176
	ds_read_b128 v[168:171], v176 offset:1024
	ds_read_b128 v[172:175], v176 offset:2048
	ds_read_b128 v[176:179], v176 offset:3072
	s_add_u32 s24, s30, 0xb0000
	s_addc_u32 s25, s31, 0
	s_mov_b32 m0, s38
	v_lshl_add_u64 v[220:221], s[24:25], 0, v[128:129]
	ds_read_b128 v[180:183], v147 offset:32768
	ds_read_b128 v[186:189], v147 offset:33792
	ds_read_b128 v[190:193], v147 offset:34816
	ds_read_b128 v[194:197], v147 offset:35840
	ds_read_b128 v[198:201], v147 offset:36864
	ds_read_b128 v[202:205], v147 offset:37888
	ds_read_b128 v[206:209], v147 offset:38912
	ds_read_b128 v[210:213], v147 offset:39936
	global_load_lds_dwordx4 v[220:221], off
	v_lshl_add_u64 v[220:221], s[24:25], 0, v[132:133]
	s_mov_b32 m0, s39
	s_nop 0
	global_load_lds_dwordx4 v[220:221], off
	s_waitcnt vmcnt(8)
	s_waitcnt lgkmcnt(0)
	s_barrier
	s_setprio 1
	s_waitcnt lgkmcnt(0)
	v_mfma_f32_16x16x32_bf16 v[124:127], v[148:151], v[180:183], v[124:127]
	v_mfma_f32_16x16x32_bf16 v[120:123], v[156:159], v[180:183], v[120:123]
	v_mfma_f32_16x16x32_bf16 v[116:119], v[148:151], v[190:193], v[116:119]
	v_mfma_f32_16x16x32_bf16 v[108:111], v[156:159], v[190:193], v[108:111]
	v_mfma_f32_16x16x32_bf16 v[100:103], v[148:151], v[198:201], v[100:103]
	v_mfma_f32_16x16x32_bf16 v[92:95], v[156:159], v[198:201], v[92:95]
	v_mfma_f32_16x16x32_bf16 v[84:87], v[148:151], v[206:209], v[84:87]
	v_mfma_f32_16x16x32_bf16 v[76:79], v[156:159], v[206:209], v[76:79]
	v_mfma_f32_16x16x32_bf16 v[124:127], v[152:155], v[186:189], v[124:127]
	v_mfma_f32_16x16x32_bf16 v[120:123], v[160:163], v[186:189], v[120:123]
	v_mfma_f32_16x16x32_bf16 v[116:119], v[152:155], v[194:197], v[116:119]
	v_mfma_f32_16x16x32_bf16 v[108:111], v[160:163], v[194:197], v[108:111]
	v_mfma_f32_16x16x32_bf16 v[100:103], v[152:155], v[202:205], v[100:103]
	v_mfma_f32_16x16x32_bf16 v[92:95], v[160:163], v[202:205], v[92:95]
	v_mfma_f32_16x16x32_bf16 v[84:87], v[152:155], v[210:213], v[84:87]
	v_mfma_f32_16x16x32_bf16 v[76:79], v[160:163], v[210:213], v[76:79]
	s_setprio 0
	s_setprio 1
	v_mfma_f32_16x16x32_bf16 v[112:115], v[164:167], v[180:183], v[112:115]
	v_mfma_f32_16x16x32_bf16 v[104:107], v[172:175], v[180:183], v[104:107]
	v_mfma_f32_16x16x32_bf16 v[96:99], v[164:167], v[190:193], v[96:99]
	v_mfma_f32_16x16x32_bf16 v[88:91], v[172:175], v[190:193], v[88:91]
	v_mfma_f32_16x16x32_bf16 v[80:83], v[164:167], v[198:201], v[80:83]
	v_mfma_f32_16x16x32_bf16 v[72:75], v[172:175], v[198:201], v[72:75]
	v_mfma_f32_16x16x32_bf16 v[68:71], v[164:167], v[206:209], v[68:71]
	v_mfma_f32_16x16x32_bf16 v[64:67], v[172:175], v[206:209], v[64:67]
	v_mfma_f32_16x16x32_bf16 v[112:115], v[168:171], v[186:189], v[112:115]
	v_mfma_f32_16x16x32_bf16 v[104:107], v[176:179], v[186:189], v[104:107]
	v_mfma_f32_16x16x32_bf16 v[96:99], v[168:171], v[194:197], v[96:99]
	v_mfma_f32_16x16x32_bf16 v[88:91], v[176:179], v[194:197], v[88:91]
	v_mfma_f32_16x16x32_bf16 v[80:83], v[168:171], v[202:205], v[80:83]
	v_mfma_f32_16x16x32_bf16 v[72:75], v[176:179], v[202:205], v[72:75]
	v_mfma_f32_16x16x32_bf16 v[68:71], v[168:171], v[210:213], v[68:71]
	v_mfma_f32_16x16x32_bf16 v[64:67], v[176:179], v[210:213], v[64:67]
	s_setprio 0
	s_barrier
; #define PG8_STAGE(bufoff, gbase, voff) do { _Pragma("unroll") for (int _i = 0; _i < 2; ++_i) \
;         __builtin_amdgcn_global_load_lds((const unsigned*)((const char*)(gbase) + (voff)[_i]), (PG8_LAS unsigned*)(lds + (bufoff) + ldsw + _i * 8192), 16, 0, 0); } while (0)
; #define PG8_LDA(dst, b, h) do { _Pragma("unroll") for (int m = 0; m < 4; ++m) _Pragma("unroll") for (int k = 0; k < 2; ++k) dst[m][k] = *(const PG8_LAS bf16x8*)(lds + PG8_SA(b, h) + aoff + m * 2048 + k * 1024); } while (0)
; #define PG8_MMA(ai, bj, At, Bt) do { __builtin_amdgcn_s_setprio(1); _Pragma("unroll") for (int m = 0; m < 4; ++m) _Pragma("unroll") for (int n = 0; n < 2; ++n) _Pragma("unroll") for (int k = 0; k < 2; ++k) \
;         acc[ai][bj][m][n] = __builtin_amdgcn_mfma_f32_16x16x32_bf16(Bt[n][k], At[m][k], acc[ai][bj][m][n], 0, 0, 0); __builtin_amdgcn_s_setprio(0); } while (0)
; #define PG8_WAIT_V(n) asm volatile("s_waitcnt vmcnt(" #n ")" ::: "memory")
; #define PG8_WAIT_L(n) asm volatile("s_waitcnt lgkmcnt(" #n ")" ::: "memory")
; #define PG8_BAR __builtin_amdgcn_s_barrier()
; #define PG8_SCHED __builtin_amdgcn_sched_barrier(0)
; template <class Epi, class Sched, bool ALIGN_EPI = false, bool SP2 = false>
; __device__ __forceinline__ void gemm_phase(PG8_LAS unsigned char* lds, const Gemm g, const Sched& S, const Epi& E) {
;     ...
;         for (int t = 0; t < nt; t += 2) {
;             const bool last = (t == nt - 2);
;             const char* a1 = cA + (size_t)(t + 1) * kstep;
;             const char* a2 = last ? nA : cA + (size_t)(t + 2) * kstep; const char* b2 = last ? nB : cB + (size_t)(t + 2) * kstep;
;             const char* a3 = a2 + kstep; const char* b3 = b2 + kstep;
;     ...
;             PG8_LDA(At, 1, 1); PG8_STAGE(PG8_SB(1, 0), b3, voffB); PG8_STAGE(PG8_SB(1, 1), b3 + hstep, voffB); PG8_STAGE(PG8_SA(1, 0), a3, voffA);
;             PG8_WAIT_V(8); PG8_WAIT_L(0); PG8_BAR; PG8_MMA(1, 0, At, B0); PG8_MMA(1, 1, At, B1); PG8_BAR; PG8_SCHED;
	s_add_i32 s24, s58, s35
	v_lshl_add_u64 v[140:141], v[140:141], 0, s[8:9]
	s_mov_b32 m0, s24
	ds_read_b128 v[180:183], v147 offset:49152
	ds_read_b128 v[186:189], v147 offset:50176
	ds_read_b128 v[190:193], v147 offset:51200
	ds_read_b128 v[194:197], v147 offset:52224
	ds_read_b128 v[198:201], v147 offset:53248
	ds_read_b128 v[202:205], v147 offset:54272
	ds_read_b128 v[206:209], v147 offset:55296
	ds_read_b128 v[210:213], v147 offset:56320
	global_load_lds_dwordx4 v[140:141], off
	s_add_i32 m0, s24, 0x2000
	s_add_u32 s24, s28, 0xb0080
	v_lshl_add_u64 v[140:141], v[214:215], 0, s[8:9]
	s_addc_u32 s25, s29, 0
	s_add_i32 s28, s59, s35
	global_load_lds_dwordx4 v[140:141], off
	v_lshl_add_u64 v[140:141], s[24:25], 0, v[130:131]
	s_mov_b32 m0, s28
	s_nop 0
	global_load_lds_dwordx4 v[140:141], off
	v_lshl_add_u64 v[140:141], s[24:25], 0, v[134:135]
	s_add_i32 m0, s28, 0x2000
	s_nop 0
	global_load_lds_dwordx4 v[140:141], off
	v_lshl_add_u64 v[140:141], v[216:217], 0, s[8:9]
	s_mov_b32 m0, s40
	s_nop 0
	global_load_lds_dwordx4 v[140:141], off
	v_lshl_add_u64 v[140:141], v[218:219], 0, s[8:9]
	s_mov_b32 m0, s41
	s_nop 0
	global_load_lds_dwordx4 v[140:141], off
	s_waitcnt vmcnt(8)
	s_waitcnt lgkmcnt(0)
	s_barrier
	s_setprio 1
	s_waitcnt lgkmcnt(0)
	v_mfma_f32_16x16x32_bf16 v[60:63], v[148:151], v[180:183], v[60:63]
	v_mfma_f32_16x16x32_bf16 v[56:59], v[156:159], v[180:183], v[56:59]
	v_mfma_f32_16x16x32_bf16 v[52:55], v[148:151], v[190:193], v[52:55]
	v_mfma_f32_16x16x32_bf16 v[44:47], v[156:159], v[190:193], v[44:47]
	v_mfma_f32_16x16x32_bf16 v[36:39], v[148:151], v[198:201], v[36:39]
	v_mfma_f32_16x16x32_bf16 v[28:31], v[156:159], v[198:201], v[28:31]
	v_mfma_f32_16x16x32_bf16 v[20:23], v[148:151], v[206:209], v[20:23]
	v_mfma_f32_16x16x32_bf16 v[12:15], v[156:159], v[206:209], v[12:15]
	v_mfma_f32_16x16x32_bf16 v[60:63], v[152:155], v[186:189], v[60:63]
	v_mfma_f32_16x16x32_bf16 v[56:59], v[160:163], v[186:189], v[56:59]
	v_mfma_f32_16x16x32_bf16 v[52:55], v[152:155], v[194:197], v[52:55]
	v_mfma_f32_16x16x32_bf16 v[44:47], v[160:163], v[194:197], v[44:47]
	v_mfma_f32_16x16x32_bf16 v[36:39], v[152:155], v[202:205], v[36:39]
	v_mfma_f32_16x16x32_bf16 v[28:31], v[160:163], v[202:205], v[28:31]
	v_mfma_f32_16x16x32_bf16 v[20:23], v[152:155], v[210:213], v[20:23]
	v_mfma_f32_16x16x32_bf16 v[12:15], v[160:163], v[210:213], v[12:15]
	s_setprio 0
	s_setprio 1
	v_mfma_f32_16x16x32_bf16 v[48:51], v[164:167], v[180:183], v[48:51]
	v_mfma_f32_16x16x32_bf16 v[40:43], v[172:175], v[180:183], v[40:43]
	v_mfma_f32_16x16x32_bf16 v[32:35], v[164:167], v[190:193], v[32:35]
	v_mfma_f32_16x16x32_bf16 v[24:27], v[172:175], v[190:193], v[24:27]
	v_mfma_f32_16x16x32_bf16 v[16:19], v[164:167], v[198:201], v[16:19]
	v_mfma_f32_16x16x32_bf16 v[8:11], v[172:175], v[198:201], v[8:11]
	v_mfma_f32_16x16x32_bf16 v[4:7], v[164:167], v[206:209], v[4:7]
	v_mfma_f32_16x16x32_bf16 v[0:3], v[172:175], v[206:209], v[0:3]
	v_mfma_f32_16x16x32_bf16 v[48:51], v[168:171], v[186:189], v[48:51]
	v_mfma_f32_16x16x32_bf16 v[40:43], v[176:179], v[186:189], v[40:43]
	v_mfma_f32_16x16x32_bf16 v[32:35], v[168:171], v[194:197], v[32:35]
	v_mfma_f32_16x16x32_bf16 v[24:27], v[176:179], v[194:197], v[24:27]
	v_mfma_f32_16x16x32_bf16 v[16:19], v[168:171], v[202:205], v[16:19]
	v_mfma_f32_16x16x32_bf16 v[8:11], v[176:179], v[202:205], v[8:11]
	v_mfma_f32_16x16x32_bf16 v[4:7], v[168:171], v[210:213], v[4:7]
	v_mfma_f32_16x16x32_bf16 v[0:3], v[176:179], v[210:213], v[0:3]
	s_setprio 0
	s_add_i32 s57, s57, 2
	s_add_u32 s55, s55, 0x100
	s_addc_u32 s56, s56, 0
	s_cmp_gt_u32 s57, 41
	s_mov_b64 s[24:25], s[26:27]
	s_barrier
	s_cbranch_scc0 .LBB0_269
	s_and_b64 vcc, exec, s[10:11]
	s_cbranch_vccz .LBB0_272
	s_barrier

; #define PG8_STAGE(bufoff, gbase, voff) do { _Pragma("unroll") for (int _i = 0; _i < 2; ++_i) \
;         __builtin_amdgcn_global_load_lds((const unsigned*)((const char*)(gbase) + (voff)[_i]), (PG8_LAS unsigned*)(lds + (bufoff) + ldsw + _i * 8192), 16, 0, 0); } while (0)
; #define PG8_LDA(dst, b, h) do { _Pragma("unroll") for (int m = 0; m < 4; ++m) _Pragma("unroll") for (int k = 0; k < 2; ++k) dst[m][k] = *(const PG8_LAS bf16x8*)(lds + PG8_SA(b, h) + aoff + m * 2048 + k * 1024); } while (0)
; #define PG8_LDB(dst, b, h) do { _Pragma("unroll") for (int n = 0; n < 2; ++n) _Pragma("unroll") for (int k = 0; k < 2; ++k) dst[n][k] = *(const PG8_LAS bf16x8*)(lds + PG8_SB(b, h) + boff + n * 2048 + k * 1024); } while (0)
; #define PG8_MMA(ai, bj, At, Bt) do { __builtin_amdgcn_s_setprio(1); _Pragma("unroll") for (int m = 0; m < 4; ++m) _Pragma("unroll") for (int n = 0; n < 2; ++n) _Pragma("unroll") for (int k = 0; k < 2; ++k) \
;         acc[ai][bj][m][n] = __builtin_amdgcn_mfma_f32_16x16x32_bf16(Bt[n][k], At[m][k], acc[ai][bj][m][n], 0, 0, 0); __builtin_amdgcn_s_setprio(0); } while (0)
; #define PG8_WAIT_V(n) asm volatile("s_waitcnt vmcnt(" #n ")" ::: "memory")
; #define PG8_BAR __builtin_amdgcn_s_barrier()
; template <class Epi, class Sched, bool ALIGN_EPI = false, bool SP2 = false>
; __device__ __forceinline__ void gemm_phase(PG8_LAS unsigned char* lds, const Gemm g, const Sched& S, const Epi& E) {
;     ...
;         for (int t = 0; t < nt; t += 2) {
;             const bool last = (t == nt - 2);
;             const char* a1 = cA + (size_t)(t + 1) * kstep;
;             const char* a2 = last ? nA : cA + (size_t)(t + 2) * kstep; const char* b2 = last ? nB : cB + (size_t)(t + 2) * kstep;
;             const char* a3 = a2 + kstep; const char* b3 = b2 + kstep;
;             if (last && has_next) S.a_ready(nxt);
;             if constexpr (SP2) {
;             PG8_LDB(B0, 0, 0); PG8_LDB(B1, 0, 1); PG8_SCHED; PG8_LDA(At, 0, 0); PG8_STAGE(PG8_SA(1, 1), a1 + hstep, voffA);
;             PG8_WAIT_V(8); PG8_WAIT_L(0); PG8_BAR; PG8_MMA(0, 0, At, B0); PG8_MMA(0, 1, At, B1); PG8_BAR; PG8_SCHED;
;             PG8_LDA(At, 0, 1); PG8_STAGE(PG8_SB(0, 0), b2, voffB); PG8_STAGE(PG8_SB(0, 1), b2 + hstep, voffB); PG8_STAGE(PG8_SA(0, 0), a2, voffA);
;             PG8_WAIT_V(8); PG8_WAIT_L(0); PG8_BAR; PG8_MMA(1, 0, At, B0); PG8_MMA(1, 1, At, B1); PG8_BAR; PG8_SCHED;
.LBB0_343:
	ds_read_b128 v[144:147], v151
	ds_read_b128 v[154:157], v151 offset:1024
	ds_read_b128 v[158:161], v151 offset:2048
	ds_read_b128 v[162:165], v151 offset:3072
	ds_read_b128 v[166:169], v152
	ds_read_b128 v[170:173], v152 offset:1024
	ds_read_b128 v[174:177], v152 offset:2048
	ds_read_b128 v[178:181], v152 offset:3072
	s_add_u32 s22, s20, 0xfffc0080
	s_addc_u32 s23, s21, -1
	s_cmp_eq_u32 s50, 12
	s_cselect_b32 s25, s13, s23
	s_cselect_b32 s24, s46, s22
	s_cselect_b32 s23, s11, s49
	s_cselect_b32 s22, s47, s48
	v_lshl_add_u64 v[182:183], s[20:21], 0, v[138:139]
	s_add_i32 m0, s19, 0xc000
	ds_read_b128 v[186:189], v153
	ds_read_b128 v[190:193], v153 offset:1024
	ds_read_b128 v[194:197], v153 offset:2048
	ds_read_b128 v[198:201], v153 offset:3072
	ds_read_b128 v[202:205], v153 offset:4096
	ds_read_b128 v[206:209], v153 offset:5120
	ds_read_b128 v[210:213], v153 offset:6144
	ds_read_b128 v[214:217], v153 offset:7168
	global_load_lds_dwordx4 v[182:183], off
	v_lshl_add_u64 v[182:183], s[20:21], 0, v[136:137]
	s_add_i32 m0, s19, 0xe000
	s_nop 0
	global_load_lds_dwordx4 v[182:183], off
	s_waitcnt vmcnt(8)
	s_waitcnt lgkmcnt(0)
	s_barrier
	s_setprio 1
	s_waitcnt lgkmcnt(0)
	v_mfma_f32_16x16x32_bf16 v[124:127], v[144:147], v[186:189], v[124:127]
	v_mfma_f32_16x16x32_bf16 v[120:123], v[158:161], v[186:189], v[120:123]
	v_mfma_f32_16x16x32_bf16 v[116:119], v[144:147], v[194:197], v[116:119]
	v_mfma_f32_16x16x32_bf16 v[108:111], v[158:161], v[194:197], v[108:111]
	v_mfma_f32_16x16x32_bf16 v[100:103], v[144:147], v[202:205], v[100:103]
	v_mfma_f32_16x16x32_bf16 v[92:95], v[158:161], v[202:205], v[92:95]
	v_mfma_f32_16x16x32_bf16 v[84:87], v[144:147], v[210:213], v[84:87]
	v_mfma_f32_16x16x32_bf16 v[76:79], v[158:161], v[210:213], v[76:79]
	v_mfma_f32_16x16x32_bf16 v[124:127], v[154:157], v[190:193], v[124:127]
	v_mfma_f32_16x16x32_bf16 v[120:123], v[162:165], v[190:193], v[120:123]
	v_mfma_f32_16x16x32_bf16 v[116:119], v[154:157], v[198:201], v[116:119]
	v_mfma_f32_16x16x32_bf16 v[108:111], v[162:165], v[198:201], v[108:111]
	v_mfma_f32_16x16x32_bf16 v[100:103], v[154:157], v[206:209], v[100:103]
	v_mfma_f32_16x16x32_bf16 v[92:95], v[162:165], v[206:209], v[92:95]
	v_mfma_f32_16x16x32_bf16 v[84:87], v[154:157], v[214:217], v[84:87]
	v_mfma_f32_16x16x32_bf16 v[76:79], v[162:165], v[214:217], v[76:79]
	s_setprio 0
	s_setprio 1
	v_mfma_f32_16x16x32_bf16 v[112:115], v[166:169], v[186:189], v[112:115]
	v_mfma_f32_16x16x32_bf16 v[104:107], v[174:177], v[186:189], v[104:107]
	v_mfma_f32_16x16x32_bf16 v[96:99], v[166:169], v[194:197], v[96:99]
	v_mfma_f32_16x16x32_bf16 v[88:91], v[174:177], v[194:197], v[88:91]
	v_mfma_f32_16x16x32_bf16 v[80:83], v[166:169], v[202:205], v[80:83]
	v_mfma_f32_16x16x32_bf16 v[72:75], v[174:177], v[202:205], v[72:75]
	v_mfma_f32_16x16x32_bf16 v[68:71], v[166:169], v[210:213], v[68:71]
	v_mfma_f32_16x16x32_bf16 v[64:67], v[174:177], v[210:213], v[64:67]
	v_mfma_f32_16x16x32_bf16 v[112:115], v[170:173], v[190:193], v[112:115]
	v_mfma_f32_16x16x32_bf16 v[104:107], v[178:181], v[190:193], v[104:107]
	v_mfma_f32_16x16x32_bf16 v[96:99], v[170:173], v[198:201], v[96:99]
	v_mfma_f32_16x16x32_bf16 v[88:91], v[178:181], v[198:201], v[88:91]
	v_mfma_f32_16x16x32_bf16 v[80:83], v[170:173], v[206:209], v[80:83]
	v_mfma_f32_16x16x32_bf16 v[72:75], v[178:181], v[206:209], v[72:75]
	v_mfma_f32_16x16x32_bf16 v[68:71], v[170:173], v[214:217], v[68:71]
	v_mfma_f32_16x16x32_bf16 v[64:67], v[178:181], v[214:217], v[64:67]
	s_setprio 0
	s_barrier
	s_add_i32 s51, s42, s30
	v_lshl_add_u64 v[182:183], s[22:23], 0, v[132:133]
	s_mov_b32 m0, s51
	ds_read_b128 v[186:189], v153 offset:16384
	ds_read_b128 v[190:193], v153 offset:17408
	ds_read_b128 v[194:197], v153 offset:18432
	ds_read_b128 v[198:201], v153 offset:19456
	ds_read_b128 v[202:205], v153 offset:20480
	ds_read_b128 v[206:209], v153 offset:21504
	ds_read_b128 v[210:213], v153 offset:22528
	ds_read_b128 v[214:217], v153 offset:23552
	global_load_lds_dwordx4 v[182:183], off
	s_add_i32 m0, s51, 0x2000
	s_add_u32 s52, s22, 0x40000
	v_lshl_add_u64 v[218:219], s[22:23], 0, v[128:129]
	s_addc_u32 s53, s23, 0
	s_add_i32 s51, s43, s30
	global_load_lds_dwordx4 v[218:219], off
	v_lshl_add_u64 v[220:221], s[52:53], 0, v[132:133]
	s_mov_b32 m0, s51
	v_lshl_add_u64 v[222:223], s[24:25], 0, v[130:131]
	global_load_lds_dwordx4 v[220:221], off
	v_lshl_add_u64 v[220:221], s[52:53], 0, v[128:129]
	s_add_i32 m0, s51, 0x2000
	s_nop 0
	global_load_lds_dwordx4 v[220:221], off
	v_lshl_add_u64 v[220:221], s[24:25], 0, v[134:135]
	s_mov_b32 m0, s19
	s_nop 0
	global_load_lds_dwordx4 v[220:221], off
	s_mov_b32 m0, s34
	s_nop 0
	global_load_lds_dwordx4 v[222:223], off
	s_waitcnt vmcnt(8)
	s_waitcnt lgkmcnt(0)
	s_barrier
; #define PG8_STAGE(bufoff, gbase, voff) do { _Pragma("unroll") for (int _i = 0; _i < 2; ++_i) \
;         __builtin_amdgcn_global_load_lds((const unsigned*)((const char*)(gbase) + (voff)[_i]), (PG8_LAS unsigned*)(lds + (bufoff) + ldsw + _i * 8192), 16, 0, 0); } while (0)
; #define PG8_LDA(dst, b, h) do { _Pragma("unroll") for (int m = 0; m < 4; ++m) _Pragma("unroll") for (int k = 0; k < 2; ++k) dst[m][k] = *(const PG8_LAS bf16x8*)(lds + PG8_SA(b, h) + aoff + m * 2048 + k * 1024); } while (0)
; #define PG8_LDB(dst, b, h) do { _Pragma("unroll") for (int n = 0; n < 2; ++n) _Pragma("unroll") for (int k = 0; k < 2; ++k) dst[n][k] = *(const PG8_LAS bf16x8*)(lds + PG8_SB(b, h) + boff + n * 2048 + k * 1024); } while (0)
; #define PG8_MMA(ai, bj, At, Bt) do { __builtin_amdgcn_s_setprio(1); _Pragma("unroll") for (int m = 0; m < 4; ++m) _Pragma("unroll") for (int n = 0; n < 2; ++n) _Pragma("unroll") for (int k = 0; k < 2; ++k) \
;         acc[ai][bj][m][n] = __builtin_amdgcn_mfma_f32_16x16x32_bf16(Bt[n][k], At[m][k], acc[ai][bj][m][n], 0, 0, 0); __builtin_amdgcn_s_setprio(0); } while (0)
; #define PG8_WAIT_V(n) asm volatile("s_waitcnt vmcnt(" #n ")" ::: "memory")
; #define PG8_WAIT_L(n) asm volatile("s_waitcnt lgkmcnt(" #n ")" ::: "memory")
; #define PG8_BAR __builtin_amdgcn_s_barrier()
; #define PG8_SCHED __builtin_amdgcn_sched_barrier(0)
; template <class Epi, class Sched, bool ALIGN_EPI = false, bool SP2 = false>
; __device__ __forceinline__ void gemm_phase(PG8_LAS unsigned char* lds, const Gemm g, const Sched& S, const Epi& E) {
;     ...
;             PG8_WAIT_V(8); PG8_WAIT_L(0); PG8_BAR; PG8_MMA(1, 0, At, B0); PG8_MMA(1, 1, At, B1); PG8_BAR; PG8_SCHED;
;             PG8_LDB(B0, 1, 0); PG8_LDB(B1, 1, 1); PG8_SCHED; PG8_LDA(At, 1, 0); PG8_STAGE(PG8_SA(0, 1), a2 + hstep, voffA);
;             PG8_WAIT_V(8); PG8_WAIT_L(0); PG8_BAR; PG8_MMA(0, 0, At, B0); PG8_MMA(0, 1, At, B1); PG8_BAR; PG8_SCHED;
	s_setprio 1
	s_waitcnt lgkmcnt(0)
	v_mfma_f32_16x16x32_bf16 v[60:63], v[144:147], v[186:189], v[60:63]
	v_mfma_f32_16x16x32_bf16 v[56:59], v[158:161], v[186:189], v[56:59]
	v_mfma_f32_16x16x32_bf16 v[52:55], v[144:147], v[194:197], v[52:55]
	v_mfma_f32_16x16x32_bf16 v[44:47], v[158:161], v[194:197], v[44:47]
	v_mfma_f32_16x16x32_bf16 v[36:39], v[144:147], v[202:205], v[36:39]
	v_mfma_f32_16x16x32_bf16 v[28:31], v[158:161], v[202:205], v[28:31]
	v_mfma_f32_16x16x32_bf16 v[20:23], v[144:147], v[210:213], v[20:23]
	v_mfma_f32_16x16x32_bf16 v[12:15], v[158:161], v[210:213], v[12:15]
	v_mfma_f32_16x16x32_bf16 v[60:63], v[154:157], v[190:193], v[60:63]
	v_mfma_f32_16x16x32_bf16 v[56:59], v[162:165], v[190:193], v[56:59]
	v_mfma_f32_16x16x32_bf16 v[52:55], v[154:157], v[198:201], v[52:55]
	v_mfma_f32_16x16x32_bf16 v[44:47], v[162:165], v[198:201], v[44:47]
	v_mfma_f32_16x16x32_bf16 v[36:39], v[154:157], v[206:209], v[36:39]
	v_mfma_f32_16x16x32_bf16 v[28:31], v[162:165], v[206:209], v[28:31]
	v_mfma_f32_16x16x32_bf16 v[20:23], v[154:157], v[214:217], v[20:23]
	v_mfma_f32_16x16x32_bf16 v[12:15], v[162:165], v[214:217], v[12:15]
	s_setprio 0
	s_setprio 1
	v_mfma_f32_16x16x32_bf16 v[48:51], v[166:169], v[186:189], v[48:51]
	v_mfma_f32_16x16x32_bf16 v[40:43], v[174:177], v[186:189], v[40:43]
	v_mfma_f32_16x16x32_bf16 v[32:35], v[166:169], v[194:197], v[32:35]
	v_mfma_f32_16x16x32_bf16 v[24:27], v[174:177], v[194:197], v[24:27]
	v_mfma_f32_16x16x32_bf16 v[16:19], v[166:169], v[202:205], v[16:19]
	v_mfma_f32_16x16x32_bf16 v[8:11], v[174:177], v[202:205], v[8:11]
	v_mfma_f32_16x16x32_bf16 v[4:7], v[166:169], v[210:213], v[4:7]
	v_mfma_f32_16x16x32_bf16 v[0:3], v[174:177], v[210:213], v[0:3]
	v_mfma_f32_16x16x32_bf16 v[48:51], v[170:173], v[190:193], v[48:51]
	v_mfma_f32_16x16x32_bf16 v[40:43], v[178:181], v[190:193], v[40:43]
	v_mfma_f32_16x16x32_bf16 v[32:35], v[170:173], v[198:201], v[32:35]
	v_mfma_f32_16x16x32_bf16 v[24:27], v[178:181], v[198:201], v[24:27]
	v_mfma_f32_16x16x32_bf16 v[16:19], v[170:173], v[206:209], v[16:19]
	v_mfma_f32_16x16x32_bf16 v[8:11], v[178:181], v[206:209], v[8:11]
	v_mfma_f32_16x16x32_bf16 v[4:7], v[170:173], v[214:217], v[4:7]
	v_mfma_f32_16x16x32_bf16 v[0:3], v[178:181], v[214:217], v[0:3]
	s_setprio 0
	s_barrier
	s_add_i32 s51, 0, 0x18000
	s_add_i32 s52, 0, 0x1c000
	v_add_u32_e32 v162, s51, v149
	v_add_u32_e32 v178, s52, v149
	ds_read_b128 v[144:147], v162
	ds_read_b128 v[154:157], v162 offset:1024
	ds_read_b128 v[158:161], v162 offset:2048
	ds_read_b128 v[162:165], v162 offset:3072
	ds_read_b128 v[166:169], v178
	ds_read_b128 v[170:173], v178 offset:1024
	ds_read_b128 v[174:177], v178 offset:2048
	ds_read_b128 v[178:181], v178 offset:3072
	s_add_u32 s24, s24, 0x40000
	s_addc_u32 s25, s25, 0
	s_mov_b32 m0, s35
	v_lshl_add_u64 v[224:225], s[24:25], 0, v[134:135]
	ds_read_b128 v[186:189], v153 offset:32768
	ds_read_b128 v[190:193], v153 offset:33792
	ds_read_b128 v[194:197], v153 offset:34816
	ds_read_b128 v[198:201], v153 offset:35840
	ds_read_b128 v[202:205], v153 offset:36864
	ds_read_b128 v[206:209], v153 offset:37888
	ds_read_b128 v[210:213], v153 offset:38912
	ds_read_b128 v[214:217], v153 offset:39936
	global_load_lds_dwordx4 v[224:225], off
	v_lshl_add_u64 v[224:225], s[24:25], 0, v[130:131]
	s_mov_b32 m0, s36
	s_nop 0
	global_load_lds_dwordx4 v[224:225], off
	s_waitcnt vmcnt(8)
	s_waitcnt lgkmcnt(0)
	s_barrier
	s_setprio 1
	s_waitcnt lgkmcnt(0)
	v_mfma_f32_16x16x32_bf16 v[124:127], v[144:147], v[186:189], v[124:127]
	v_mfma_f32_16x16x32_bf16 v[120:123], v[158:161], v[186:189], v[120:123]
	v_mfma_f32_16x16x32_bf16 v[116:119], v[144:147], v[194:197], v[116:119]
	v_mfma_f32_16x16x32_bf16 v[108:111], v[158:161], v[194:197], v[108:111]
	v_mfma_f32_16x16x32_bf16 v[100:103], v[144:147], v[202:205], v[100:103]
	v_mfma_f32_16x16x32_bf16 v[92:95], v[158:161], v[202:205], v[92:95]
	v_mfma_f32_16x16x32_bf16 v[84:87], v[144:147], v[210:213], v[84:87]
	v_mfma_f32_16x16x32_bf16 v[76:79], v[158:161], v[210:213], v[76:79]
	v_mfma_f32_16x16x32_bf16 v[124:127], v[154:157], v[190:193], v[124:127]
	v_mfma_f32_16x16x32_bf16 v[120:123], v[162:165], v[190:193], v[120:123]
	v_mfma_f32_16x16x32_bf16 v[116:119], v[154:157], v[198:201], v[116:119]
	v_mfma_f32_16x16x32_bf16 v[108:111], v[162:165], v[198:201], v[108:111]
	v_mfma_f32_16x16x32_bf16 v[100:103], v[154:157], v[206:209], v[100:103]
	v_mfma_f32_16x16x32_bf16 v[92:95], v[162:165], v[206:209], v[92:95]
	v_mfma_f32_16x16x32_bf16 v[84:87], v[154:157], v[214:217], v[84:87]
	v_mfma_f32_16x16x32_bf16 v[76:79], v[162:165], v[214:217], v[76:79]
	s_setprio 0
	s_setprio 1
	v_mfma_f32_16x16x32_bf16 v[112:115], v[166:169], v[186:189], v[112:115]
	v_mfma_f32_16x16x32_bf16 v[104:107], v[174:177], v[186:189], v[104:107]
	v_mfma_f32_16x16x32_bf16 v[96:99], v[166:169], v[194:197], v[96:99]
	v_mfma_f32_16x16x32_bf16 v[88:91], v[174:177], v[194:197], v[88:91]
	v_mfma_f32_16x16x32_bf16 v[80:83], v[166:169], v[202:205], v[80:83]
	v_mfma_f32_16x16x32_bf16 v[72:75], v[174:177], v[202:205], v[72:75]
	v_mfma_f32_16x16x32_bf16 v[68:71], v[166:169], v[210:213], v[68:71]
	v_mfma_f32_16x16x32_bf16 v[64:67], v[174:177], v[210:213], v[64:67]
	v_mfma_f32_16x16x32_bf16 v[112:115], v[170:173], v[190:193], v[112:115]
	v_mfma_f32_16x16x32_bf16 v[104:107], v[178:181], v[190:193], v[104:107]
	v_mfma_f32_16x16x32_bf16 v[96:99], v[170:173], v[198:201], v[96:99]
	v_mfma_f32_16x16x32_bf16 v[88:91], v[178:181], v[198:201], v[88:91]
	v_mfma_f32_16x16x32_bf16 v[80:83], v[170:173], v[206:209], v[80:83]
	v_mfma_f32_16x16x32_bf16 v[72:75], v[178:181], v[206:209], v[72:75]
	v_mfma_f32_16x16x32_bf16 v[68:71], v[170:173], v[214:217], v[68:71]
	v_mfma_f32_16x16x32_bf16 v[64:67], v[178:181], v[214:217], v[64:67]
	s_setprio 0
	s_barrier
; #define PG8_STAGE(bufoff, gbase, voff) do { _Pragma("unroll") for (int _i = 0; _i < 2; ++_i) \
;         __builtin_amdgcn_global_load_lds((const unsigned*)((const char*)(gbase) + (voff)[_i]), (PG8_LAS unsigned*)(lds + (bufoff) + ldsw + _i * 8192), 16, 0, 0); } while (0)
; #define PG8_LDA(dst, b, h) do { _Pragma("unroll") for (int m = 0; m < 4; ++m) _Pragma("unroll") for (int k = 0; k < 2; ++k) dst[m][k] = *(const PG8_LAS bf16x8*)(lds + PG8_SA(b, h) + aoff + m * 2048 + k * 1024); } while (0)
; #define PG8_MMA(ai, bj, At, Bt) do { __builtin_amdgcn_s_setprio(1); _Pragma("unroll") for (int m = 0; m < 4; ++m) _Pragma("unroll") for (int n = 0; n < 2; ++n) _Pragma("unroll") for (int k = 0; k < 2; ++k) \
;         acc[ai][bj][m][n] = __builtin_amdgcn_mfma_f32_16x16x32_bf16(Bt[n][k], At[m][k], acc[ai][bj][m][n], 0, 0, 0); __builtin_amdgcn_s_setprio(0); } while (0)
; #define PG8_WAIT_V(n) asm volatile("s_waitcnt vmcnt(" #n ")" ::: "memory")
; #define PG8_WAIT_L(n) asm volatile("s_waitcnt lgkmcnt(" #n ")" ::: "memory")
; #define PG8_BAR __builtin_amdgcn_s_barrier()
; #define PG8_SCHED __builtin_amdgcn_sched_barrier(0)
; template <class Epi, class Sched, bool ALIGN_EPI = false, bool SP2 = false>
; __device__ __forceinline__ void gemm_phase(PG8_LAS unsigned char* lds, const Gemm g, const Sched& S, const Epi& E) {
;     ...
;         for (int t = 0; t < nt; t += 2) {
;             const bool last = (t == nt - 2);
;             const char* a1 = cA + (size_t)(t + 1) * kstep;
;             const char* a2 = last ? nA : cA + (size_t)(t + 2) * kstep; const char* b2 = last ? nB : cB + (size_t)(t + 2) * kstep;
;             const char* a3 = a2 + kstep; const char* b3 = b2 + kstep;
;     ...
;             PG8_LDA(At, 1, 1); PG8_STAGE(PG8_SB(1, 0), b3, voffB); PG8_STAGE(PG8_SB(1, 1), b3 + hstep, voffB); PG8_STAGE(PG8_SA(1, 0), a3, voffA);
;             PG8_WAIT_V(8); PG8_WAIT_L(0); PG8_BAR; PG8_MMA(1, 0, At, B0); PG8_MMA(1, 1, At, B1); PG8_BAR; PG8_SCHED;
	s_add_i32 s24, s51, s30
	v_lshl_add_u64 v[182:183], v[182:183], 0, s[6:7]
	s_mov_b32 m0, s24
	ds_read_b128 v[186:189], v153 offset:49152
	ds_read_b128 v[190:193], v153 offset:50176
	ds_read_b128 v[194:197], v153 offset:51200
	ds_read_b128 v[198:201], v153 offset:52224
	ds_read_b128 v[202:205], v153 offset:53248
	ds_read_b128 v[206:209], v153 offset:54272
	ds_read_b128 v[210:213], v153 offset:55296
	ds_read_b128 v[214:217], v153 offset:56320
	global_load_lds_dwordx4 v[182:183], off
	s_add_i32 m0, s24, 0x2000
	s_add_u32 s22, s22, 0x40080
	v_lshl_add_u64 v[182:183], v[218:219], 0, s[6:7]
	s_addc_u32 s23, s23, 0
	s_add_i32 s24, s52, s30
	global_load_lds_dwordx4 v[182:183], off
	v_lshl_add_u64 v[182:183], s[22:23], 0, v[132:133]
	s_mov_b32 m0, s24
	s_nop 0
	global_load_lds_dwordx4 v[182:183], off
	v_lshl_add_u64 v[182:183], s[22:23], 0, v[128:129]
	s_add_i32 m0, s24, 0x2000
	s_nop 0
	global_load_lds_dwordx4 v[182:183], off
	v_lshl_add_u64 v[182:183], v[220:221], 0, s[6:7]
	s_mov_b32 m0, s37
	s_nop 0
	global_load_lds_dwordx4 v[182:183], off
	v_lshl_add_u64 v[182:183], v[222:223], 0, s[6:7]
	s_mov_b32 m0, s38
	s_nop 0
	global_load_lds_dwordx4 v[182:183], off
	s_waitcnt vmcnt(8)
	s_waitcnt lgkmcnt(0)
	s_barrier
	s_setprio 1
	s_waitcnt lgkmcnt(0)
	v_mfma_f32_16x16x32_bf16 v[60:63], v[144:147], v[186:189], v[60:63]
	v_mfma_f32_16x16x32_bf16 v[56:59], v[158:161], v[186:189], v[56:59]
	v_mfma_f32_16x16x32_bf16 v[52:55], v[144:147], v[194:197], v[52:55]
	v_mfma_f32_16x16x32_bf16 v[44:47], v[158:161], v[194:197], v[44:47]
	v_mfma_f32_16x16x32_bf16 v[36:39], v[144:147], v[202:205], v[36:39]
	v_mfma_f32_16x16x32_bf16 v[28:31], v[158:161], v[202:205], v[28:31]
	v_mfma_f32_16x16x32_bf16 v[20:23], v[144:147], v[210:213], v[20:23]
	v_mfma_f32_16x16x32_bf16 v[12:15], v[158:161], v[210:213], v[12:15]
	v_mfma_f32_16x16x32_bf16 v[60:63], v[154:157], v[190:193], v[60:63]
	v_mfma_f32_16x16x32_bf16 v[56:59], v[162:165], v[190:193], v[56:59]
	v_mfma_f32_16x16x32_bf16 v[52:55], v[154:157], v[198:201], v[52:55]
	v_mfma_f32_16x16x32_bf16 v[44:47], v[162:165], v[198:201], v[44:47]
	v_mfma_f32_16x16x32_bf16 v[36:39], v[154:157], v[206:209], v[36:39]
	v_mfma_f32_16x16x32_bf16 v[28:31], v[162:165], v[206:209], v[28:31]
	v_mfma_f32_16x16x32_bf16 v[20:23], v[154:157], v[214:217], v[20:23]
	v_mfma_f32_16x16x32_bf16 v[12:15], v[162:165], v[214:217], v[12:15]
	s_setprio 0
	s_setprio 1
	v_mfma_f32_16x16x32_bf16 v[48:51], v[166:169], v[186:189], v[48:51]
	v_mfma_f32_16x16x32_bf16 v[40:43], v[174:177], v[186:189], v[40:43]
	v_mfma_f32_16x16x32_bf16 v[32:35], v[166:169], v[194:197], v[32:35]
	v_mfma_f32_16x16x32_bf16 v[24:27], v[174:177], v[194:197], v[24:27]
	v_mfma_f32_16x16x32_bf16 v[16:19], v[166:169], v[202:205], v[16:19]
	v_mfma_f32_16x16x32_bf16 v[8:11], v[174:177], v[202:205], v[8:11]
	v_mfma_f32_16x16x32_bf16 v[4:7], v[166:169], v[210:213], v[4:7]
	v_mfma_f32_16x16x32_bf16 v[0:3], v[174:177], v[210:213], v[0:3]
	v_mfma_f32_16x16x32_bf16 v[48:51], v[170:173], v[190:193], v[48:51]
	v_mfma_f32_16x16x32_bf16 v[40:43], v[178:181], v[190:193], v[40:43]
	v_mfma_f32_16x16x32_bf16 v[32:35], v[170:173], v[198:201], v[32:35]
	v_mfma_f32_16x16x32_bf16 v[24:27], v[178:181], v[198:201], v[24:27]
	v_mfma_f32_16x16x32_bf16 v[16:19], v[170:173], v[206:209], v[16:19]
	v_mfma_f32_16x16x32_bf16 v[8:11], v[178:181], v[206:209], v[8:11]
	v_mfma_f32_16x16x32_bf16 v[4:7], v[170:173], v[214:217], v[4:7]
	v_mfma_f32_16x16x32_bf16 v[0:3], v[178:181], v[214:217], v[0:3]
	s_setprio 0
	s_add_i32 s50, s50, 2
	s_add_u32 s48, s48, 0x100
	s_addc_u32 s49, s49, 0
	s_add_u32 s20, s20, 0x100
	s_addc_u32 s21, s21, 0
	s_cmp_gt_u32 s50, 13
	s_barrier
	s_cbranch_scc0 .LBB0_343
	s_and_b64 vcc, exec, s[8:9]
	s_cbranch_vccz .LBB0_346
	s_barrier

; #define PG8_STAGE(bufoff, gbase, voff) do { _Pragma("unroll") for (int _i = 0; _i < 2; ++_i) \
;         __builtin_amdgcn_global_load_lds((const unsigned*)((const char*)(gbase) + (voff)[_i]), (PG8_LAS unsigned*)(lds + (bufoff) + ldsw + _i * 8192), 16, 0, 0); } while (0)
; #define PG8_LDA(dst, b, h) do { _Pragma("unroll") for (int m = 0; m < 4; ++m) _Pragma("unroll") for (int k = 0; k < 2; ++k) dst[m][k] = *(const PG8_LAS bf16x8*)(lds + PG8_SA(b, h) + aoff + m * 2048 + k * 1024); } while (0)
; #define PG8_LDB(dst, b, h) do { _Pragma("unroll") for (int n = 0; n < 2; ++n) _Pragma("unroll") for (int k = 0; k < 2; ++k) dst[n][k] = *(const PG8_LAS bf16x8*)(lds + PG8_SB(b, h) + boff + n * 2048 + k * 1024); } while (0)
; #define PG8_MMA(ai, bj, At, Bt) do { __builtin_amdgcn_s_setprio(1); _Pragma("unroll") for (int m = 0; m < 4; ++m) _Pragma("unroll") for (int n = 0; n < 2; ++n) _Pragma("unroll") for (int k = 0; k < 2; ++k) \
;         acc[ai][bj][m][n] = __builtin_amdgcn_mfma_f32_16x16x32_bf16(Bt[n][k], At[m][k], acc[ai][bj][m][n], 0, 0, 0); __builtin_amdgcn_s_setprio(0); } while (0)
; #define PG8_WAIT_V(n) asm volatile("s_waitcnt vmcnt(" #n ")" ::: "memory")
; #define PG8_BAR __builtin_amdgcn_s_barrier()
; template <class Epi, class Sched, bool ALIGN_EPI = false, bool SP2 = false>
; __device__ __forceinline__ void gemm_phase(PG8_LAS unsigned char* lds, const Gemm g, const Sched& S, const Epi& E) {
;     ...
;         for (int t = 0; t < nt; t += 2) {
;             const bool last = (t == nt - 2);
;             const char* a1 = cA + (size_t)(t + 1) * kstep;
;             const char* a2 = last ? nA : cA + (size_t)(t + 2) * kstep; const char* b2 = last ? nB : cB + (size_t)(t + 2) * kstep;
;             const char* a3 = a2 + kstep; const char* b3 = b2 + kstep;
;             if (last && has_next) S.a_ready(nxt);
;             if constexpr (SP2) {
;             PG8_LDB(B0, 0, 0); PG8_LDB(B1, 0, 1); PG8_SCHED; PG8_LDA(At, 0, 0); PG8_STAGE(PG8_SA(1, 1), a1 + hstep, voffA);
;             PG8_WAIT_V(8); PG8_WAIT_L(0); PG8_BAR; PG8_MMA(0, 0, At, B0); PG8_MMA(0, 1, At, B1); PG8_BAR; PG8_SCHED;
;             PG8_LDA(At, 0, 1); PG8_STAGE(PG8_SB(0, 0), b2, voffB); PG8_STAGE(PG8_SB(0, 1), b2 + hstep, voffB); PG8_STAGE(PG8_SA(0, 0), a2, voffA);
;             PG8_WAIT_V(8); PG8_WAIT_L(0); PG8_BAR; PG8_MMA(1, 0, At, B0); PG8_MMA(1, 1, At, B1); PG8_BAR; PG8_SCHED;
.LBB0_424:
	ds_read_b128 v[140:143], v147
	ds_read_b128 v[150:153], v147 offset:1024
	ds_read_b128 v[154:157], v147 offset:2048
	ds_read_b128 v[158:161], v147 offset:3072
	ds_read_b128 v[162:165], v148
	ds_read_b128 v[166:169], v148 offset:1024
	ds_read_b128 v[170:173], v148 offset:2048
	ds_read_b128 v[174:177], v148 offset:3072
	s_add_u32 s22, s20, 0xfffc0080
	s_addc_u32 s23, s21, -1
	s_cmp_eq_u32 s48, 12
	s_cselect_b32 s25, s15, s23
	s_cselect_b32 s24, s44, s22
	s_cselect_b32 s23, s11, s47
	s_cselect_b32 s22, s45, s46
	v_lshl_add_u64 v[182:183], s[20:21], 0, v[138:139]
	s_add_i32 m0, s29, 0xc000
	ds_read_b128 v[178:181], v149
	ds_read_b128 v[186:189], v149 offset:1024
	ds_read_b128 v[190:193], v149 offset:2048
	ds_read_b128 v[194:197], v149 offset:3072
	ds_read_b128 v[198:201], v149 offset:4096
	ds_read_b128 v[202:205], v149 offset:5120
	ds_read_b128 v[206:209], v149 offset:6144
	ds_read_b128 v[210:213], v149 offset:7168
	global_load_lds_dwordx4 v[182:183], off
	v_lshl_add_u64 v[182:183], s[20:21], 0, v[136:137]
	s_add_i32 m0, s29, 0xe000
	s_nop 0
	global_load_lds_dwordx4 v[182:183], off
	s_waitcnt vmcnt(8)
	s_waitcnt lgkmcnt(0)
	s_barrier
	s_setprio 1
	s_waitcnt lgkmcnt(0)
	v_mfma_f32_16x16x32_bf16 v[124:127], v[140:143], v[178:181], v[124:127]
	v_mfma_f32_16x16x32_bf16 v[120:123], v[154:157], v[178:181], v[120:123]
	v_mfma_f32_16x16x32_bf16 v[116:119], v[140:143], v[190:193], v[116:119]
	v_mfma_f32_16x16x32_bf16 v[108:111], v[154:157], v[190:193], v[108:111]
	v_mfma_f32_16x16x32_bf16 v[100:103], v[140:143], v[198:201], v[100:103]
	v_mfma_f32_16x16x32_bf16 v[92:95], v[154:157], v[198:201], v[92:95]
	v_mfma_f32_16x16x32_bf16 v[84:87], v[140:143], v[206:209], v[84:87]
	v_mfma_f32_16x16x32_bf16 v[76:79], v[154:157], v[206:209], v[76:79]
	v_mfma_f32_16x16x32_bf16 v[124:127], v[150:153], v[186:189], v[124:127]
	v_mfma_f32_16x16x32_bf16 v[120:123], v[158:161], v[186:189], v[120:123]
	v_mfma_f32_16x16x32_bf16 v[116:119], v[150:153], v[194:197], v[116:119]
	v_mfma_f32_16x16x32_bf16 v[108:111], v[158:161], v[194:197], v[108:111]
	v_mfma_f32_16x16x32_bf16 v[100:103], v[150:153], v[202:205], v[100:103]
	v_mfma_f32_16x16x32_bf16 v[92:95], v[158:161], v[202:205], v[92:95]
	v_mfma_f32_16x16x32_bf16 v[84:87], v[150:153], v[210:213], v[84:87]
	v_mfma_f32_16x16x32_bf16 v[76:79], v[158:161], v[210:213], v[76:79]
	s_setprio 0
	s_setprio 1
	v_mfma_f32_16x16x32_bf16 v[112:115], v[162:165], v[178:181], v[112:115]
	v_mfma_f32_16x16x32_bf16 v[104:107], v[170:173], v[178:181], v[104:107]
	v_mfma_f32_16x16x32_bf16 v[96:99], v[162:165], v[190:193], v[96:99]
	v_mfma_f32_16x16x32_bf16 v[88:91], v[170:173], v[190:193], v[88:91]
	v_mfma_f32_16x16x32_bf16 v[80:83], v[162:165], v[198:201], v[80:83]
	v_mfma_f32_16x16x32_bf16 v[72:75], v[170:173], v[198:201], v[72:75]
	v_mfma_f32_16x16x32_bf16 v[68:71], v[162:165], v[206:209], v[68:71]
	v_mfma_f32_16x16x32_bf16 v[64:67], v[170:173], v[206:209], v[64:67]
	v_mfma_f32_16x16x32_bf16 v[112:115], v[166:169], v[186:189], v[112:115]
	v_mfma_f32_16x16x32_bf16 v[104:107], v[174:177], v[186:189], v[104:107]
	v_mfma_f32_16x16x32_bf16 v[96:99], v[166:169], v[194:197], v[96:99]
	v_mfma_f32_16x16x32_bf16 v[88:91], v[174:177], v[194:197], v[88:91]
	v_mfma_f32_16x16x32_bf16 v[80:83], v[166:169], v[202:205], v[80:83]
	v_mfma_f32_16x16x32_bf16 v[72:75], v[174:177], v[202:205], v[72:75]
	v_mfma_f32_16x16x32_bf16 v[68:71], v[166:169], v[210:213], v[68:71]
	v_mfma_f32_16x16x32_bf16 v[64:67], v[174:177], v[210:213], v[64:67]
	s_setprio 0
	s_barrier
	s_add_i32 s49, s38, s28
	v_lshl_add_u64 v[182:183], s[22:23], 0, v[130:131]
	s_mov_b32 m0, s49
	ds_read_b128 v[178:181], v149 offset:16384
	ds_read_b128 v[186:189], v149 offset:17408
	ds_read_b128 v[190:193], v149 offset:18432
	ds_read_b128 v[194:197], v149 offset:19456
	ds_read_b128 v[198:201], v149 offset:20480
	ds_read_b128 v[202:205], v149 offset:21504
	ds_read_b128 v[206:209], v149 offset:22528
	ds_read_b128 v[210:213], v149 offset:23552
	global_load_lds_dwordx4 v[182:183], off
	s_add_i32 m0, s49, 0x2000
	s_add_u32 s50, s22, 0x40000
	v_lshl_add_u64 v[214:215], s[22:23], 0, v[134:135]
	s_addc_u32 s51, s23, 0
	s_add_i32 s49, s39, s28
	global_load_lds_dwordx4 v[214:215], off
	v_lshl_add_u64 v[216:217], s[50:51], 0, v[130:131]
	s_mov_b32 m0, s49
	v_lshl_add_u64 v[218:219], s[24:25], 0, v[132:133]
	global_load_lds_dwordx4 v[216:217], off
	v_lshl_add_u64 v[216:217], s[50:51], 0, v[134:135]
	s_add_i32 m0, s49, 0x2000
	s_nop 0
	global_load_lds_dwordx4 v[216:217], off
	v_lshl_add_u64 v[216:217], s[24:25], 0, v[128:129]
	s_mov_b32 m0, s29
	s_nop 0
	global_load_lds_dwordx4 v[216:217], off
	s_mov_b32 m0, s30
	s_nop 0
	global_load_lds_dwordx4 v[218:219], off
	s_waitcnt vmcnt(8)
	s_waitcnt lgkmcnt(0)
	s_barrier
; #define PG8_STAGE(bufoff, gbase, voff) do { _Pragma("unroll") for (int _i = 0; _i < 2; ++_i) \
;         __builtin_amdgcn_global_load_lds((const unsigned*)((const char*)(gbase) + (voff)[_i]), (PG8_LAS unsigned*)(lds + (bufoff) + ldsw + _i * 8192), 16, 0, 0); } while (0)
; #define PG8_LDA(dst, b, h) do { _Pragma("unroll") for (int m = 0; m < 4; ++m) _Pragma("unroll") for (int k = 0; k < 2; ++k) dst[m][k] = *(const PG8_LAS bf16x8*)(lds + PG8_SA(b, h) + aoff + m * 2048 + k * 1024); } while (0)
; #define PG8_LDB(dst, b, h) do { _Pragma("unroll") for (int n = 0; n < 2; ++n) _Pragma("unroll") for (int k = 0; k < 2; ++k) dst[n][k] = *(const PG8_LAS bf16x8*)(lds + PG8_SB(b, h) + boff + n * 2048 + k * 1024); } while (0)
; #define PG8_MMA(ai, bj, At, Bt) do { __builtin_amdgcn_s_setprio(1); _Pragma("unroll") for (int m = 0; m < 4; ++m) _Pragma("unroll") for (int n = 0; n < 2; ++n) _Pragma("unroll") for (int k = 0; k < 2; ++k) \
;         acc[ai][bj][m][n] = __builtin_amdgcn_mfma_f32_16x16x32_bf16(Bt[n][k], At[m][k], acc[ai][bj][m][n], 0, 0, 0); __builtin_amdgcn_s_setprio(0); } while (0)
; #define PG8_WAIT_V(n) asm volatile("s_waitcnt vmcnt(" #n ")" ::: "memory")
; #define PG8_WAIT_L(n) asm volatile("s_waitcnt lgkmcnt(" #n ")" ::: "memory")
; #define PG8_BAR __builtin_amdgcn_s_barrier()
; #define PG8_SCHED __builtin_amdgcn_sched_barrier(0)
; template <class Epi, class Sched, bool ALIGN_EPI = false, bool SP2 = false>
; __device__ __forceinline__ void gemm_phase(PG8_LAS unsigned char* lds, const Gemm g, const Sched& S, const Epi& E) {
;     ...
;             PG8_WAIT_V(8); PG8_WAIT_L(0); PG8_BAR; PG8_MMA(1, 0, At, B0); PG8_MMA(1, 1, At, B1); PG8_BAR; PG8_SCHED;
;             PG8_LDB(B0, 1, 0); PG8_LDB(B1, 1, 1); PG8_SCHED; PG8_LDA(At, 1, 0); PG8_STAGE(PG8_SA(0, 1), a2 + hstep, voffA);
;             PG8_WAIT_V(8); PG8_WAIT_L(0); PG8_BAR; PG8_MMA(0, 0, At, B0); PG8_MMA(0, 1, At, B1); PG8_BAR; PG8_SCHED;
	s_setprio 1
	s_waitcnt lgkmcnt(0)
	v_mfma_f32_16x16x32_bf16 v[60:63], v[140:143], v[178:181], v[60:63]
	v_mfma_f32_16x16x32_bf16 v[56:59], v[154:157], v[178:181], v[56:59]
	v_mfma_f32_16x16x32_bf16 v[52:55], v[140:143], v[190:193], v[52:55]
	v_mfma_f32_16x16x32_bf16 v[44:47], v[154:157], v[190:193], v[44:47]
	v_mfma_f32_16x16x32_bf16 v[36:39], v[140:143], v[198:201], v[36:39]
	v_mfma_f32_16x16x32_bf16 v[28:31], v[154:157], v[198:201], v[28:31]
	v_mfma_f32_16x16x32_bf16 v[20:23], v[140:143], v[206:209], v[20:23]
	v_mfma_f32_16x16x32_bf16 v[12:15], v[154:157], v[206:209], v[12:15]
	v_mfma_f32_16x16x32_bf16 v[60:63], v[150:153], v[186:189], v[60:63]
	v_mfma_f32_16x16x32_bf16 v[56:59], v[158:161], v[186:189], v[56:59]
	v_mfma_f32_16x16x32_bf16 v[52:55], v[150:153], v[194:197], v[52:55]
	v_mfma_f32_16x16x32_bf16 v[44:47], v[158:161], v[194:197], v[44:47]
	v_mfma_f32_16x16x32_bf16 v[36:39], v[150:153], v[202:205], v[36:39]
	v_mfma_f32_16x16x32_bf16 v[28:31], v[158:161], v[202:205], v[28:31]
	v_mfma_f32_16x16x32_bf16 v[20:23], v[150:153], v[210:213], v[20:23]
	v_mfma_f32_16x16x32_bf16 v[12:15], v[158:161], v[210:213], v[12:15]
	s_setprio 0
	s_setprio 1
	v_mfma_f32_16x16x32_bf16 v[48:51], v[162:165], v[178:181], v[48:51]
	v_mfma_f32_16x16x32_bf16 v[40:43], v[170:173], v[178:181], v[40:43]
	v_mfma_f32_16x16x32_bf16 v[32:35], v[162:165], v[190:193], v[32:35]
	v_mfma_f32_16x16x32_bf16 v[24:27], v[170:173], v[190:193], v[24:27]
	v_mfma_f32_16x16x32_bf16 v[16:19], v[162:165], v[198:201], v[16:19]
	v_mfma_f32_16x16x32_bf16 v[8:11], v[170:173], v[198:201], v[8:11]
	v_mfma_f32_16x16x32_bf16 v[4:7], v[162:165], v[206:209], v[4:7]
	v_mfma_f32_16x16x32_bf16 v[0:3], v[170:173], v[206:209], v[0:3]
	v_mfma_f32_16x16x32_bf16 v[48:51], v[166:169], v[186:189], v[48:51]
	v_mfma_f32_16x16x32_bf16 v[40:43], v[174:177], v[186:189], v[40:43]
	v_mfma_f32_16x16x32_bf16 v[32:35], v[166:169], v[194:197], v[32:35]
	v_mfma_f32_16x16x32_bf16 v[24:27], v[174:177], v[194:197], v[24:27]
	v_mfma_f32_16x16x32_bf16 v[16:19], v[166:169], v[202:205], v[16:19]
	v_mfma_f32_16x16x32_bf16 v[8:11], v[174:177], v[202:205], v[8:11]
	v_mfma_f32_16x16x32_bf16 v[4:7], v[166:169], v[210:213], v[4:7]
	v_mfma_f32_16x16x32_bf16 v[0:3], v[174:177], v[210:213], v[0:3]
	s_setprio 0
	s_barrier
	s_add_i32 s49, 0, 0x18000
	s_add_i32 s50, 0, 0x1c000
	v_add_u32_e32 v158, s49, v145
	v_add_u32_e32 v174, s50, v145
	ds_read_b128 v[140:143], v158
	ds_read_b128 v[150:153], v158 offset:1024
	ds_read_b128 v[154:157], v158 offset:2048
	ds_read_b128 v[158:161], v158 offset:3072
	ds_read_b128 v[162:165], v174
	ds_read_b128 v[166:169], v174 offset:1024
	ds_read_b128 v[170:173], v174 offset:2048
	ds_read_b128 v[174:177], v174 offset:3072
	s_add_u32 s24, s24, 0x40000
	s_addc_u32 s25, s25, 0
	s_mov_b32 m0, s31
	v_lshl_add_u64 v[220:221], s[24:25], 0, v[128:129]
	ds_read_b128 v[178:181], v149 offset:32768
	ds_read_b128 v[186:189], v149 offset:33792
	ds_read_b128 v[190:193], v149 offset:34816
	ds_read_b128 v[194:197], v149 offset:35840
	ds_read_b128 v[198:201], v149 offset:36864
	ds_read_b128 v[202:205], v149 offset:37888
	ds_read_b128 v[206:209], v149 offset:38912
	ds_read_b128 v[210:213], v149 offset:39936
	global_load_lds_dwordx4 v[220:221], off
	v_lshl_add_u64 v[220:221], s[24:25], 0, v[132:133]
	s_mov_b32 m0, s33
	s_nop 0
	global_load_lds_dwordx4 v[220:221], off
	s_waitcnt vmcnt(8)
	s_waitcnt lgkmcnt(0)
	s_barrier
	s_setprio 1
	s_waitcnt lgkmcnt(0)
	v_mfma_f32_16x16x32_bf16 v[124:127], v[140:143], v[178:181], v[124:127]
	v_mfma_f32_16x16x32_bf16 v[120:123], v[154:157], v[178:181], v[120:123]
	v_mfma_f32_16x16x32_bf16 v[116:119], v[140:143], v[190:193], v[116:119]
	v_mfma_f32_16x16x32_bf16 v[108:111], v[154:157], v[190:193], v[108:111]
	v_mfma_f32_16x16x32_bf16 v[100:103], v[140:143], v[198:201], v[100:103]
	v_mfma_f32_16x16x32_bf16 v[92:95], v[154:157], v[198:201], v[92:95]
	v_mfma_f32_16x16x32_bf16 v[84:87], v[140:143], v[206:209], v[84:87]
	v_mfma_f32_16x16x32_bf16 v[76:79], v[154:157], v[206:209], v[76:79]
	v_mfma_f32_16x16x32_bf16 v[124:127], v[150:153], v[186:189], v[124:127]
	v_mfma_f32_16x16x32_bf16 v[120:123], v[158:161], v[186:189], v[120:123]
	v_mfma_f32_16x16x32_bf16 v[116:119], v[150:153], v[194:197], v[116:119]
	v_mfma_f32_16x16x32_bf16 v[108:111], v[158:161], v[194:197], v[108:111]
	v_mfma_f32_16x16x32_bf16 v[100:103], v[150:153], v[202:205], v[100:103]
	v_mfma_f32_16x16x32_bf16 v[92:95], v[158:161], v[202:205], v[92:95]
	v_mfma_f32_16x16x32_bf16 v[84:87], v[150:153], v[210:213], v[84:87]
	v_mfma_f32_16x16x32_bf16 v[76:79], v[158:161], v[210:213], v[76:79]
	s_setprio 0
	s_setprio 1
	v_mfma_f32_16x16x32_bf16 v[112:115], v[162:165], v[178:181], v[112:115]
	v_mfma_f32_16x16x32_bf16 v[104:107], v[170:173], v[178:181], v[104:107]
	v_mfma_f32_16x16x32_bf16 v[96:99], v[162:165], v[190:193], v[96:99]
	v_mfma_f32_16x16x32_bf16 v[88:91], v[170:173], v[190:193], v[88:91]
	v_mfma_f32_16x16x32_bf16 v[80:83], v[162:165], v[198:201], v[80:83]
	v_mfma_f32_16x16x32_bf16 v[72:75], v[170:173], v[198:201], v[72:75]
	v_mfma_f32_16x16x32_bf16 v[68:71], v[162:165], v[206:209], v[68:71]
	v_mfma_f32_16x16x32_bf16 v[64:67], v[170:173], v[206:209], v[64:67]
	v_mfma_f32_16x16x32_bf16 v[112:115], v[166:169], v[186:189], v[112:115]
	v_mfma_f32_16x16x32_bf16 v[104:107], v[174:177], v[186:189], v[104:107]
	v_mfma_f32_16x16x32_bf16 v[96:99], v[166:169], v[194:197], v[96:99]
	v_mfma_f32_16x16x32_bf16 v[88:91], v[174:177], v[194:197], v[88:91]
	v_mfma_f32_16x16x32_bf16 v[80:83], v[166:169], v[202:205], v[80:83]
	v_mfma_f32_16x16x32_bf16 v[72:75], v[174:177], v[202:205], v[72:75]
	v_mfma_f32_16x16x32_bf16 v[68:71], v[166:169], v[210:213], v[68:71]
	v_mfma_f32_16x16x32_bf16 v[64:67], v[174:177], v[210:213], v[64:67]
	s_setprio 0
	s_barrier
; #define PG8_STAGE(bufoff, gbase, voff) do { _Pragma("unroll") for (int _i = 0; _i < 2; ++_i) \
;         __builtin_amdgcn_global_load_lds((const unsigned*)((const char*)(gbase) + (voff)[_i]), (PG8_LAS unsigned*)(lds + (bufoff) + ldsw + _i * 8192), 16, 0, 0); } while (0)
; #define PG8_LDA(dst, b, h) do { _Pragma("unroll") for (int m = 0; m < 4; ++m) _Pragma("unroll") for (int k = 0; k < 2; ++k) dst[m][k] = *(const PG8_LAS bf16x8*)(lds + PG8_SA(b, h) + aoff + m * 2048 + k * 1024); } while (0)
; #define PG8_MMA(ai, bj, At, Bt) do { __builtin_amdgcn_s_setprio(1); _Pragma("unroll") for (int m = 0; m < 4; ++m) _Pragma("unroll") for (int n = 0; n < 2; ++n) _Pragma("unroll") for (int k = 0; k < 2; ++k) \
;         acc[ai][bj][m][n] = __builtin_amdgcn_mfma_f32_16x16x32_bf16(Bt[n][k], At[m][k], acc[ai][bj][m][n], 0, 0, 0); __builtin_amdgcn_s_setprio(0); } while (0)
; #define PG8_WAIT_V(n) asm volatile("s_waitcnt vmcnt(" #n ")" ::: "memory")
; #define PG8_WAIT_L(n) asm volatile("s_waitcnt lgkmcnt(" #n ")" ::: "memory")
; #define PG8_BAR __builtin_amdgcn_s_barrier()
; #define PG8_SCHED __builtin_amdgcn_sched_barrier(0)
; template <class Epi, class Sched, bool ALIGN_EPI = false, bool SP2 = false>
; __device__ __forceinline__ void gemm_phase(PG8_LAS unsigned char* lds, const Gemm g, const Sched& S, const Epi& E) {
;     ...
;         for (int t = 0; t < nt; t += 2) {
;             const bool last = (t == nt - 2);
;             const char* a1 = cA + (size_t)(t + 1) * kstep;
;             const char* a2 = last ? nA : cA + (size_t)(t + 2) * kstep; const char* b2 = last ? nB : cB + (size_t)(t + 2) * kstep;
;             const char* a3 = a2 + kstep; const char* b3 = b2 + kstep;
;     ...
;             PG8_LDA(At, 1, 1); PG8_STAGE(PG8_SB(1, 0), b3, voffB); PG8_STAGE(PG8_SB(1, 1), b3 + hstep, voffB); PG8_STAGE(PG8_SA(1, 0), a3, voffA);
;             PG8_WAIT_V(8); PG8_WAIT_L(0); PG8_BAR; PG8_MMA(1, 0, At, B0); PG8_MMA(1, 1, At, B1); PG8_BAR; PG8_SCHED;
	s_add_i32 s24, s49, s28
	v_lshl_add_u64 v[182:183], v[182:183], 0, s[6:7]
	s_mov_b32 m0, s24
	ds_read_b128 v[178:181], v149 offset:49152
	ds_read_b128 v[186:189], v149 offset:50176
	ds_read_b128 v[190:193], v149 offset:51200
	ds_read_b128 v[194:197], v149 offset:52224
	ds_read_b128 v[198:201], v149 offset:53248
	ds_read_b128 v[202:205], v149 offset:54272
	ds_read_b128 v[206:209], v149 offset:55296
	ds_read_b128 v[210:213], v149 offset:56320
	global_load_lds_dwordx4 v[182:183], off
	s_add_i32 m0, s24, 0x2000
	s_add_u32 s22, s22, 0x40080
	v_lshl_add_u64 v[182:183], v[214:215], 0, s[6:7]
	s_addc_u32 s23, s23, 0
	s_add_i32 s24, s50, s28
	global_load_lds_dwordx4 v[182:183], off
	v_lshl_add_u64 v[182:183], s[22:23], 0, v[130:131]
	s_mov_b32 m0, s24
	s_nop 0
	global_load_lds_dwordx4 v[182:183], off
	v_lshl_add_u64 v[182:183], s[22:23], 0, v[134:135]
	s_add_i32 m0, s24, 0x2000
	s_nop 0
	global_load_lds_dwordx4 v[182:183], off
	v_lshl_add_u64 v[182:183], v[216:217], 0, s[6:7]
	s_mov_b32 m0, s34
	s_nop 0
	global_load_lds_dwordx4 v[182:183], off
	v_lshl_add_u64 v[182:183], v[218:219], 0, s[6:7]
	s_mov_b32 m0, s35
	s_nop 0
	global_load_lds_dwordx4 v[182:183], off
	s_waitcnt vmcnt(8)
	s_waitcnt lgkmcnt(0)
	s_barrier
	s_setprio 1
	s_waitcnt lgkmcnt(0)
	v_mfma_f32_16x16x32_bf16 v[60:63], v[140:143], v[178:181], v[60:63]
	v_mfma_f32_16x16x32_bf16 v[56:59], v[154:157], v[178:181], v[56:59]
	v_mfma_f32_16x16x32_bf16 v[52:55], v[140:143], v[190:193], v[52:55]
	v_mfma_f32_16x16x32_bf16 v[44:47], v[154:157], v[190:193], v[44:47]
	v_mfma_f32_16x16x32_bf16 v[36:39], v[140:143], v[198:201], v[36:39]
	v_mfma_f32_16x16x32_bf16 v[28:31], v[154:157], v[198:201], v[28:31]
	v_mfma_f32_16x16x32_bf16 v[20:23], v[140:143], v[206:209], v[20:23]
	v_mfma_f32_16x16x32_bf16 v[12:15], v[154:157], v[206:209], v[12:15]
	v_mfma_f32_16x16x32_bf16 v[60:63], v[150:153], v[186:189], v[60:63]
	v_mfma_f32_16x16x32_bf16 v[56:59], v[158:161], v[186:189], v[56:59]
	v_mfma_f32_16x16x32_bf16 v[52:55], v[150:153], v[194:197], v[52:55]
	v_mfma_f32_16x16x32_bf16 v[44:47], v[158:161], v[194:197], v[44:47]
	v_mfma_f32_16x16x32_bf16 v[36:39], v[150:153], v[202:205], v[36:39]
	v_mfma_f32_16x16x32_bf16 v[28:31], v[158:161], v[202:205], v[28:31]
	v_mfma_f32_16x16x32_bf16 v[20:23], v[150:153], v[210:213], v[20:23]
	v_mfma_f32_16x16x32_bf16 v[12:15], v[158:161], v[210:213], v[12:15]
	s_setprio 0
	s_setprio 1
	v_mfma_f32_16x16x32_bf16 v[48:51], v[162:165], v[178:181], v[48:51]
	v_mfma_f32_16x16x32_bf16 v[40:43], v[170:173], v[178:181], v[40:43]
	v_mfma_f32_16x16x32_bf16 v[32:35], v[162:165], v[190:193], v[32:35]
	v_mfma_f32_16x16x32_bf16 v[24:27], v[170:173], v[190:193], v[24:27]
	v_mfma_f32_16x16x32_bf16 v[16:19], v[162:165], v[198:201], v[16:19]
	v_mfma_f32_16x16x32_bf16 v[8:11], v[170:173], v[198:201], v[8:11]
	v_mfma_f32_16x16x32_bf16 v[4:7], v[162:165], v[206:209], v[4:7]
	v_mfma_f32_16x16x32_bf16 v[0:3], v[170:173], v[206:209], v[0:3]
	v_mfma_f32_16x16x32_bf16 v[48:51], v[166:169], v[186:189], v[48:51]
	v_mfma_f32_16x16x32_bf16 v[40:43], v[174:177], v[186:189], v[40:43]
	v_mfma_f32_16x16x32_bf16 v[32:35], v[166:169], v[194:197], v[32:35]
	v_mfma_f32_16x16x32_bf16 v[24:27], v[174:177], v[194:197], v[24:27]
	v_mfma_f32_16x16x32_bf16 v[16:19], v[166:169], v[202:205], v[16:19]
	v_mfma_f32_16x16x32_bf16 v[8:11], v[174:177], v[202:205], v[8:11]
	v_mfma_f32_16x16x32_bf16 v[4:7], v[166:169], v[210:213], v[4:7]
	v_mfma_f32_16x16x32_bf16 v[0:3], v[174:177], v[210:213], v[0:3]
	s_setprio 0
	s_add_i32 s48, s48, 2
	s_add_u32 s46, s46, 0x100
	s_addc_u32 s47, s47, 0
	s_add_u32 s20, s20, 0x100
	s_addc_u32 s21, s21, 0
	s_cmp_gt_u32 s48, 13
	s_barrier
	s_cbranch_scc0 .LBB0_424
	s_and_b64 vcc, exec, s[8:9]
	s_cbranch_vccz .LBB0_427
	s_barrier

; #define PG8_STAGE(bufoff, gbase, voff) do { _Pragma("unroll") for (int _i = 0; _i < 2; ++_i) \
;         __builtin_amdgcn_global_load_lds((const unsigned*)((const char*)(gbase) + (voff)[_i]), (PG8_LAS unsigned*)(lds + (bufoff) + ldsw + _i * 8192), 16, 0, 0); } while (0)
; #define PG8_LDA(dst, b, h) do { _Pragma("unroll") for (int m = 0; m < 4; ++m) _Pragma("unroll") for (int k = 0; k < 2; ++k) dst[m][k] = *(const PG8_LAS bf16x8*)(lds + PG8_SA(b, h) + aoff + m * 2048 + k * 1024); } while (0)
; #define PG8_LDB(dst, b, h) do { _Pragma("unroll") for (int n = 0; n < 2; ++n) _Pragma("unroll") for (int k = 0; k < 2; ++k) dst[n][k] = *(const PG8_LAS bf16x8*)(lds + PG8_SB(b, h) + boff + n * 2048 + k * 1024); } while (0)
; #define PG8_MMA(ai, bj, At, Bt) do { __builtin_amdgcn_s_setprio(1); _Pragma("unroll") for (int m = 0; m < 4; ++m) _Pragma("unroll") for (int n = 0; n < 2; ++n) _Pragma("unroll") for (int k = 0; k < 2; ++k) \
;         acc[ai][bj][m][n] = __builtin_amdgcn_mfma_f32_16x16x32_bf16(Bt[n][k], At[m][k], acc[ai][bj][m][n], 0, 0, 0); __builtin_amdgcn_s_setprio(0); } while (0)
; #define PG8_WAIT_V(n) asm volatile("s_waitcnt vmcnt(" #n ")" ::: "memory")
; #define PG8_BAR __builtin_amdgcn_s_barrier()
; template <class Epi, class Sched, bool ALIGN_EPI = false, bool SP2 = false>
; __device__ __forceinline__ void gemm_phase(PG8_LAS unsigned char* lds, const Gemm g, const Sched& S, const Epi& E) {
;     ...
;         for (int t = 0; t < nt; t += 2) {
;             const bool last = (t == nt - 2);
;             const char* a1 = cA + (size_t)(t + 1) * kstep;
;             const char* a2 = last ? nA : cA + (size_t)(t + 2) * kstep; const char* b2 = last ? nB : cB + (size_t)(t + 2) * kstep;
;             const char* a3 = a2 + kstep; const char* b3 = b2 + kstep;
;             if (last && has_next) S.a_ready(nxt);
;             if constexpr (SP2) {
;             PG8_LDB(B0, 0, 0); PG8_LDB(B1, 0, 1); PG8_SCHED; PG8_LDA(At, 0, 0); PG8_STAGE(PG8_SA(1, 1), a1 + hstep, voffA);
;             PG8_WAIT_V(8); PG8_WAIT_L(0); PG8_BAR; PG8_MMA(0, 0, At, B0); PG8_MMA(0, 1, At, B1); PG8_BAR; PG8_SCHED;
;             PG8_LDA(At, 0, 1); PG8_STAGE(PG8_SB(0, 0), b2, voffB); PG8_STAGE(PG8_SB(0, 1), b2 + hstep, voffB); PG8_STAGE(PG8_SA(0, 0), a2, voffA);
;             PG8_WAIT_V(8); PG8_WAIT_L(0); PG8_BAR; PG8_MMA(1, 0, At, B0); PG8_MMA(1, 1, At, B1); PG8_BAR; PG8_SCHED;
.LBB0_515:
	ds_read_b128 v[144:147], v151
	ds_read_b128 v[154:157], v151 offset:1024
	ds_read_b128 v[158:161], v151 offset:2048
	ds_read_b128 v[162:165], v151 offset:3072
	ds_read_b128 v[166:169], v152
	ds_read_b128 v[170:173], v152 offset:1024
	ds_read_b128 v[174:177], v152 offset:2048
	ds_read_b128 v[178:181], v152 offset:3072
	s_add_u32 s16, s14, 0x100
	s_addc_u32 s17, s15, 0
	s_cmp_eq_u32 s48, 2
	s_cselect_b32 s21, s5, s17
	s_cselect_b32 s20, s4, s16
	s_cselect_b32 s19, s13, s47
	s_cselect_b32 s18, s12, s46
	v_lshl_add_u64 v[182:183], s[14:15], 0, v[138:139]
	s_add_i32 m0, s29, 0xc000
	ds_read_b128 v[186:189], v153
	ds_read_b128 v[190:193], v153 offset:1024
	ds_read_b128 v[194:197], v153 offset:2048
	ds_read_b128 v[198:201], v153 offset:3072
	ds_read_b128 v[202:205], v153 offset:4096
	ds_read_b128 v[206:209], v153 offset:5120
	ds_read_b128 v[210:213], v153 offset:6144
	ds_read_b128 v[214:217], v153 offset:7168
	global_load_lds_dwordx4 v[182:183], off
	v_lshl_add_u64 v[182:183], s[14:15], 0, v[136:137]
	s_add_i32 m0, s29, 0xe000
	s_nop 0
	global_load_lds_dwordx4 v[182:183], off
	s_waitcnt vmcnt(8)
	s_waitcnt lgkmcnt(0)
	s_barrier
	s_setprio 1
	s_waitcnt lgkmcnt(0)
	v_mfma_f32_16x16x32_bf16 v[124:127], v[144:147], v[186:189], v[124:127]
	v_mfma_f32_16x16x32_bf16 v[120:123], v[158:161], v[186:189], v[120:123]
	v_mfma_f32_16x16x32_bf16 v[116:119], v[144:147], v[194:197], v[116:119]
	v_mfma_f32_16x16x32_bf16 v[108:111], v[158:161], v[194:197], v[108:111]
	v_mfma_f32_16x16x32_bf16 v[100:103], v[144:147], v[202:205], v[100:103]
	v_mfma_f32_16x16x32_bf16 v[92:95], v[158:161], v[202:205], v[92:95]
	v_mfma_f32_16x16x32_bf16 v[84:87], v[144:147], v[210:213], v[84:87]
	v_mfma_f32_16x16x32_bf16 v[76:79], v[158:161], v[210:213], v[76:79]
	v_mfma_f32_16x16x32_bf16 v[124:127], v[154:157], v[190:193], v[124:127]
	v_mfma_f32_16x16x32_bf16 v[120:123], v[162:165], v[190:193], v[120:123]
	v_mfma_f32_16x16x32_bf16 v[116:119], v[154:157], v[198:201], v[116:119]
	v_mfma_f32_16x16x32_bf16 v[108:111], v[162:165], v[198:201], v[108:111]
	v_mfma_f32_16x16x32_bf16 v[100:103], v[154:157], v[206:209], v[100:103]
	v_mfma_f32_16x16x32_bf16 v[92:95], v[162:165], v[206:209], v[92:95]
	v_mfma_f32_16x16x32_bf16 v[84:87], v[154:157], v[214:217], v[84:87]
	v_mfma_f32_16x16x32_bf16 v[76:79], v[162:165], v[214:217], v[76:79]
	s_setprio 0
	s_setprio 1
	v_mfma_f32_16x16x32_bf16 v[112:115], v[166:169], v[186:189], v[112:115]
	v_mfma_f32_16x16x32_bf16 v[104:107], v[174:177], v[186:189], v[104:107]
	v_mfma_f32_16x16x32_bf16 v[96:99], v[166:169], v[194:197], v[96:99]
	v_mfma_f32_16x16x32_bf16 v[88:91], v[174:177], v[194:197], v[88:91]
	v_mfma_f32_16x16x32_bf16 v[80:83], v[166:169], v[202:205], v[80:83]
	v_mfma_f32_16x16x32_bf16 v[72:75], v[174:177], v[202:205], v[72:75]
	v_mfma_f32_16x16x32_bf16 v[68:71], v[166:169], v[210:213], v[68:71]
	v_mfma_f32_16x16x32_bf16 v[64:67], v[174:177], v[210:213], v[64:67]
	v_mfma_f32_16x16x32_bf16 v[112:115], v[170:173], v[190:193], v[112:115]
	v_mfma_f32_16x16x32_bf16 v[104:107], v[178:181], v[190:193], v[104:107]
	v_mfma_f32_16x16x32_bf16 v[96:99], v[170:173], v[198:201], v[96:99]
	v_mfma_f32_16x16x32_bf16 v[88:91], v[178:181], v[198:201], v[88:91]
	v_mfma_f32_16x16x32_bf16 v[80:83], v[170:173], v[206:209], v[80:83]
	v_mfma_f32_16x16x32_bf16 v[72:75], v[178:181], v[206:209], v[72:75]
	v_mfma_f32_16x16x32_bf16 v[68:71], v[170:173], v[214:217], v[68:71]
	v_mfma_f32_16x16x32_bf16 v[64:67], v[178:181], v[214:217], v[64:67]
	s_setprio 0
	s_barrier
	s_add_i32 s14, s39, s28
	v_lshl_add_u64 v[182:183], s[18:19], 0, v[130:131]
	s_mov_b32 m0, s14
	ds_read_b128 v[186:189], v153 offset:16384
	ds_read_b128 v[190:193], v153 offset:17408
	ds_read_b128 v[194:197], v153 offset:18432
	ds_read_b128 v[198:201], v153 offset:19456
	ds_read_b128 v[202:205], v153 offset:20480
	ds_read_b128 v[206:209], v153 offset:21504
	ds_read_b128 v[210:213], v153 offset:22528
	ds_read_b128 v[214:217], v153 offset:23552
	global_load_lds_dwordx4 v[182:183], off
	s_add_i32 m0, s14, 0x2000
	s_add_u32 s14, s18, 0x18000
	v_lshl_add_u64 v[218:219], s[18:19], 0, v[134:135]
	s_addc_u32 s15, s19, 0
	s_add_i32 s49, s40, s28
	global_load_lds_dwordx4 v[218:219], off
	v_lshl_add_u64 v[220:221], s[14:15], 0, v[130:131]
	s_mov_b32 m0, s49
	v_lshl_add_u64 v[222:223], s[20:21], 0, v[132:133]
	global_load_lds_dwordx4 v[220:221], off
	v_lshl_add_u64 v[220:221], s[14:15], 0, v[134:135]
	s_add_i32 m0, s49, 0x2000
	s_nop 0
	global_load_lds_dwordx4 v[220:221], off
	v_lshl_add_u64 v[220:221], s[20:21], 0, v[128:129]
	s_mov_b32 m0, s29
	s_nop 0
	global_load_lds_dwordx4 v[220:221], off
	s_mov_b32 m0, s30
	s_nop 0
	global_load_lds_dwordx4 v[222:223], off
	s_waitcnt vmcnt(8)
	s_waitcnt lgkmcnt(0)
	s_barrier
; #define PG8_STAGE(bufoff, gbase, voff) do { _Pragma("unroll") for (int _i = 0; _i < 2; ++_i) \
;         __builtin_amdgcn_global_load_lds((const unsigned*)((const char*)(gbase) + (voff)[_i]), (PG8_LAS unsigned*)(lds + (bufoff) + ldsw + _i * 8192), 16, 0, 0); } while (0)
; #define PG8_LDA(dst, b, h) do { _Pragma("unroll") for (int m = 0; m < 4; ++m) _Pragma("unroll") for (int k = 0; k < 2; ++k) dst[m][k] = *(const PG8_LAS bf16x8*)(lds + PG8_SA(b, h) + aoff + m * 2048 + k * 1024); } while (0)
; #define PG8_LDB(dst, b, h) do { _Pragma("unroll") for (int n = 0; n < 2; ++n) _Pragma("unroll") for (int k = 0; k < 2; ++k) dst[n][k] = *(const PG8_LAS bf16x8*)(lds + PG8_SB(b, h) + boff + n * 2048 + k * 1024); } while (0)
; #define PG8_MMA(ai, bj, At, Bt) do { __builtin_amdgcn_s_setprio(1); _Pragma("unroll") for (int m = 0; m < 4; ++m) _Pragma("unroll") for (int n = 0; n < 2; ++n) _Pragma("unroll") for (int k = 0; k < 2; ++k) \
;         acc[ai][bj][m][n] = __builtin_amdgcn_mfma_f32_16x16x32_bf16(Bt[n][k], At[m][k], acc[ai][bj][m][n], 0, 0, 0); __builtin_amdgcn_s_setprio(0); } while (0)
; #define PG8_WAIT_V(n) asm volatile("s_waitcnt vmcnt(" #n ")" ::: "memory")
; #define PG8_WAIT_L(n) asm volatile("s_waitcnt lgkmcnt(" #n ")" ::: "memory")
; #define PG8_BAR __builtin_amdgcn_s_barrier()
; #define PG8_SCHED __builtin_amdgcn_sched_barrier(0)
; template <class Epi, class Sched, bool ALIGN_EPI = false, bool SP2 = false>
; __device__ __forceinline__ void gemm_phase(PG8_LAS unsigned char* lds, const Gemm g, const Sched& S, const Epi& E) {
;     ...
;             PG8_WAIT_V(8); PG8_WAIT_L(0); PG8_BAR; PG8_MMA(1, 0, At, B0); PG8_MMA(1, 1, At, B1); PG8_BAR; PG8_SCHED;
;             PG8_LDB(B0, 1, 0); PG8_LDB(B1, 1, 1); PG8_SCHED; PG8_LDA(At, 1, 0); PG8_STAGE(PG8_SA(0, 1), a2 + hstep, voffA);
;             PG8_WAIT_V(8); PG8_WAIT_L(0); PG8_BAR; PG8_MMA(0, 0, At, B0); PG8_MMA(0, 1, At, B1); PG8_BAR; PG8_SCHED;
	s_setprio 1
	s_waitcnt lgkmcnt(0)
	v_mfma_f32_16x16x32_bf16 v[60:63], v[144:147], v[186:189], v[60:63]
	v_mfma_f32_16x16x32_bf16 v[56:59], v[158:161], v[186:189], v[56:59]
	v_mfma_f32_16x16x32_bf16 v[52:55], v[144:147], v[194:197], v[52:55]
	v_mfma_f32_16x16x32_bf16 v[44:47], v[158:161], v[194:197], v[44:47]
	v_mfma_f32_16x16x32_bf16 v[36:39], v[144:147], v[202:205], v[36:39]
	v_mfma_f32_16x16x32_bf16 v[28:31], v[158:161], v[202:205], v[28:31]
	v_mfma_f32_16x16x32_bf16 v[20:23], v[144:147], v[210:213], v[20:23]
	v_mfma_f32_16x16x32_bf16 v[12:15], v[158:161], v[210:213], v[12:15]
	v_mfma_f32_16x16x32_bf16 v[60:63], v[154:157], v[190:193], v[60:63]
	v_mfma_f32_16x16x32_bf16 v[56:59], v[162:165], v[190:193], v[56:59]
	v_mfma_f32_16x16x32_bf16 v[52:55], v[154:157], v[198:201], v[52:55]
	v_mfma_f32_16x16x32_bf16 v[44:47], v[162:165], v[198:201], v[44:47]
	v_mfma_f32_16x16x32_bf16 v[36:39], v[154:157], v[206:209], v[36:39]
	v_mfma_f32_16x16x32_bf16 v[28:31], v[162:165], v[206:209], v[28:31]
	v_mfma_f32_16x16x32_bf16 v[20:23], v[154:157], v[214:217], v[20:23]
	v_mfma_f32_16x16x32_bf16 v[12:15], v[162:165], v[214:217], v[12:15]
	s_setprio 0
	s_setprio 1
	v_mfma_f32_16x16x32_bf16 v[48:51], v[166:169], v[186:189], v[48:51]
	v_mfma_f32_16x16x32_bf16 v[40:43], v[174:177], v[186:189], v[40:43]
	v_mfma_f32_16x16x32_bf16 v[32:35], v[166:169], v[194:197], v[32:35]
	v_mfma_f32_16x16x32_bf16 v[24:27], v[174:177], v[194:197], v[24:27]
	v_mfma_f32_16x16x32_bf16 v[16:19], v[166:169], v[202:205], v[16:19]
	v_mfma_f32_16x16x32_bf16 v[8:11], v[174:177], v[202:205], v[8:11]
	v_mfma_f32_16x16x32_bf16 v[4:7], v[166:169], v[210:213], v[4:7]
	v_mfma_f32_16x16x32_bf16 v[0:3], v[174:177], v[210:213], v[0:3]
	v_mfma_f32_16x16x32_bf16 v[48:51], v[170:173], v[190:193], v[48:51]
	v_mfma_f32_16x16x32_bf16 v[40:43], v[178:181], v[190:193], v[40:43]
	v_mfma_f32_16x16x32_bf16 v[32:35], v[170:173], v[198:201], v[32:35]
	v_mfma_f32_16x16x32_bf16 v[24:27], v[178:181], v[198:201], v[24:27]
	v_mfma_f32_16x16x32_bf16 v[16:19], v[170:173], v[206:209], v[16:19]
	v_mfma_f32_16x16x32_bf16 v[8:11], v[178:181], v[206:209], v[8:11]
	v_mfma_f32_16x16x32_bf16 v[4:7], v[170:173], v[214:217], v[4:7]
	v_mfma_f32_16x16x32_bf16 v[0:3], v[178:181], v[214:217], v[0:3]
	s_setprio 0
	s_barrier
	s_add_i32 s49, 0, 0x18000
	s_add_i32 s50, 0, 0x1c000
	v_add_u32_e32 v162, s49, v149
	v_add_u32_e32 v178, s50, v149
	ds_read_b128 v[144:147], v162
	ds_read_b128 v[154:157], v162 offset:1024
	ds_read_b128 v[158:161], v162 offset:2048
	ds_read_b128 v[162:165], v162 offset:3072
	ds_read_b128 v[166:169], v178
	ds_read_b128 v[170:173], v178 offset:1024
	ds_read_b128 v[174:177], v178 offset:2048
	ds_read_b128 v[178:181], v178 offset:3072
	s_add_u32 s14, s20, 0x18000
	s_addc_u32 s15, s21, 0
	s_mov_b32 m0, s31
	v_lshl_add_u64 v[224:225], s[14:15], 0, v[128:129]
	ds_read_b128 v[186:189], v153 offset:32768
	ds_read_b128 v[190:193], v153 offset:33792
	ds_read_b128 v[194:197], v153 offset:34816
	ds_read_b128 v[198:201], v153 offset:35840
	ds_read_b128 v[202:205], v153 offset:36864
	ds_read_b128 v[206:209], v153 offset:37888
	ds_read_b128 v[210:213], v153 offset:38912
	ds_read_b128 v[214:217], v153 offset:39936
	global_load_lds_dwordx4 v[224:225], off
	v_lshl_add_u64 v[224:225], s[14:15], 0, v[132:133]
	s_mov_b32 m0, s33
	s_nop 0
	global_load_lds_dwordx4 v[224:225], off
	s_waitcnt vmcnt(8)
	s_waitcnt lgkmcnt(0)
	s_barrier
	s_setprio 1
	s_waitcnt lgkmcnt(0)
	v_mfma_f32_16x16x32_bf16 v[124:127], v[144:147], v[186:189], v[124:127]
	v_mfma_f32_16x16x32_bf16 v[120:123], v[158:161], v[186:189], v[120:123]
	v_mfma_f32_16x16x32_bf16 v[116:119], v[144:147], v[194:197], v[116:119]
	v_mfma_f32_16x16x32_bf16 v[108:111], v[158:161], v[194:197], v[108:111]
	v_mfma_f32_16x16x32_bf16 v[100:103], v[144:147], v[202:205], v[100:103]
	v_mfma_f32_16x16x32_bf16 v[92:95], v[158:161], v[202:205], v[92:95]
	v_mfma_f32_16x16x32_bf16 v[84:87], v[144:147], v[210:213], v[84:87]
	v_mfma_f32_16x16x32_bf16 v[76:79], v[158:161], v[210:213], v[76:79]
	v_mfma_f32_16x16x32_bf16 v[124:127], v[154:157], v[190:193], v[124:127]
	v_mfma_f32_16x16x32_bf16 v[120:123], v[162:165], v[190:193], v[120:123]
	v_mfma_f32_16x16x32_bf16 v[116:119], v[154:157], v[198:201], v[116:119]
	v_mfma_f32_16x16x32_bf16 v[108:111], v[162:165], v[198:201], v[108:111]
	v_mfma_f32_16x16x32_bf16 v[100:103], v[154:157], v[206:209], v[100:103]
	v_mfma_f32_16x16x32_bf16 v[92:95], v[162:165], v[206:209], v[92:95]
	v_mfma_f32_16x16x32_bf16 v[84:87], v[154:157], v[214:217], v[84:87]
	v_mfma_f32_16x16x32_bf16 v[76:79], v[162:165], v[214:217], v[76:79]
	s_setprio 0
	s_setprio 1
	v_mfma_f32_16x16x32_bf16 v[112:115], v[166:169], v[186:189], v[112:115]
	v_mfma_f32_16x16x32_bf16 v[104:107], v[174:177], v[186:189], v[104:107]
	v_mfma_f32_16x16x32_bf16 v[96:99], v[166:169], v[194:197], v[96:99]
	v_mfma_f32_16x16x32_bf16 v[88:91], v[174:177], v[194:197], v[88:91]
	v_mfma_f32_16x16x32_bf16 v[80:83], v[166:169], v[202:205], v[80:83]
	v_mfma_f32_16x16x32_bf16 v[72:75], v[174:177], v[202:205], v[72:75]
	v_mfma_f32_16x16x32_bf16 v[68:71], v[166:169], v[210:213], v[68:71]
	v_mfma_f32_16x16x32_bf16 v[64:67], v[174:177], v[210:213], v[64:67]
	v_mfma_f32_16x16x32_bf16 v[112:115], v[170:173], v[190:193], v[112:115]
	v_mfma_f32_16x16x32_bf16 v[104:107], v[178:181], v[190:193], v[104:107]
	v_mfma_f32_16x16x32_bf16 v[96:99], v[170:173], v[198:201], v[96:99]
	v_mfma_f32_16x16x32_bf16 v[88:91], v[178:181], v[198:201], v[88:91]
	v_mfma_f32_16x16x32_bf16 v[80:83], v[170:173], v[206:209], v[80:83]
	v_mfma_f32_16x16x32_bf16 v[72:75], v[178:181], v[206:209], v[72:75]
	v_mfma_f32_16x16x32_bf16 v[68:71], v[170:173], v[214:217], v[68:71]
	v_mfma_f32_16x16x32_bf16 v[64:67], v[178:181], v[214:217], v[64:67]
	s_setprio 0
	s_barrier
; #define PG8_STAGE(bufoff, gbase, voff) do { _Pragma("unroll") for (int _i = 0; _i < 2; ++_i) \
;         __builtin_amdgcn_global_load_lds((const unsigned*)((const char*)(gbase) + (voff)[_i]), (PG8_LAS unsigned*)(lds + (bufoff) + ldsw + _i * 8192), 16, 0, 0); } while (0)
; #define PG8_LDA(dst, b, h) do { _Pragma("unroll") for (int m = 0; m < 4; ++m) _Pragma("unroll") for (int k = 0; k < 2; ++k) dst[m][k] = *(const PG8_LAS bf16x8*)(lds + PG8_SA(b, h) + aoff + m * 2048 + k * 1024); } while (0)
; #define PG8_MMA(ai, bj, At, Bt) do { __builtin_amdgcn_s_setprio(1); _Pragma("unroll") for (int m = 0; m < 4; ++m) _Pragma("unroll") for (int n = 0; n < 2; ++n) _Pragma("unroll") for (int k = 0; k < 2; ++k) \
;         acc[ai][bj][m][n] = __builtin_amdgcn_mfma_f32_16x16x32_bf16(Bt[n][k], At[m][k], acc[ai][bj][m][n], 0, 0, 0); __builtin_amdgcn_s_setprio(0); } while (0)
; #define PG8_WAIT_V(n) asm volatile("s_waitcnt vmcnt(" #n ")" ::: "memory")
; #define PG8_WAIT_L(n) asm volatile("s_waitcnt lgkmcnt(" #n ")" ::: "memory")
; #define PG8_BAR __builtin_amdgcn_s_barrier()
; #define PG8_SCHED __builtin_amdgcn_sched_barrier(0)
; template <class Epi, class Sched, bool ALIGN_EPI = false, bool SP2 = false>
; __device__ __forceinline__ void gemm_phase(PG8_LAS unsigned char* lds, const Gemm g, const Sched& S, const Epi& E) {
;     ...
;         for (int t = 0; t < nt; t += 2) {
;             const bool last = (t == nt - 2);
;             const char* a1 = cA + (size_t)(t + 1) * kstep;
;             const char* a2 = last ? nA : cA + (size_t)(t + 2) * kstep; const char* b2 = last ? nB : cB + (size_t)(t + 2) * kstep;
;             const char* a3 = a2 + kstep; const char* b3 = b2 + kstep;
;     ...
;             PG8_LDA(At, 1, 1); PG8_STAGE(PG8_SB(1, 0), b3, voffB); PG8_STAGE(PG8_SB(1, 1), b3 + hstep, voffB); PG8_STAGE(PG8_SA(1, 0), a3, voffA);
;             PG8_WAIT_V(8); PG8_WAIT_L(0); PG8_BAR; PG8_MMA(1, 0, At, B0); PG8_MMA(1, 1, At, B1); PG8_BAR; PG8_SCHED;
	s_add_i32 s14, s49, s28
	v_lshl_add_u64 v[182:183], v[182:183], 0, s[8:9]
	s_mov_b32 m0, s14
	ds_read_b128 v[186:189], v153 offset:49152
	ds_read_b128 v[190:193], v153 offset:50176
	ds_read_b128 v[194:197], v153 offset:51200
	ds_read_b128 v[198:201], v153 offset:52224
	ds_read_b128 v[202:205], v153 offset:53248
	ds_read_b128 v[206:209], v153 offset:54272
	ds_read_b128 v[210:213], v153 offset:55296
	ds_read_b128 v[214:217], v153 offset:56320
	global_load_lds_dwordx4 v[182:183], off
	s_add_i32 m0, s14, 0x2000
	s_add_u32 s14, s18, 0x18080
	v_lshl_add_u64 v[182:183], v[218:219], 0, s[8:9]
	s_addc_u32 s15, s19, 0
	s_add_i32 s18, s50, s28
	global_load_lds_dwordx4 v[182:183], off
	v_lshl_add_u64 v[182:183], s[14:15], 0, v[130:131]
	s_mov_b32 m0, s18
	s_nop 0
	global_load_lds_dwordx4 v[182:183], off
	v_lshl_add_u64 v[182:183], s[14:15], 0, v[134:135]
	s_add_i32 m0, s18, 0x2000
	s_nop 0
	global_load_lds_dwordx4 v[182:183], off
	v_lshl_add_u64 v[182:183], v[220:221], 0, s[8:9]
	s_mov_b32 m0, s35
	s_nop 0
	global_load_lds_dwordx4 v[182:183], off
	v_lshl_add_u64 v[182:183], v[222:223], 0, s[8:9]
	s_mov_b32 m0, s36
	s_nop 0
	global_load_lds_dwordx4 v[182:183], off
	s_waitcnt vmcnt(8)
	s_waitcnt lgkmcnt(0)
	s_barrier
	s_setprio 1
	s_waitcnt lgkmcnt(0)
	v_mfma_f32_16x16x32_bf16 v[60:63], v[144:147], v[186:189], v[60:63]
	v_mfma_f32_16x16x32_bf16 v[56:59], v[158:161], v[186:189], v[56:59]
	v_mfma_f32_16x16x32_bf16 v[52:55], v[144:147], v[194:197], v[52:55]
	v_mfma_f32_16x16x32_bf16 v[44:47], v[158:161], v[194:197], v[44:47]
	v_mfma_f32_16x16x32_bf16 v[36:39], v[144:147], v[202:205], v[36:39]
	v_mfma_f32_16x16x32_bf16 v[28:31], v[158:161], v[202:205], v[28:31]
	v_mfma_f32_16x16x32_bf16 v[20:23], v[144:147], v[210:213], v[20:23]
	v_mfma_f32_16x16x32_bf16 v[12:15], v[158:161], v[210:213], v[12:15]
	v_mfma_f32_16x16x32_bf16 v[60:63], v[154:157], v[190:193], v[60:63]
	v_mfma_f32_16x16x32_bf16 v[56:59], v[162:165], v[190:193], v[56:59]
	v_mfma_f32_16x16x32_bf16 v[52:55], v[154:157], v[198:201], v[52:55]
	v_mfma_f32_16x16x32_bf16 v[44:47], v[162:165], v[198:201], v[44:47]
	v_mfma_f32_16x16x32_bf16 v[36:39], v[154:157], v[206:209], v[36:39]
	v_mfma_f32_16x16x32_bf16 v[28:31], v[162:165], v[206:209], v[28:31]
	v_mfma_f32_16x16x32_bf16 v[20:23], v[154:157], v[214:217], v[20:23]
	v_mfma_f32_16x16x32_bf16 v[12:15], v[162:165], v[214:217], v[12:15]
	s_setprio 0
	s_setprio 1
	v_mfma_f32_16x16x32_bf16 v[48:51], v[166:169], v[186:189], v[48:51]
	v_mfma_f32_16x16x32_bf16 v[40:43], v[174:177], v[186:189], v[40:43]
	v_mfma_f32_16x16x32_bf16 v[32:35], v[166:169], v[194:197], v[32:35]
	v_mfma_f32_16x16x32_bf16 v[24:27], v[174:177], v[194:197], v[24:27]
	v_mfma_f32_16x16x32_bf16 v[16:19], v[166:169], v[202:205], v[16:19]
	v_mfma_f32_16x16x32_bf16 v[8:11], v[174:177], v[202:205], v[8:11]
	v_mfma_f32_16x16x32_bf16 v[4:7], v[166:169], v[210:213], v[4:7]
	v_mfma_f32_16x16x32_bf16 v[0:3], v[174:177], v[210:213], v[0:3]
	v_mfma_f32_16x16x32_bf16 v[48:51], v[170:173], v[190:193], v[48:51]
	v_mfma_f32_16x16x32_bf16 v[40:43], v[178:181], v[190:193], v[40:43]
	v_mfma_f32_16x16x32_bf16 v[32:35], v[170:173], v[198:201], v[32:35]
	v_mfma_f32_16x16x32_bf16 v[24:27], v[178:181], v[198:201], v[24:27]
	v_mfma_f32_16x16x32_bf16 v[16:19], v[170:173], v[206:209], v[16:19]
	v_mfma_f32_16x16x32_bf16 v[8:11], v[178:181], v[206:209], v[8:11]
	v_mfma_f32_16x16x32_bf16 v[4:7], v[170:173], v[214:217], v[4:7]
	v_mfma_f32_16x16x32_bf16 v[0:3], v[178:181], v[214:217], v[0:3]
	s_setprio 0
	s_add_i32 s48, s48, 2
	s_add_u32 s46, s46, 0x100
	s_addc_u32 s47, s47, 0
	s_cmp_gt_u32 s48, 3
	s_mov_b64 s[14:15], s[16:17]
	s_barrier
	s_cbranch_scc0 .LBB0_515
	s_and_b64 vcc, exec, s[10:11]
	s_cbranch_vccz .LBB0_518
	s_barrier

; #define PG8_STAGE(bufoff, gbase, voff) do { _Pragma("unroll") for (int _i = 0; _i < 2; ++_i) \
;         __builtin_amdgcn_global_load_lds((const unsigned*)((const char*)(gbase) + (voff)[_i]), (PG8_LAS unsigned*)(lds + (bufoff) + ldsw + _i * 8192), 16, 0, 0); } while (0)
; #define PG8_LDA(dst, b, h) do { _Pragma("unroll") for (int m = 0; m < 4; ++m) _Pragma("unroll") for (int k = 0; k < 2; ++k) dst[m][k] = *(const PG8_LAS bf16x8*)(lds + PG8_SA(b, h) + aoff + m * 2048 + k * 1024); } while (0)
; #define PG8_LDB(dst, b, h) do { _Pragma("unroll") for (int n = 0; n < 2; ++n) _Pragma("unroll") for (int k = 0; k < 2; ++k) dst[n][k] = *(const PG8_LAS bf16x8*)(lds + PG8_SB(b, h) + boff + n * 2048 + k * 1024); } while (0)
; #define PG8_MMA(ai, bj, At, Bt) do { __builtin_amdgcn_s_setprio(1); _Pragma("unroll") for (int m = 0; m < 4; ++m) _Pragma("unroll") for (int n = 0; n < 2; ++n) _Pragma("unroll") for (int k = 0; k < 2; ++k) \
;         acc[ai][bj][m][n] = __builtin_amdgcn_mfma_f32_16x16x32_bf16(Bt[n][k], At[m][k], acc[ai][bj][m][n], 0, 0, 0); __builtin_amdgcn_s_setprio(0); } while (0)
; #define PG8_WAIT_V(n) asm volatile("s_waitcnt vmcnt(" #n ")" ::: "memory")
; #define PG8_BAR __builtin_amdgcn_s_barrier()
; template <class Epi, class Sched, bool ALIGN_EPI = false, bool SP2 = false>
; __device__ __forceinline__ void gemm_phase(PG8_LAS unsigned char* lds, const Gemm g, const Sched& S, const Epi& E) {
;     ...
;         for (int t = 0; t < nt; t += 2) {
;             const bool last = (t == nt - 2);
;             const char* a1 = cA + (size_t)(t + 1) * kstep;
;             const char* a2 = last ? nA : cA + (size_t)(t + 2) * kstep; const char* b2 = last ? nB : cB + (size_t)(t + 2) * kstep;
;             const char* a3 = a2 + kstep; const char* b3 = b2 + kstep;
;             if (last && has_next) S.a_ready(nxt);
;             if constexpr (SP2) {
;             PG8_LDB(B0, 0, 0); PG8_LDB(B1, 0, 1); PG8_SCHED; PG8_LDA(At, 0, 0); PG8_STAGE(PG8_SA(1, 1), a1 + hstep, voffA);
;             PG8_WAIT_V(8); PG8_WAIT_L(0); PG8_BAR; PG8_MMA(0, 0, At, B0); PG8_MMA(0, 1, At, B1); PG8_BAR; PG8_SCHED;
;             PG8_LDA(At, 0, 1); PG8_STAGE(PG8_SB(0, 0), b2, voffB); PG8_STAGE(PG8_SB(0, 1), b2 + hstep, voffB); PG8_STAGE(PG8_SA(0, 0), a2, voffA);
;             PG8_WAIT_V(8); PG8_WAIT_L(0); PG8_BAR; PG8_MMA(1, 0, At, B0); PG8_MMA(1, 1, At, B1); PG8_BAR; PG8_SCHED;
.LBB0_868:
	ds_read_b128 v[152:155], v149
	ds_read_b128 v[156:159], v149 offset:1024
	ds_read_b128 v[160:163], v149 offset:2048
	ds_read_b128 v[164:167], v149 offset:3072
	ds_read_b128 v[168:171], v150
	ds_read_b128 v[172:175], v150 offset:1024
	ds_read_b128 v[176:179], v150 offset:2048
	ds_read_b128 v[180:183], v150 offset:3072
	s_add_u32 s34, s30, 0xfffc0080
	s_addc_u32 s35, s31, -1
	s_cmp_eq_u32 s61, 12
	s_cselect_b32 s37, s23, s35
	s_cselect_b32 s36, s57, s34
	s_cselect_b32 s35, s21, s60
	s_cselect_b32 s34, s58, s59
	v_lshl_add_u64 v[144:145], s[30:31], 0, v[138:139]
	s_add_i32 m0, s29, 0xc000
	ds_read_b128 v[186:189], v151
	ds_read_b128 v[190:193], v151 offset:1024
	ds_read_b128 v[194:197], v151 offset:2048
	ds_read_b128 v[198:201], v151 offset:3072
	ds_read_b128 v[202:205], v151 offset:4096
	ds_read_b128 v[206:209], v151 offset:5120
	ds_read_b128 v[210:213], v151 offset:6144
	ds_read_b128 v[214:217], v151 offset:7168
	global_load_lds_dwordx4 v[144:145], off
	v_lshl_add_u64 v[144:145], s[30:31], 0, v[136:137]
	s_add_i32 m0, s29, 0xe000
	s_nop 0
	global_load_lds_dwordx4 v[144:145], off
	s_waitcnt vmcnt(8)
	s_waitcnt lgkmcnt(0)
	s_barrier
	s_setprio 1
	s_waitcnt lgkmcnt(0)
	v_mfma_f32_16x16x32_bf16 v[124:127], v[152:155], v[186:189], v[124:127]
	v_mfma_f32_16x16x32_bf16 v[120:123], v[160:163], v[186:189], v[120:123]
	v_mfma_f32_16x16x32_bf16 v[116:119], v[152:155], v[194:197], v[116:119]
	v_mfma_f32_16x16x32_bf16 v[108:111], v[160:163], v[194:197], v[108:111]
	v_mfma_f32_16x16x32_bf16 v[100:103], v[152:155], v[202:205], v[100:103]
	v_mfma_f32_16x16x32_bf16 v[92:95], v[160:163], v[202:205], v[92:95]
	v_mfma_f32_16x16x32_bf16 v[84:87], v[152:155], v[210:213], v[84:87]
	v_mfma_f32_16x16x32_bf16 v[76:79], v[160:163], v[210:213], v[76:79]
	v_mfma_f32_16x16x32_bf16 v[124:127], v[156:159], v[190:193], v[124:127]
	v_mfma_f32_16x16x32_bf16 v[120:123], v[164:167], v[190:193], v[120:123]
	v_mfma_f32_16x16x32_bf16 v[116:119], v[156:159], v[198:201], v[116:119]
	v_mfma_f32_16x16x32_bf16 v[108:111], v[164:167], v[198:201], v[108:111]
	v_mfma_f32_16x16x32_bf16 v[100:103], v[156:159], v[206:209], v[100:103]
	v_mfma_f32_16x16x32_bf16 v[92:95], v[164:167], v[206:209], v[92:95]
	v_mfma_f32_16x16x32_bf16 v[84:87], v[156:159], v[214:217], v[84:87]
	v_mfma_f32_16x16x32_bf16 v[76:79], v[164:167], v[214:217], v[76:79]
	s_setprio 0
	s_setprio 1
	v_mfma_f32_16x16x32_bf16 v[112:115], v[168:171], v[186:189], v[112:115]
	v_mfma_f32_16x16x32_bf16 v[104:107], v[176:179], v[186:189], v[104:107]
	v_mfma_f32_16x16x32_bf16 v[96:99], v[168:171], v[194:197], v[96:99]
	v_mfma_f32_16x16x32_bf16 v[88:91], v[176:179], v[194:197], v[88:91]
	v_mfma_f32_16x16x32_bf16 v[80:83], v[168:171], v[202:205], v[80:83]
	v_mfma_f32_16x16x32_bf16 v[72:75], v[176:179], v[202:205], v[72:75]
	v_mfma_f32_16x16x32_bf16 v[68:71], v[168:171], v[210:213], v[68:71]
	v_mfma_f32_16x16x32_bf16 v[64:67], v[176:179], v[210:213], v[64:67]
	v_mfma_f32_16x16x32_bf16 v[112:115], v[172:175], v[190:193], v[112:115]
	v_mfma_f32_16x16x32_bf16 v[104:107], v[180:183], v[190:193], v[104:107]
	v_mfma_f32_16x16x32_bf16 v[96:99], v[172:175], v[198:201], v[96:99]
	v_mfma_f32_16x16x32_bf16 v[88:91], v[180:183], v[198:201], v[88:91]
	v_mfma_f32_16x16x32_bf16 v[80:83], v[172:175], v[206:209], v[80:83]
	v_mfma_f32_16x16x32_bf16 v[72:75], v[180:183], v[206:209], v[72:75]
	v_mfma_f32_16x16x32_bf16 v[68:71], v[172:175], v[214:217], v[68:71]
	v_mfma_f32_16x16x32_bf16 v[64:67], v[180:183], v[214:217], v[64:67]
	s_setprio 0
	s_barrier
	s_add_i32 s62, s51, s42
	v_lshl_add_u64 v[144:145], s[34:35], 0, v[130:131]
	s_mov_b32 m0, s62
	ds_read_b128 v[186:189], v151 offset:16384
	ds_read_b128 v[190:193], v151 offset:17408
	ds_read_b128 v[194:197], v151 offset:18432
	ds_read_b128 v[198:201], v151 offset:19456
	ds_read_b128 v[202:205], v151 offset:20480
	ds_read_b128 v[206:209], v151 offset:21504
	ds_read_b128 v[210:213], v151 offset:22528
	ds_read_b128 v[214:217], v151 offset:23552
	global_load_lds_dwordx4 v[144:145], off
	s_add_i32 m0, s62, 0x2000
	s_add_u32 s62, s34, 0x40000
	v_lshl_add_u64 v[218:219], s[34:35], 0, v[134:135]
	s_addc_u32 s63, s35, 0
	s_add_i32 s64, s93, s42
	global_load_lds_dwordx4 v[218:219], off
	v_lshl_add_u64 v[220:221], s[62:63], 0, v[130:131]
	s_mov_b32 m0, s64
	v_lshl_add_u64 v[222:223], s[36:37], 0, v[132:133]
	global_load_lds_dwordx4 v[220:221], off
	v_lshl_add_u64 v[220:221], s[62:63], 0, v[134:135]
	s_add_i32 m0, s64, 0x2000
	s_nop 0
	global_load_lds_dwordx4 v[220:221], off
	v_lshl_add_u64 v[220:221], s[36:37], 0, v[128:129]
	s_mov_b32 m0, s29
	s_nop 0
	global_load_lds_dwordx4 v[220:221], off
	s_mov_b32 m0, s43
	s_nop 0
	global_load_lds_dwordx4 v[222:223], off
	s_waitcnt vmcnt(8)
	s_waitcnt lgkmcnt(0)
	s_barrier
; #define PG8_STAGE(bufoff, gbase, voff) do { _Pragma("unroll") for (int _i = 0; _i < 2; ++_i) \
;         __builtin_amdgcn_global_load_lds((const unsigned*)((const char*)(gbase) + (voff)[_i]), (PG8_LAS unsigned*)(lds + (bufoff) + ldsw + _i * 8192), 16, 0, 0); } while (0)
; #define PG8_LDA(dst, b, h) do { _Pragma("unroll") for (int m = 0; m < 4; ++m) _Pragma("unroll") for (int k = 0; k < 2; ++k) dst[m][k] = *(const PG8_LAS bf16x8*)(lds + PG8_SA(b, h) + aoff + m * 2048 + k * 1024); } while (0)
; #define PG8_LDB(dst, b, h) do { _Pragma("unroll") for (int n = 0; n < 2; ++n) _Pragma("unroll") for (int k = 0; k < 2; ++k) dst[n][k] = *(const PG8_LAS bf16x8*)(lds + PG8_SB(b, h) + boff + n * 2048 + k * 1024); } while (0)
; #define PG8_MMA(ai, bj, At, Bt) do { __builtin_amdgcn_s_setprio(1); _Pragma("unroll") for (int m = 0; m < 4; ++m) _Pragma("unroll") for (int n = 0; n < 2; ++n) _Pragma("unroll") for (int k = 0; k < 2; ++k) \
;         acc[ai][bj][m][n] = __builtin_amdgcn_mfma_f32_16x16x32_bf16(Bt[n][k], At[m][k], acc[ai][bj][m][n], 0, 0, 0); __builtin_amdgcn_s_setprio(0); } while (0)
; #define PG8_WAIT_V(n) asm volatile("s_waitcnt vmcnt(" #n ")" ::: "memory")
; #define PG8_WAIT_L(n) asm volatile("s_waitcnt lgkmcnt(" #n ")" ::: "memory")
; #define PG8_BAR __builtin_amdgcn_s_barrier()
; #define PG8_SCHED __builtin_amdgcn_sched_barrier(0)
; template <class Epi, class Sched, bool ALIGN_EPI = false, bool SP2 = false>
; __device__ __forceinline__ void gemm_phase(PG8_LAS unsigned char* lds, const Gemm g, const Sched& S, const Epi& E) {
;     ...
;             PG8_WAIT_V(8); PG8_WAIT_L(0); PG8_BAR; PG8_MMA(1, 0, At, B0); PG8_MMA(1, 1, At, B1); PG8_BAR; PG8_SCHED;
;             PG8_LDB(B0, 1, 0); PG8_LDB(B1, 1, 1); PG8_SCHED; PG8_LDA(At, 1, 0); PG8_STAGE(PG8_SA(0, 1), a2 + hstep, voffA);
;             PG8_WAIT_V(8); PG8_WAIT_L(0); PG8_BAR; PG8_MMA(0, 0, At, B0); PG8_MMA(0, 1, At, B1); PG8_BAR; PG8_SCHED;
	s_setprio 1
	s_waitcnt lgkmcnt(0)
	v_mfma_f32_16x16x32_bf16 v[60:63], v[152:155], v[186:189], v[60:63]
	v_mfma_f32_16x16x32_bf16 v[56:59], v[160:163], v[186:189], v[56:59]
	v_mfma_f32_16x16x32_bf16 v[52:55], v[152:155], v[194:197], v[52:55]
	v_mfma_f32_16x16x32_bf16 v[44:47], v[160:163], v[194:197], v[44:47]
	v_mfma_f32_16x16x32_bf16 v[36:39], v[152:155], v[202:205], v[36:39]
	v_mfma_f32_16x16x32_bf16 v[28:31], v[160:163], v[202:205], v[28:31]
	v_mfma_f32_16x16x32_bf16 v[20:23], v[152:155], v[210:213], v[20:23]
	v_mfma_f32_16x16x32_bf16 v[12:15], v[160:163], v[210:213], v[12:15]
	v_mfma_f32_16x16x32_bf16 v[60:63], v[156:159], v[190:193], v[60:63]
	v_mfma_f32_16x16x32_bf16 v[56:59], v[164:167], v[190:193], v[56:59]
	v_mfma_f32_16x16x32_bf16 v[52:55], v[156:159], v[198:201], v[52:55]
	v_mfma_f32_16x16x32_bf16 v[44:47], v[164:167], v[198:201], v[44:47]
	v_mfma_f32_16x16x32_bf16 v[36:39], v[156:159], v[206:209], v[36:39]
	v_mfma_f32_16x16x32_bf16 v[28:31], v[164:167], v[206:209], v[28:31]
	v_mfma_f32_16x16x32_bf16 v[20:23], v[156:159], v[214:217], v[20:23]
	v_mfma_f32_16x16x32_bf16 v[12:15], v[164:167], v[214:217], v[12:15]
	s_setprio 0
	s_setprio 1
	v_mfma_f32_16x16x32_bf16 v[48:51], v[168:171], v[186:189], v[48:51]
	v_mfma_f32_16x16x32_bf16 v[40:43], v[176:179], v[186:189], v[40:43]
	v_mfma_f32_16x16x32_bf16 v[32:35], v[168:171], v[194:197], v[32:35]
	v_mfma_f32_16x16x32_bf16 v[24:27], v[176:179], v[194:197], v[24:27]
	v_mfma_f32_16x16x32_bf16 v[16:19], v[168:171], v[202:205], v[16:19]
	v_mfma_f32_16x16x32_bf16 v[8:11], v[176:179], v[202:205], v[8:11]
	v_mfma_f32_16x16x32_bf16 v[4:7], v[168:171], v[210:213], v[4:7]
	v_mfma_f32_16x16x32_bf16 v[0:3], v[176:179], v[210:213], v[0:3]
	v_mfma_f32_16x16x32_bf16 v[48:51], v[172:175], v[190:193], v[48:51]
	v_mfma_f32_16x16x32_bf16 v[40:43], v[180:183], v[190:193], v[40:43]
	v_mfma_f32_16x16x32_bf16 v[32:35], v[172:175], v[198:201], v[32:35]
	v_mfma_f32_16x16x32_bf16 v[24:27], v[180:183], v[198:201], v[24:27]
	v_mfma_f32_16x16x32_bf16 v[16:19], v[172:175], v[206:209], v[16:19]
	v_mfma_f32_16x16x32_bf16 v[8:11], v[180:183], v[206:209], v[8:11]
	v_mfma_f32_16x16x32_bf16 v[4:7], v[172:175], v[214:217], v[4:7]
	v_mfma_f32_16x16x32_bf16 v[0:3], v[180:183], v[214:217], v[0:3]
	s_setprio 0
	s_barrier
	s_add_i32 s62, 0, 0x18000
	s_add_i32 s63, 0, 0x1c000
	v_add_u32_e32 v164, s62, v147
	v_add_u32_e32 v180, s63, v147
	ds_read_b128 v[152:155], v164
	ds_read_b128 v[156:159], v164 offset:1024
	ds_read_b128 v[160:163], v164 offset:2048
	ds_read_b128 v[164:167], v164 offset:3072
	ds_read_b128 v[168:171], v180
	ds_read_b128 v[172:175], v180 offset:1024
	ds_read_b128 v[176:179], v180 offset:2048
	ds_read_b128 v[180:183], v180 offset:3072
	s_add_u32 s36, s36, 0x40000
	s_addc_u32 s37, s37, 0
	s_mov_b32 m0, s44
	v_lshl_add_u64 v[224:225], s[36:37], 0, v[128:129]
	ds_read_b128 v[186:189], v151 offset:32768
	ds_read_b128 v[190:193], v151 offset:33792
	ds_read_b128 v[194:197], v151 offset:34816
	ds_read_b128 v[198:201], v151 offset:35840
	ds_read_b128 v[202:205], v151 offset:36864
	ds_read_b128 v[206:209], v151 offset:37888
	ds_read_b128 v[210:213], v151 offset:38912
	ds_read_b128 v[214:217], v151 offset:39936
	global_load_lds_dwordx4 v[224:225], off
	v_lshl_add_u64 v[224:225], s[36:37], 0, v[132:133]
	s_mov_b32 m0, s45
	s_nop 0
	global_load_lds_dwordx4 v[224:225], off
	s_waitcnt vmcnt(8)
	s_waitcnt lgkmcnt(0)
	s_barrier
	s_setprio 1
	s_waitcnt lgkmcnt(0)
	v_mfma_f32_16x16x32_bf16 v[124:127], v[152:155], v[186:189], v[124:127]
	v_mfma_f32_16x16x32_bf16 v[120:123], v[160:163], v[186:189], v[120:123]
	v_mfma_f32_16x16x32_bf16 v[116:119], v[152:155], v[194:197], v[116:119]
	v_mfma_f32_16x16x32_bf16 v[108:111], v[160:163], v[194:197], v[108:111]
	v_mfma_f32_16x16x32_bf16 v[100:103], v[152:155], v[202:205], v[100:103]
	v_mfma_f32_16x16x32_bf16 v[92:95], v[160:163], v[202:205], v[92:95]
	v_mfma_f32_16x16x32_bf16 v[84:87], v[152:155], v[210:213], v[84:87]
	v_mfma_f32_16x16x32_bf16 v[76:79], v[160:163], v[210:213], v[76:79]
	v_mfma_f32_16x16x32_bf16 v[124:127], v[156:159], v[190:193], v[124:127]
	v_mfma_f32_16x16x32_bf16 v[120:123], v[164:167], v[190:193], v[120:123]
	v_mfma_f32_16x16x32_bf16 v[116:119], v[156:159], v[198:201], v[116:119]
	v_mfma_f32_16x16x32_bf16 v[108:111], v[164:167], v[198:201], v[108:111]
	v_mfma_f32_16x16x32_bf16 v[100:103], v[156:159], v[206:209], v[100:103]
	v_mfma_f32_16x16x32_bf16 v[92:95], v[164:167], v[206:209], v[92:95]
	v_mfma_f32_16x16x32_bf16 v[84:87], v[156:159], v[214:217], v[84:87]
	v_mfma_f32_16x16x32_bf16 v[76:79], v[164:167], v[214:217], v[76:79]
	s_setprio 0
	s_setprio 1
	v_mfma_f32_16x16x32_bf16 v[112:115], v[168:171], v[186:189], v[112:115]
	v_mfma_f32_16x16x32_bf16 v[104:107], v[176:179], v[186:189], v[104:107]
	v_mfma_f32_16x16x32_bf16 v[96:99], v[168:171], v[194:197], v[96:99]
	v_mfma_f32_16x16x32_bf16 v[88:91], v[176:179], v[194:197], v[88:91]
	v_mfma_f32_16x16x32_bf16 v[80:83], v[168:171], v[202:205], v[80:83]
	v_mfma_f32_16x16x32_bf16 v[72:75], v[176:179], v[202:205], v[72:75]
	v_mfma_f32_16x16x32_bf16 v[68:71], v[168:171], v[210:213], v[68:71]
	v_mfma_f32_16x16x32_bf16 v[64:67], v[176:179], v[210:213], v[64:67]
	v_mfma_f32_16x16x32_bf16 v[112:115], v[172:175], v[190:193], v[112:115]
	v_mfma_f32_16x16x32_bf16 v[104:107], v[180:183], v[190:193], v[104:107]
	v_mfma_f32_16x16x32_bf16 v[96:99], v[172:175], v[198:201], v[96:99]
	v_mfma_f32_16x16x32_bf16 v[88:91], v[180:183], v[198:201], v[88:91]
	v_mfma_f32_16x16x32_bf16 v[80:83], v[172:175], v[206:209], v[80:83]
	v_mfma_f32_16x16x32_bf16 v[72:75], v[180:183], v[206:209], v[72:75]
	v_mfma_f32_16x16x32_bf16 v[68:71], v[172:175], v[214:217], v[68:71]
	v_mfma_f32_16x16x32_bf16 v[64:67], v[180:183], v[214:217], v[64:67]
	s_setprio 0
	s_barrier
; #define PG8_STAGE(bufoff, gbase, voff) do { _Pragma("unroll") for (int _i = 0; _i < 2; ++_i) \
;         __builtin_amdgcn_global_load_lds((const unsigned*)((const char*)(gbase) + (voff)[_i]), (PG8_LAS unsigned*)(lds + (bufoff) + ldsw + _i * 8192), 16, 0, 0); } while (0)
; #define PG8_LDA(dst, b, h) do { _Pragma("unroll") for (int m = 0; m < 4; ++m) _Pragma("unroll") for (int k = 0; k < 2; ++k) dst[m][k] = *(const PG8_LAS bf16x8*)(lds + PG8_SA(b, h) + aoff + m * 2048 + k * 1024); } while (0)
; #define PG8_MMA(ai, bj, At, Bt) do { __builtin_amdgcn_s_setprio(1); _Pragma("unroll") for (int m = 0; m < 4; ++m) _Pragma("unroll") for (int n = 0; n < 2; ++n) _Pragma("unroll") for (int k = 0; k < 2; ++k) \
;         acc[ai][bj][m][n] = __builtin_amdgcn_mfma_f32_16x16x32_bf16(Bt[n][k], At[m][k], acc[ai][bj][m][n], 0, 0, 0); __builtin_amdgcn_s_setprio(0); } while (0)
; #define PG8_WAIT_V(n) asm volatile("s_waitcnt vmcnt(" #n ")" ::: "memory")
; #define PG8_WAIT_L(n) asm volatile("s_waitcnt lgkmcnt(" #n ")" ::: "memory")
; #define PG8_BAR __builtin_amdgcn_s_barrier()
; #define PG8_SCHED __builtin_amdgcn_sched_barrier(0)
; template <class Epi, class Sched, bool ALIGN_EPI = false, bool SP2 = false>
; __device__ __forceinline__ void gemm_phase(PG8_LAS unsigned char* lds, const Gemm g, const Sched& S, const Epi& E) {
;     ...
;         for (int t = 0; t < nt; t += 2) {
;             const bool last = (t == nt - 2);
;             const char* a1 = cA + (size_t)(t + 1) * kstep;
;             const char* a2 = last ? nA : cA + (size_t)(t + 2) * kstep; const char* b2 = last ? nB : cB + (size_t)(t + 2) * kstep;
;             const char* a3 = a2 + kstep; const char* b3 = b2 + kstep;
;     ...
;             PG8_LDA(At, 1, 1); PG8_STAGE(PG8_SB(1, 0), b3, voffB); PG8_STAGE(PG8_SB(1, 1), b3 + hstep, voffB); PG8_STAGE(PG8_SA(1, 0), a3, voffA);
;             PG8_WAIT_V(8); PG8_WAIT_L(0); PG8_BAR; PG8_MMA(1, 0, At, B0); PG8_MMA(1, 1, At, B1); PG8_BAR; PG8_SCHED;
	s_add_i32 s36, s62, s42
	v_lshl_add_u64 v[144:145], v[144:145], 0, s[10:11]
	s_mov_b32 m0, s36
	ds_read_b128 v[186:189], v151 offset:49152
	ds_read_b128 v[190:193], v151 offset:50176
	ds_read_b128 v[194:197], v151 offset:51200
	ds_read_b128 v[198:201], v151 offset:52224
	ds_read_b128 v[202:205], v151 offset:53248
	ds_read_b128 v[206:209], v151 offset:54272
	ds_read_b128 v[210:213], v151 offset:55296
	ds_read_b128 v[214:217], v151 offset:56320
	global_load_lds_dwordx4 v[144:145], off
	s_add_i32 m0, s36, 0x2000
	s_add_u32 s34, s34, 0x40080
	v_lshl_add_u64 v[144:145], v[218:219], 0, s[10:11]
	s_addc_u32 s35, s35, 0
	s_add_i32 s36, s63, s42
	global_load_lds_dwordx4 v[144:145], off
	v_lshl_add_u64 v[144:145], s[34:35], 0, v[130:131]
	s_mov_b32 m0, s36
	s_nop 0
	global_load_lds_dwordx4 v[144:145], off
	v_lshl_add_u64 v[144:145], s[34:35], 0, v[134:135]
	s_add_i32 m0, s36, 0x2000
	s_nop 0
	global_load_lds_dwordx4 v[144:145], off
	v_lshl_add_u64 v[144:145], v[220:221], 0, s[10:11]
	s_mov_b32 m0, s47
	s_nop 0
	global_load_lds_dwordx4 v[144:145], off
	v_lshl_add_u64 v[144:145], v[222:223], 0, s[10:11]
	s_mov_b32 m0, s48
	s_nop 0
	global_load_lds_dwordx4 v[144:145], off
	s_waitcnt vmcnt(8)
	s_waitcnt lgkmcnt(0)
	s_barrier
	s_setprio 1
	s_waitcnt lgkmcnt(0)
	v_mfma_f32_16x16x32_bf16 v[60:63], v[152:155], v[186:189], v[60:63]
	v_mfma_f32_16x16x32_bf16 v[56:59], v[160:163], v[186:189], v[56:59]
	v_mfma_f32_16x16x32_bf16 v[52:55], v[152:155], v[194:197], v[52:55]
	v_mfma_f32_16x16x32_bf16 v[44:47], v[160:163], v[194:197], v[44:47]
	v_mfma_f32_16x16x32_bf16 v[36:39], v[152:155], v[202:205], v[36:39]
	v_mfma_f32_16x16x32_bf16 v[28:31], v[160:163], v[202:205], v[28:31]
	v_mfma_f32_16x16x32_bf16 v[20:23], v[152:155], v[210:213], v[20:23]
	v_mfma_f32_16x16x32_bf16 v[12:15], v[160:163], v[210:213], v[12:15]
	v_mfma_f32_16x16x32_bf16 v[60:63], v[156:159], v[190:193], v[60:63]
	v_mfma_f32_16x16x32_bf16 v[56:59], v[164:167], v[190:193], v[56:59]
	v_mfma_f32_16x16x32_bf16 v[52:55], v[156:159], v[198:201], v[52:55]
	v_mfma_f32_16x16x32_bf16 v[44:47], v[164:167], v[198:201], v[44:47]
	v_mfma_f32_16x16x32_bf16 v[36:39], v[156:159], v[206:209], v[36:39]
	v_mfma_f32_16x16x32_bf16 v[28:31], v[164:167], v[206:209], v[28:31]
	v_mfma_f32_16x16x32_bf16 v[20:23], v[156:159], v[214:217], v[20:23]
	v_mfma_f32_16x16x32_bf16 v[12:15], v[164:167], v[214:217], v[12:15]
	s_setprio 0
	s_setprio 1
	v_mfma_f32_16x16x32_bf16 v[48:51], v[168:171], v[186:189], v[48:51]
	v_mfma_f32_16x16x32_bf16 v[40:43], v[176:179], v[186:189], v[40:43]
	v_mfma_f32_16x16x32_bf16 v[32:35], v[168:171], v[194:197], v[32:35]
	v_mfma_f32_16x16x32_bf16 v[24:27], v[176:179], v[194:197], v[24:27]
	v_mfma_f32_16x16x32_bf16 v[16:19], v[168:171], v[202:205], v[16:19]
	v_mfma_f32_16x16x32_bf16 v[8:11], v[176:179], v[202:205], v[8:11]
	v_mfma_f32_16x16x32_bf16 v[4:7], v[168:171], v[210:213], v[4:7]
	v_mfma_f32_16x16x32_bf16 v[0:3], v[176:179], v[210:213], v[0:3]
	v_mfma_f32_16x16x32_bf16 v[48:51], v[172:175], v[190:193], v[48:51]
	v_mfma_f32_16x16x32_bf16 v[40:43], v[180:183], v[190:193], v[40:43]
	v_mfma_f32_16x16x32_bf16 v[32:35], v[172:175], v[198:201], v[32:35]
	v_mfma_f32_16x16x32_bf16 v[24:27], v[180:183], v[198:201], v[24:27]
	v_mfma_f32_16x16x32_bf16 v[16:19], v[172:175], v[206:209], v[16:19]
	v_mfma_f32_16x16x32_bf16 v[8:11], v[180:183], v[206:209], v[8:11]
	v_mfma_f32_16x16x32_bf16 v[4:7], v[172:175], v[214:217], v[4:7]
	v_mfma_f32_16x16x32_bf16 v[0:3], v[180:183], v[214:217], v[0:3]
	s_setprio 0
	s_add_i32 s61, s61, 2
	s_add_u32 s59, s59, 0x100
	s_addc_u32 s60, s60, 0
	s_add_u32 s30, s30, 0x100
	s_addc_u32 s31, s31, 0
	s_cmp_gt_u32 s61, 13
	s_barrier
	s_cbranch_scc0 .LBB0_868
	s_and_b64 vcc, exec, s[12:13]
	s_cbranch_vccz .LBB0_871
	s_barrier

; #define PG8_STAGE(bufoff, gbase, voff) do { _Pragma("unroll") for (int _i = 0; _i < 2; ++_i) \
;         __builtin_amdgcn_global_load_lds((const unsigned*)((const char*)(gbase) + (voff)[_i]), (PG8_LAS unsigned*)(lds + (bufoff) + ldsw + _i * 8192), 16, 0, 0); } while (0)
; #define PG8_LDA(dst, b, h) do { _Pragma("unroll") for (int m = 0; m < 4; ++m) _Pragma("unroll") for (int k = 0; k < 2; ++k) dst[m][k] = *(const PG8_LAS bf16x8*)(lds + PG8_SA(b, h) + aoff + m * 2048 + k * 1024); } while (0)
; #define PG8_LDB(dst, b, h) do { _Pragma("unroll") for (int n = 0; n < 2; ++n) _Pragma("unroll") for (int k = 0; k < 2; ++k) dst[n][k] = *(const PG8_LAS bf16x8*)(lds + PG8_SB(b, h) + boff + n * 2048 + k * 1024); } while (0)
; #define PG8_MMA(ai, bj, At, Bt) do { __builtin_amdgcn_s_setprio(1); _Pragma("unroll") for (int m = 0; m < 4; ++m) _Pragma("unroll") for (int n = 0; n < 2; ++n) _Pragma("unroll") for (int k = 0; k < 2; ++k) \
;         acc[ai][bj][m][n] = __builtin_amdgcn_mfma_f32_16x16x32_bf16(Bt[n][k], At[m][k], acc[ai][bj][m][n], 0, 0, 0); __builtin_amdgcn_s_setprio(0); } while (0)
; #define PG8_WAIT_V(n) asm volatile("s_waitcnt vmcnt(" #n ")" ::: "memory")
; #define PG8_BAR __builtin_amdgcn_s_barrier()
; template <class Epi, class Sched, bool ALIGN_EPI = false, bool SP2 = false>
; __device__ __forceinline__ void gemm_phase(PG8_LAS unsigned char* lds, const Gemm g, const Sched& S, const Epi& E) {
;     ...
;         for (int t = 0; t < nt; t += 2) {
;             const bool last = (t == nt - 2);
;             const char* a1 = cA + (size_t)(t + 1) * kstep;
;             const char* a2 = last ? nA : cA + (size_t)(t + 2) * kstep; const char* b2 = last ? nB : cB + (size_t)(t + 2) * kstep;
;             const char* a3 = a2 + kstep; const char* b3 = b2 + kstep;
;             if (last && has_next) S.a_ready(nxt);
;             if constexpr (SP2) {
;             PG8_LDB(B0, 0, 0); PG8_LDB(B1, 0, 1); PG8_SCHED; PG8_LDA(At, 0, 0); PG8_STAGE(PG8_SA(1, 1), a1 + hstep, voffA);
;             PG8_WAIT_V(8); PG8_WAIT_L(0); PG8_BAR; PG8_MMA(0, 0, At, B0); PG8_MMA(0, 1, At, B1); PG8_BAR; PG8_SCHED;
;             PG8_LDA(At, 0, 1); PG8_STAGE(PG8_SB(0, 0), b2, voffB); PG8_STAGE(PG8_SB(0, 1), b2 + hstep, voffB); PG8_STAGE(PG8_SA(0, 0), a2, voffA);
;             PG8_WAIT_V(8); PG8_WAIT_L(0); PG8_BAR; PG8_MMA(1, 0, At, B0); PG8_MMA(1, 1, At, B1); PG8_BAR; PG8_SCHED;
.LBB0_937:
	ds_read_b128 v[148:151], v145
	ds_read_b128 v[152:155], v145 offset:1024
	ds_read_b128 v[156:159], v145 offset:2048
	ds_read_b128 v[160:163], v145 offset:3072
	ds_read_b128 v[164:167], v146
	ds_read_b128 v[168:171], v146 offset:1024
	ds_read_b128 v[172:175], v146 offset:2048
	ds_read_b128 v[176:179], v146 offset:3072
	s_add_u32 s34, s30, 0xfffc0080
	s_addc_u32 s35, s31, -1
	s_cmp_eq_u32 s60, 12
	s_cselect_b32 s37, s23, s35
	s_cselect_b32 s36, s56, s34
	s_cselect_b32 s35, s21, s59
	s_cselect_b32 s34, s57, s58
	v_lshl_add_u64 v[140:141], s[30:31], 0, v[138:139]
	s_add_i32 m0, s40, 0xc000
	ds_read_b128 v[180:183], v147
	ds_read_b128 v[186:189], v147 offset:1024
	ds_read_b128 v[190:193], v147 offset:2048
	ds_read_b128 v[194:197], v147 offset:3072
	ds_read_b128 v[198:201], v147 offset:4096
	ds_read_b128 v[202:205], v147 offset:5120
	ds_read_b128 v[206:209], v147 offset:6144
	ds_read_b128 v[210:213], v147 offset:7168
	global_load_lds_dwordx4 v[140:141], off
	v_lshl_add_u64 v[140:141], s[30:31], 0, v[136:137]
	s_add_i32 m0, s40, 0xe000
	s_nop 0
	global_load_lds_dwordx4 v[140:141], off
	s_waitcnt vmcnt(8)
	s_waitcnt lgkmcnt(0)
	s_barrier
	s_setprio 1
	s_waitcnt lgkmcnt(0)
	v_mfma_f32_16x16x32_bf16 v[124:127], v[148:151], v[180:183], v[124:127]
	v_mfma_f32_16x16x32_bf16 v[120:123], v[156:159], v[180:183], v[120:123]
	v_mfma_f32_16x16x32_bf16 v[116:119], v[148:151], v[190:193], v[116:119]
	v_mfma_f32_16x16x32_bf16 v[108:111], v[156:159], v[190:193], v[108:111]
	v_mfma_f32_16x16x32_bf16 v[100:103], v[148:151], v[198:201], v[100:103]
	v_mfma_f32_16x16x32_bf16 v[92:95], v[156:159], v[198:201], v[92:95]
	v_mfma_f32_16x16x32_bf16 v[84:87], v[148:151], v[206:209], v[84:87]
	v_mfma_f32_16x16x32_bf16 v[76:79], v[156:159], v[206:209], v[76:79]
	v_mfma_f32_16x16x32_bf16 v[124:127], v[152:155], v[186:189], v[124:127]
	v_mfma_f32_16x16x32_bf16 v[120:123], v[160:163], v[186:189], v[120:123]
	v_mfma_f32_16x16x32_bf16 v[116:119], v[152:155], v[194:197], v[116:119]
	v_mfma_f32_16x16x32_bf16 v[108:111], v[160:163], v[194:197], v[108:111]
	v_mfma_f32_16x16x32_bf16 v[100:103], v[152:155], v[202:205], v[100:103]
	v_mfma_f32_16x16x32_bf16 v[92:95], v[160:163], v[202:205], v[92:95]
	v_mfma_f32_16x16x32_bf16 v[84:87], v[152:155], v[210:213], v[84:87]
	v_mfma_f32_16x16x32_bf16 v[76:79], v[160:163], v[210:213], v[76:79]
	s_setprio 0
	s_setprio 1
	v_mfma_f32_16x16x32_bf16 v[112:115], v[164:167], v[180:183], v[112:115]
	v_mfma_f32_16x16x32_bf16 v[104:107], v[172:175], v[180:183], v[104:107]
	v_mfma_f32_16x16x32_bf16 v[96:99], v[164:167], v[190:193], v[96:99]
	v_mfma_f32_16x16x32_bf16 v[88:91], v[172:175], v[190:193], v[88:91]
	v_mfma_f32_16x16x32_bf16 v[80:83], v[164:167], v[198:201], v[80:83]
	v_mfma_f32_16x16x32_bf16 v[72:75], v[172:175], v[198:201], v[72:75]
	v_mfma_f32_16x16x32_bf16 v[68:71], v[164:167], v[206:209], v[68:71]
	v_mfma_f32_16x16x32_bf16 v[64:67], v[172:175], v[206:209], v[64:67]
	v_mfma_f32_16x16x32_bf16 v[112:115], v[168:171], v[186:189], v[112:115]
	v_mfma_f32_16x16x32_bf16 v[104:107], v[176:179], v[186:189], v[104:107]
	v_mfma_f32_16x16x32_bf16 v[96:99], v[168:171], v[194:197], v[96:99]
	v_mfma_f32_16x16x32_bf16 v[88:91], v[176:179], v[194:197], v[88:91]
	v_mfma_f32_16x16x32_bf16 v[80:83], v[168:171], v[202:205], v[80:83]
	v_mfma_f32_16x16x32_bf16 v[72:75], v[176:179], v[202:205], v[72:75]
	v_mfma_f32_16x16x32_bf16 v[68:71], v[168:171], v[210:213], v[68:71]
	v_mfma_f32_16x16x32_bf16 v[64:67], v[176:179], v[210:213], v[64:67]
	s_setprio 0
	s_barrier
	s_add_i32 s61, s48, s39
	v_lshl_add_u64 v[140:141], s[34:35], 0, v[130:131]
	s_mov_b32 m0, s61
	ds_read_b128 v[180:183], v147 offset:16384
	ds_read_b128 v[186:189], v147 offset:17408
	ds_read_b128 v[190:193], v147 offset:18432
	ds_read_b128 v[194:197], v147 offset:19456
	ds_read_b128 v[198:201], v147 offset:20480
	ds_read_b128 v[202:205], v147 offset:21504
	ds_read_b128 v[206:209], v147 offset:22528
	ds_read_b128 v[210:213], v147 offset:23552
	global_load_lds_dwordx4 v[140:141], off
	s_add_i32 m0, s61, 0x2000
	s_add_u32 s62, s34, 0x40000
	v_lshl_add_u64 v[214:215], s[34:35], 0, v[134:135]
	s_addc_u32 s63, s35, 0
	s_add_i32 s61, s93, s39
	global_load_lds_dwordx4 v[214:215], off
	v_lshl_add_u64 v[216:217], s[62:63], 0, v[130:131]
	s_mov_b32 m0, s61
	v_lshl_add_u64 v[218:219], s[36:37], 0, v[132:133]
	global_load_lds_dwordx4 v[216:217], off
	v_lshl_add_u64 v[216:217], s[62:63], 0, v[134:135]
	s_add_i32 m0, s61, 0x2000
	s_nop 0
	global_load_lds_dwordx4 v[216:217], off
	v_lshl_add_u64 v[216:217], s[36:37], 0, v[128:129]
	s_mov_b32 m0, s40
	s_nop 0
	global_load_lds_dwordx4 v[216:217], off
	s_mov_b32 m0, s41
	s_nop 0
	global_load_lds_dwordx4 v[218:219], off
	s_waitcnt vmcnt(8)
	s_waitcnt lgkmcnt(0)
	s_barrier
; #define PG8_STAGE(bufoff, gbase, voff) do { _Pragma("unroll") for (int _i = 0; _i < 2; ++_i) \
;         __builtin_amdgcn_global_load_lds((const unsigned*)((const char*)(gbase) + (voff)[_i]), (PG8_LAS unsigned*)(lds + (bufoff) + ldsw + _i * 8192), 16, 0, 0); } while (0)
; #define PG8_LDA(dst, b, h) do { _Pragma("unroll") for (int m = 0; m < 4; ++m) _Pragma("unroll") for (int k = 0; k < 2; ++k) dst[m][k] = *(const PG8_LAS bf16x8*)(lds + PG8_SA(b, h) + aoff + m * 2048 + k * 1024); } while (0)
; #define PG8_LDB(dst, b, h) do { _Pragma("unroll") for (int n = 0; n < 2; ++n) _Pragma("unroll") for (int k = 0; k < 2; ++k) dst[n][k] = *(const PG8_LAS bf16x8*)(lds + PG8_SB(b, h) + boff + n * 2048 + k * 1024); } while (0)
; #define PG8_MMA(ai, bj, At, Bt) do { __builtin_amdgcn_s_setprio(1); _Pragma("unroll") for (int m = 0; m < 4; ++m) _Pragma("unroll") for (int n = 0; n < 2; ++n) _Pragma("unroll") for (int k = 0; k < 2; ++k) \
;         acc[ai][bj][m][n] = __builtin_amdgcn_mfma_f32_16x16x32_bf16(Bt[n][k], At[m][k], acc[ai][bj][m][n], 0, 0, 0); __builtin_amdgcn_s_setprio(0); } while (0)
; #define PG8_WAIT_V(n) asm volatile("s_waitcnt vmcnt(" #n ")" ::: "memory")
; #define PG8_WAIT_L(n) asm volatile("s_waitcnt lgkmcnt(" #n ")" ::: "memory")
; #define PG8_BAR __builtin_amdgcn_s_barrier()
; #define PG8_SCHED __builtin_amdgcn_sched_barrier(0)
; template <class Epi, class Sched, bool ALIGN_EPI = false, bool SP2 = false>
; __device__ __forceinline__ void gemm_phase(PG8_LAS unsigned char* lds, const Gemm g, const Sched& S, const Epi& E) {
;     ...
;             PG8_WAIT_V(8); PG8_WAIT_L(0); PG8_BAR; PG8_MMA(1, 0, At, B0); PG8_MMA(1, 1, At, B1); PG8_BAR; PG8_SCHED;
;             PG8_LDB(B0, 1, 0); PG8_LDB(B1, 1, 1); PG8_SCHED; PG8_LDA(At, 1, 0); PG8_STAGE(PG8_SA(0, 1), a2 + hstep, voffA);
;             PG8_WAIT_V(8); PG8_WAIT_L(0); PG8_BAR; PG8_MMA(0, 0, At, B0); PG8_MMA(0, 1, At, B1); PG8_BAR; PG8_SCHED;
	s_setprio 1
	s_waitcnt lgkmcnt(0)
	v_mfma_f32_16x16x32_bf16 v[60:63], v[148:151], v[180:183], v[60:63]
	v_mfma_f32_16x16x32_bf16 v[56:59], v[156:159], v[180:183], v[56:59]
	v_mfma_f32_16x16x32_bf16 v[52:55], v[148:151], v[190:193], v[52:55]
	v_mfma_f32_16x16x32_bf16 v[44:47], v[156:159], v[190:193], v[44:47]
	v_mfma_f32_16x16x32_bf16 v[36:39], v[148:151], v[198:201], v[36:39]
	v_mfma_f32_16x16x32_bf16 v[28:31], v[156:159], v[198:201], v[28:31]
	v_mfma_f32_16x16x32_bf16 v[20:23], v[148:151], v[206:209], v[20:23]
	v_mfma_f32_16x16x32_bf16 v[12:15], v[156:159], v[206:209], v[12:15]
	v_mfma_f32_16x16x32_bf16 v[60:63], v[152:155], v[186:189], v[60:63]
	v_mfma_f32_16x16x32_bf16 v[56:59], v[160:163], v[186:189], v[56:59]
	v_mfma_f32_16x16x32_bf16 v[52:55], v[152:155], v[194:197], v[52:55]
	v_mfma_f32_16x16x32_bf16 v[44:47], v[160:163], v[194:197], v[44:47]
	v_mfma_f32_16x16x32_bf16 v[36:39], v[152:155], v[202:205], v[36:39]
	v_mfma_f32_16x16x32_bf16 v[28:31], v[160:163], v[202:205], v[28:31]
	v_mfma_f32_16x16x32_bf16 v[20:23], v[152:155], v[210:213], v[20:23]
	v_mfma_f32_16x16x32_bf16 v[12:15], v[160:163], v[210:213], v[12:15]
	s_setprio 0
	s_setprio 1
	v_mfma_f32_16x16x32_bf16 v[48:51], v[164:167], v[180:183], v[48:51]
	v_mfma_f32_16x16x32_bf16 v[40:43], v[172:175], v[180:183], v[40:43]
	v_mfma_f32_16x16x32_bf16 v[32:35], v[164:167], v[190:193], v[32:35]
	v_mfma_f32_16x16x32_bf16 v[24:27], v[172:175], v[190:193], v[24:27]
	v_mfma_f32_16x16x32_bf16 v[16:19], v[164:167], v[198:201], v[16:19]
	v_mfma_f32_16x16x32_bf16 v[8:11], v[172:175], v[198:201], v[8:11]
	v_mfma_f32_16x16x32_bf16 v[4:7], v[164:167], v[206:209], v[4:7]
	v_mfma_f32_16x16x32_bf16 v[0:3], v[172:175], v[206:209], v[0:3]
	v_mfma_f32_16x16x32_bf16 v[48:51], v[168:171], v[186:189], v[48:51]
	v_mfma_f32_16x16x32_bf16 v[40:43], v[176:179], v[186:189], v[40:43]
	v_mfma_f32_16x16x32_bf16 v[32:35], v[168:171], v[194:197], v[32:35]
	v_mfma_f32_16x16x32_bf16 v[24:27], v[176:179], v[194:197], v[24:27]
	v_mfma_f32_16x16x32_bf16 v[16:19], v[168:171], v[202:205], v[16:19]
	v_mfma_f32_16x16x32_bf16 v[8:11], v[176:179], v[202:205], v[8:11]
	v_mfma_f32_16x16x32_bf16 v[4:7], v[168:171], v[210:213], v[4:7]
	v_mfma_f32_16x16x32_bf16 v[0:3], v[176:179], v[210:213], v[0:3]
	s_setprio 0
	s_barrier
	s_add_i32 s61, 0, 0x18000
	s_add_i32 s62, 0, 0x1c000
	v_add_u32_e32 v160, s61, v143
	v_add_u32_e32 v176, s62, v143
	ds_read_b128 v[148:151], v160
	ds_read_b128 v[152:155], v160 offset:1024
	ds_read_b128 v[156:159], v160 offset:2048
	ds_read_b128 v[160:163], v160 offset:3072
	ds_read_b128 v[164:167], v176
	ds_read_b128 v[168:171], v176 offset:1024
	ds_read_b128 v[172:175], v176 offset:2048
	ds_read_b128 v[176:179], v176 offset:3072
	s_add_u32 s36, s36, 0x40000
	s_addc_u32 s37, s37, 0
	s_mov_b32 m0, s42
	v_lshl_add_u64 v[220:221], s[36:37], 0, v[128:129]
	ds_read_b128 v[180:183], v147 offset:32768
	ds_read_b128 v[186:189], v147 offset:33792
	ds_read_b128 v[190:193], v147 offset:34816
	ds_read_b128 v[194:197], v147 offset:35840
	ds_read_b128 v[198:201], v147 offset:36864
	ds_read_b128 v[202:205], v147 offset:37888
	ds_read_b128 v[206:209], v147 offset:38912
	ds_read_b128 v[210:213], v147 offset:39936
	global_load_lds_dwordx4 v[220:221], off
	v_lshl_add_u64 v[220:221], s[36:37], 0, v[132:133]
	s_mov_b32 m0, s43
	s_nop 0
	global_load_lds_dwordx4 v[220:221], off
	s_waitcnt vmcnt(8)
	s_waitcnt lgkmcnt(0)
	s_barrier
	s_setprio 1
	s_waitcnt lgkmcnt(0)
	v_mfma_f32_16x16x32_bf16 v[124:127], v[148:151], v[180:183], v[124:127]
	v_mfma_f32_16x16x32_bf16 v[120:123], v[156:159], v[180:183], v[120:123]
	v_mfma_f32_16x16x32_bf16 v[116:119], v[148:151], v[190:193], v[116:119]
	v_mfma_f32_16x16x32_bf16 v[108:111], v[156:159], v[190:193], v[108:111]
	v_mfma_f32_16x16x32_bf16 v[100:103], v[148:151], v[198:201], v[100:103]
	v_mfma_f32_16x16x32_bf16 v[92:95], v[156:159], v[198:201], v[92:95]
	v_mfma_f32_16x16x32_bf16 v[84:87], v[148:151], v[206:209], v[84:87]
	v_mfma_f32_16x16x32_bf16 v[76:79], v[156:159], v[206:209], v[76:79]
	v_mfma_f32_16x16x32_bf16 v[124:127], v[152:155], v[186:189], v[124:127]
	v_mfma_f32_16x16x32_bf16 v[120:123], v[160:163], v[186:189], v[120:123]
	v_mfma_f32_16x16x32_bf16 v[116:119], v[152:155], v[194:197], v[116:119]
	v_mfma_f32_16x16x32_bf16 v[108:111], v[160:163], v[194:197], v[108:111]
	v_mfma_f32_16x16x32_bf16 v[100:103], v[152:155], v[202:205], v[100:103]
	v_mfma_f32_16x16x32_bf16 v[92:95], v[160:163], v[202:205], v[92:95]
	v_mfma_f32_16x16x32_bf16 v[84:87], v[152:155], v[210:213], v[84:87]
	v_mfma_f32_16x16x32_bf16 v[76:79], v[160:163], v[210:213], v[76:79]
	s_setprio 0
	s_setprio 1
	v_mfma_f32_16x16x32_bf16 v[112:115], v[164:167], v[180:183], v[112:115]
	v_mfma_f32_16x16x32_bf16 v[104:107], v[172:175], v[180:183], v[104:107]
	v_mfma_f32_16x16x32_bf16 v[96:99], v[164:167], v[190:193], v[96:99]
	v_mfma_f32_16x16x32_bf16 v[88:91], v[172:175], v[190:193], v[88:91]
	v_mfma_f32_16x16x32_bf16 v[80:83], v[164:167], v[198:201], v[80:83]
	v_mfma_f32_16x16x32_bf16 v[72:75], v[172:175], v[198:201], v[72:75]
	v_mfma_f32_16x16x32_bf16 v[68:71], v[164:167], v[206:209], v[68:71]
	v_mfma_f32_16x16x32_bf16 v[64:67], v[172:175], v[206:209], v[64:67]
	v_mfma_f32_16x16x32_bf16 v[112:115], v[168:171], v[186:189], v[112:115]
	v_mfma_f32_16x16x32_bf16 v[104:107], v[176:179], v[186:189], v[104:107]
	v_mfma_f32_16x16x32_bf16 v[96:99], v[168:171], v[194:197], v[96:99]
	v_mfma_f32_16x16x32_bf16 v[88:91], v[176:179], v[194:197], v[88:91]
	v_mfma_f32_16x16x32_bf16 v[80:83], v[168:171], v[202:205], v[80:83]
	v_mfma_f32_16x16x32_bf16 v[72:75], v[176:179], v[202:205], v[72:75]
	v_mfma_f32_16x16x32_bf16 v[68:71], v[168:171], v[210:213], v[68:71]
	v_mfma_f32_16x16x32_bf16 v[64:67], v[176:179], v[210:213], v[64:67]
	s_setprio 0
	s_barrier
; #define PG8_STAGE(bufoff, gbase, voff) do { _Pragma("unroll") for (int _i = 0; _i < 2; ++_i) \
;         __builtin_amdgcn_global_load_lds((const unsigned*)((const char*)(gbase) + (voff)[_i]), (PG8_LAS unsigned*)(lds + (bufoff) + ldsw + _i * 8192), 16, 0, 0); } while (0)
; #define PG8_LDA(dst, b, h) do { _Pragma("unroll") for (int m = 0; m < 4; ++m) _Pragma("unroll") for (int k = 0; k < 2; ++k) dst[m][k] = *(const PG8_LAS bf16x8*)(lds + PG8_SA(b, h) + aoff + m * 2048 + k * 1024); } while (0)
; #define PG8_MMA(ai, bj, At, Bt) do { __builtin_amdgcn_s_setprio(1); _Pragma("unroll") for (int m = 0; m < 4; ++m) _Pragma("unroll") for (int n = 0; n < 2; ++n) _Pragma("unroll") for (int k = 0; k < 2; ++k) \
;         acc[ai][bj][m][n] = __builtin_amdgcn_mfma_f32_16x16x32_bf16(Bt[n][k], At[m][k], acc[ai][bj][m][n], 0, 0, 0); __builtin_amdgcn_s_setprio(0); } while (0)
; #define PG8_WAIT_V(n) asm volatile("s_waitcnt vmcnt(" #n ")" ::: "memory")
; #define PG8_WAIT_L(n) asm volatile("s_waitcnt lgkmcnt(" #n ")" ::: "memory")
; #define PG8_BAR __builtin_amdgcn_s_barrier()
; #define PG8_SCHED __builtin_amdgcn_sched_barrier(0)
; template <class Epi, class Sched, bool ALIGN_EPI = false, bool SP2 = false>
; __device__ __forceinline__ void gemm_phase(PG8_LAS unsigned char* lds, const Gemm g, const Sched& S, const Epi& E) {
;     ...
;         for (int t = 0; t < nt; t += 2) {
;             const bool last = (t == nt - 2);
;             const char* a1 = cA + (size_t)(t + 1) * kstep;
;             const char* a2 = last ? nA : cA + (size_t)(t + 2) * kstep; const char* b2 = last ? nB : cB + (size_t)(t + 2) * kstep;
;             const char* a3 = a2 + kstep; const char* b3 = b2 + kstep;
;     ...
;             PG8_LDA(At, 1, 1); PG8_STAGE(PG8_SB(1, 0), b3, voffB); PG8_STAGE(PG8_SB(1, 1), b3 + hstep, voffB); PG8_STAGE(PG8_SA(1, 0), a3, voffA);
;             PG8_WAIT_V(8); PG8_WAIT_L(0); PG8_BAR; PG8_MMA(1, 0, At, B0); PG8_MMA(1, 1, At, B1); PG8_BAR; PG8_SCHED;
	s_add_i32 s36, s61, s39
	v_lshl_add_u64 v[140:141], v[140:141], 0, s[10:11]
	s_mov_b32 m0, s36
	ds_read_b128 v[180:183], v147 offset:49152
	ds_read_b128 v[186:189], v147 offset:50176
	ds_read_b128 v[190:193], v147 offset:51200
	ds_read_b128 v[194:197], v147 offset:52224
	ds_read_b128 v[198:201], v147 offset:53248
	ds_read_b128 v[202:205], v147 offset:54272
	ds_read_b128 v[206:209], v147 offset:55296
	ds_read_b128 v[210:213], v147 offset:56320
	global_load_lds_dwordx4 v[140:141], off
	s_add_i32 m0, s36, 0x2000
	s_add_u32 s34, s34, 0x40080
	v_lshl_add_u64 v[140:141], v[214:215], 0, s[10:11]
	s_addc_u32 s35, s35, 0
	s_add_i32 s36, s62, s39
	global_load_lds_dwordx4 v[140:141], off
	v_lshl_add_u64 v[140:141], s[34:35], 0, v[130:131]
	s_mov_b32 m0, s36
	s_nop 0
	global_load_lds_dwordx4 v[140:141], off
	v_lshl_add_u64 v[140:141], s[34:35], 0, v[134:135]
	s_add_i32 m0, s36, 0x2000
	s_nop 0
	global_load_lds_dwordx4 v[140:141], off
	v_lshl_add_u64 v[140:141], v[216:217], 0, s[10:11]
	s_mov_b32 m0, s44
	s_nop 0
	global_load_lds_dwordx4 v[140:141], off
	v_lshl_add_u64 v[140:141], v[218:219], 0, s[10:11]
	s_mov_b32 m0, s45
	s_nop 0
	global_load_lds_dwordx4 v[140:141], off
	s_waitcnt vmcnt(8)
	s_waitcnt lgkmcnt(0)
	s_barrier
	s_setprio 1
	s_waitcnt lgkmcnt(0)
	v_mfma_f32_16x16x32_bf16 v[60:63], v[148:151], v[180:183], v[60:63]
	v_mfma_f32_16x16x32_bf16 v[56:59], v[156:159], v[180:183], v[56:59]
	v_mfma_f32_16x16x32_bf16 v[52:55], v[148:151], v[190:193], v[52:55]
	v_mfma_f32_16x16x32_bf16 v[44:47], v[156:159], v[190:193], v[44:47]
	v_mfma_f32_16x16x32_bf16 v[36:39], v[148:151], v[198:201], v[36:39]
	v_mfma_f32_16x16x32_bf16 v[28:31], v[156:159], v[198:201], v[28:31]
	v_mfma_f32_16x16x32_bf16 v[20:23], v[148:151], v[206:209], v[20:23]
	v_mfma_f32_16x16x32_bf16 v[12:15], v[156:159], v[206:209], v[12:15]
	v_mfma_f32_16x16x32_bf16 v[60:63], v[152:155], v[186:189], v[60:63]
	v_mfma_f32_16x16x32_bf16 v[56:59], v[160:163], v[186:189], v[56:59]
	v_mfma_f32_16x16x32_bf16 v[52:55], v[152:155], v[194:197], v[52:55]
	v_mfma_f32_16x16x32_bf16 v[44:47], v[160:163], v[194:197], v[44:47]
	v_mfma_f32_16x16x32_bf16 v[36:39], v[152:155], v[202:205], v[36:39]
	v_mfma_f32_16x16x32_bf16 v[28:31], v[160:163], v[202:205], v[28:31]
	v_mfma_f32_16x16x32_bf16 v[20:23], v[152:155], v[210:213], v[20:23]
	v_mfma_f32_16x16x32_bf16 v[12:15], v[160:163], v[210:213], v[12:15]
	s_setprio 0
	s_setprio 1
	v_mfma_f32_16x16x32_bf16 v[48:51], v[164:167], v[180:183], v[48:51]
	v_mfma_f32_16x16x32_bf16 v[40:43], v[172:175], v[180:183], v[40:43]
	v_mfma_f32_16x16x32_bf16 v[32:35], v[164:167], v[190:193], v[32:35]
	v_mfma_f32_16x16x32_bf16 v[24:27], v[172:175], v[190:193], v[24:27]
	v_mfma_f32_16x16x32_bf16 v[16:19], v[164:167], v[198:201], v[16:19]
	v_mfma_f32_16x16x32_bf16 v[8:11], v[172:175], v[198:201], v[8:11]
	v_mfma_f32_16x16x32_bf16 v[4:7], v[164:167], v[206:209], v[4:7]
	v_mfma_f32_16x16x32_bf16 v[0:3], v[172:175], v[206:209], v[0:3]
	v_mfma_f32_16x16x32_bf16 v[48:51], v[168:171], v[186:189], v[48:51]
	v_mfma_f32_16x16x32_bf16 v[40:43], v[176:179], v[186:189], v[40:43]
	v_mfma_f32_16x16x32_bf16 v[32:35], v[168:171], v[194:197], v[32:35]
	v_mfma_f32_16x16x32_bf16 v[24:27], v[176:179], v[194:197], v[24:27]
	v_mfma_f32_16x16x32_bf16 v[16:19], v[168:171], v[202:205], v[16:19]
	v_mfma_f32_16x16x32_bf16 v[8:11], v[176:179], v[202:205], v[8:11]
	v_mfma_f32_16x16x32_bf16 v[4:7], v[168:171], v[210:213], v[4:7]
	v_mfma_f32_16x16x32_bf16 v[0:3], v[176:179], v[210:213], v[0:3]
	s_setprio 0
	s_add_i32 s60, s60, 2
	s_add_u32 s58, s58, 0x100
	s_addc_u32 s59, s59, 0
	s_add_u32 s30, s30, 0x100
	s_addc_u32 s31, s31, 0
	s_cmp_gt_u32 s60, 13
	s_barrier
	s_cbranch_scc0 .LBB0_937
	s_and_b64 vcc, exec, s[12:13]
	s_cbranch_vccz .LBB0_940
	s_barrier

; #define PG8_STAGE(bufoff, gbase, voff) do { _Pragma("unroll") for (int _i = 0; _i < 2; ++_i) \
;         __builtin_amdgcn_global_load_lds((const unsigned*)((const char*)(gbase) + (voff)[_i]), (PG8_LAS unsigned*)(lds + (bufoff) + ldsw + _i * 8192), 16, 0, 0); } while (0)
; #define PG8_LDA(dst, b, h) do { _Pragma("unroll") for (int m = 0; m < 4; ++m) _Pragma("unroll") for (int k = 0; k < 2; ++k) dst[m][k] = *(const PG8_LAS bf16x8*)(lds + PG8_SA(b, h) + aoff + m * 2048 + k * 1024); } while (0)
; #define PG8_LDB(dst, b, h) do { _Pragma("unroll") for (int n = 0; n < 2; ++n) _Pragma("unroll") for (int k = 0; k < 2; ++k) dst[n][k] = *(const PG8_LAS bf16x8*)(lds + PG8_SB(b, h) + boff + n * 2048 + k * 1024); } while (0)
; #define PG8_MMA(ai, bj, At, Bt) do { __builtin_amdgcn_s_setprio(1); _Pragma("unroll") for (int m = 0; m < 4; ++m) _Pragma("unroll") for (int n = 0; n < 2; ++n) _Pragma("unroll") for (int k = 0; k < 2; ++k) \
;         acc[ai][bj][m][n] = __builtin_amdgcn_mfma_f32_16x16x32_bf16(Bt[n][k], At[m][k], acc[ai][bj][m][n], 0, 0, 0); __builtin_amdgcn_s_setprio(0); } while (0)
; #define PG8_WAIT_V(n) asm volatile("s_waitcnt vmcnt(" #n ")" ::: "memory")
; #define PG8_WAIT_L(n) asm volatile("s_waitcnt lgkmcnt(" #n ")" ::: "memory")
; #define PG8_BAR __builtin_amdgcn_s_barrier()
; #define PG8_SCHED __builtin_amdgcn_sched_barrier(0)
; template <class Epi, class Sched, bool ALIGN_EPI = false, bool SP2 = false>
; __device__ __forceinline__ void gemm_phase(PG8_LAS unsigned char* lds, const Gemm g, const Sched& S, const Epi& E) {
;     ...
;         for (int t = 0; t < nt; t += 2) {
;             const bool last = (t == nt - 2);
;             const char* a1 = cA + (size_t)(t + 1) * kstep;
;             const char* a2 = last ? nA : cA + (size_t)(t + 2) * kstep; const char* b2 = last ? nB : cB + (size_t)(t + 2) * kstep;
;             const char* a3 = a2 + kstep; const char* b3 = b2 + kstep;
;             if (last && has_next) S.a_ready(nxt);
;             if constexpr (SP2) {
;             PG8_LDB(B0, 0, 0); PG8_LDB(B1, 0, 1); PG8_SCHED; PG8_LDA(At, 0, 0); PG8_STAGE(PG8_SA(1, 1), a1 + hstep, voffA);
;             PG8_WAIT_V(8); PG8_WAIT_L(0); PG8_BAR; PG8_MMA(0, 0, At, B0); PG8_MMA(0, 1, At, B1); PG8_BAR; PG8_SCHED;
;             PG8_LDA(At, 0, 1); PG8_STAGE(PG8_SB(0, 0), b2, voffB); PG8_STAGE(PG8_SB(0, 1), b2 + hstep, voffB); PG8_STAGE(PG8_SA(0, 0), a2, voffA);
.LBB0_1017:
	ds_read_b128 v[144:147], v151
	ds_read_b128 v[154:157], v151 offset:1024
	ds_read_b128 v[158:161], v151 offset:2048
	ds_read_b128 v[162:165], v151 offset:3072
	ds_read_b128 v[166:169], v152
	ds_read_b128 v[170:173], v152 offset:1024
	ds_read_b128 v[174:177], v152 offset:2048
	ds_read_b128 v[178:181], v152 offset:3072
	s_add_u32 s24, s22, 0xfffc0080
	s_addc_u32 s25, s23, -1
	s_cmp_eq_u32 s50, 12
	s_cselect_b32 s27, s15, s25
	s_cselect_b32 s26, s46, s24
	s_cselect_b32 s25, s13, s49
	s_cselect_b32 s24, s47, s48
	v_lshl_add_u64 v[182:183], s[22:23], 0, v[138:139]
	s_add_i32 m0, s21, 0xc000
	ds_read_b128 v[186:189], v153
	ds_read_b128 v[190:193], v153 offset:1024
	ds_read_b128 v[194:197], v153 offset:2048
	ds_read_b128 v[198:201], v153 offset:3072
	ds_read_b128 v[202:205], v153 offset:4096
	ds_read_b128 v[206:209], v153 offset:5120
	ds_read_b128 v[210:213], v153 offset:6144
	ds_read_b128 v[214:217], v153 offset:7168
	global_load_lds_dwordx4 v[182:183], off
	v_lshl_add_u64 v[182:183], s[22:23], 0, v[136:137]
	s_add_i32 m0, s21, 0xe000
	s_nop 0
	global_load_lds_dwordx4 v[182:183], off
	s_waitcnt vmcnt(8)
	s_waitcnt lgkmcnt(0)
	s_barrier
	s_setprio 1
	s_waitcnt lgkmcnt(0)
	v_mfma_f32_16x16x32_bf16 v[124:127], v[144:147], v[186:189], v[124:127]
	v_mfma_f32_16x16x32_bf16 v[116:119], v[158:161], v[186:189], v[116:119]
	v_mfma_f32_16x16x32_bf16 v[108:111], v[144:147], v[194:197], v[108:111]
	v_mfma_f32_16x16x32_bf16 v[100:103], v[158:161], v[194:197], v[100:103]
	v_mfma_f32_16x16x32_bf16 v[92:95], v[144:147], v[202:205], v[92:95]
	v_mfma_f32_16x16x32_bf16 v[84:87], v[158:161], v[202:205], v[84:87]
	v_mfma_f32_16x16x32_bf16 v[76:79], v[144:147], v[210:213], v[76:79]
	v_mfma_f32_16x16x32_bf16 v[68:71], v[158:161], v[210:213], v[68:71]
	v_mfma_f32_16x16x32_bf16 v[124:127], v[154:157], v[190:193], v[124:127]
	v_mfma_f32_16x16x32_bf16 v[116:119], v[162:165], v[190:193], v[116:119]
	v_mfma_f32_16x16x32_bf16 v[108:111], v[154:157], v[198:201], v[108:111]
	v_mfma_f32_16x16x32_bf16 v[100:103], v[162:165], v[198:201], v[100:103]
	v_mfma_f32_16x16x32_bf16 v[92:95], v[154:157], v[206:209], v[92:95]
	v_mfma_f32_16x16x32_bf16 v[84:87], v[162:165], v[206:209], v[84:87]
	v_mfma_f32_16x16x32_bf16 v[76:79], v[154:157], v[214:217], v[76:79]
	v_mfma_f32_16x16x32_bf16 v[68:71], v[162:165], v[214:217], v[68:71]
	s_setprio 0
	s_setprio 1
	v_mfma_f32_16x16x32_bf16 v[120:123], v[166:169], v[186:189], v[120:123]
	v_mfma_f32_16x16x32_bf16 v[112:115], v[174:177], v[186:189], v[112:115]
	v_mfma_f32_16x16x32_bf16 v[104:107], v[166:169], v[194:197], v[104:107]
	v_mfma_f32_16x16x32_bf16 v[96:99], v[174:177], v[194:197], v[96:99]
	v_mfma_f32_16x16x32_bf16 v[88:91], v[166:169], v[202:205], v[88:91]
	v_mfma_f32_16x16x32_bf16 v[80:83], v[174:177], v[202:205], v[80:83]
	v_mfma_f32_16x16x32_bf16 v[72:75], v[166:169], v[210:213], v[72:75]
	v_mfma_f32_16x16x32_bf16 v[64:67], v[174:177], v[210:213], v[64:67]
	v_mfma_f32_16x16x32_bf16 v[120:123], v[170:173], v[190:193], v[120:123]
	v_mfma_f32_16x16x32_bf16 v[112:115], v[178:181], v[190:193], v[112:115]
	v_mfma_f32_16x16x32_bf16 v[104:107], v[170:173], v[198:201], v[104:107]
	v_mfma_f32_16x16x32_bf16 v[96:99], v[178:181], v[198:201], v[96:99]
	v_mfma_f32_16x16x32_bf16 v[88:91], v[170:173], v[206:209], v[88:91]
	v_mfma_f32_16x16x32_bf16 v[80:83], v[178:181], v[206:209], v[80:83]
	v_mfma_f32_16x16x32_bf16 v[72:75], v[170:173], v[214:217], v[72:75]
	v_mfma_f32_16x16x32_bf16 v[64:67], v[178:181], v[214:217], v[64:67]
	s_setprio 0
	s_barrier
	s_add_i32 s51, s43, s34
	v_lshl_add_u64 v[182:183], s[24:25], 0, v[130:131]
	s_mov_b32 m0, s51
	ds_read_b128 v[186:189], v153 offset:16384
	ds_read_b128 v[190:193], v153 offset:17408
	ds_read_b128 v[194:197], v153 offset:18432
	ds_read_b128 v[198:201], v153 offset:19456
	ds_read_b128 v[202:205], v153 offset:20480
	ds_read_b128 v[206:209], v153 offset:21504
	ds_read_b128 v[210:213], v153 offset:22528
	ds_read_b128 v[214:217], v153 offset:23552
	global_load_lds_dwordx4 v[182:183], off
	s_add_i32 m0, s51, 0x2000
	s_add_u32 s52, s24, 0x40000
	v_lshl_add_u64 v[218:219], s[24:25], 0, v[134:135]
	s_addc_u32 s53, s25, 0
	s_add_i32 s51, s93, s34
	global_load_lds_dwordx4 v[218:219], off
	v_lshl_add_u64 v[220:221], s[52:53], 0, v[130:131]
	s_mov_b32 m0, s51
	v_lshl_add_u64 v[222:223], s[26:27], 0, v[132:133]
	global_load_lds_dwordx4 v[220:221], off
	v_lshl_add_u64 v[220:221], s[52:53], 0, v[134:135]
	s_add_i32 m0, s51, 0x2000
	s_nop 0
	global_load_lds_dwordx4 v[220:221], off
	v_lshl_add_u64 v[220:221], s[26:27], 0, v[128:129]
	s_mov_b32 m0, s21
	s_nop 0
	global_load_lds_dwordx4 v[220:221], off
	s_mov_b32 m0, s35
	s_nop 0
	global_load_lds_dwordx4 v[222:223], off
	s_waitcnt vmcnt(8)
	s_waitcnt lgkmcnt(0)
	s_barrier
; #define PG8_STAGE(bufoff, gbase, voff) do { _Pragma("unroll") for (int _i = 0; _i < 2; ++_i) \
;         __builtin_amdgcn_global_load_lds((const unsigned*)((const char*)(gbase) + (voff)[_i]), (PG8_LAS unsigned*)(lds + (bufoff) + ldsw + _i * 8192), 16, 0, 0); } while (0)
; #define PG8_LDA(dst, b, h) do { _Pragma("unroll") for (int m = 0; m < 4; ++m) _Pragma("unroll") for (int k = 0; k < 2; ++k) dst[m][k] = *(const PG8_LAS bf16x8*)(lds + PG8_SA(b, h) + aoff + m * 2048 + k * 1024); } while (0)
; #define PG8_LDB(dst, b, h) do { _Pragma("unroll") for (int n = 0; n < 2; ++n) _Pragma("unroll") for (int k = 0; k < 2; ++k) dst[n][k] = *(const PG8_LAS bf16x8*)(lds + PG8_SB(b, h) + boff + n * 2048 + k * 1024); } while (0)
; #define PG8_MMA(ai, bj, At, Bt) do { __builtin_amdgcn_s_setprio(1); _Pragma("unroll") for (int m = 0; m < 4; ++m) _Pragma("unroll") for (int n = 0; n < 2; ++n) _Pragma("unroll") for (int k = 0; k < 2; ++k) \
;         acc[ai][bj][m][n] = __builtin_amdgcn_mfma_f32_16x16x32_bf16(Bt[n][k], At[m][k], acc[ai][bj][m][n], 0, 0, 0); __builtin_amdgcn_s_setprio(0); } while (0)
; #define PG8_WAIT_V(n) asm volatile("s_waitcnt vmcnt(" #n ")" ::: "memory")
; #define PG8_WAIT_L(n) asm volatile("s_waitcnt lgkmcnt(" #n ")" ::: "memory")
; #define PG8_BAR __builtin_amdgcn_s_barrier()
; #define PG8_SCHED __builtin_amdgcn_sched_barrier(0)
; template <class Epi, class Sched, bool ALIGN_EPI = false, bool SP2 = false>
; __device__ __forceinline__ void gemm_phase(PG8_LAS unsigned char* lds, const Gemm g, const Sched& S, const Epi& E) {
;     ...
;             PG8_WAIT_V(8); PG8_WAIT_L(0); PG8_BAR; PG8_MMA(1, 0, At, B0); PG8_MMA(1, 1, At, B1); PG8_BAR; PG8_SCHED;
;             PG8_LDB(B0, 1, 0); PG8_LDB(B1, 1, 1); PG8_SCHED; PG8_LDA(At, 1, 0); PG8_STAGE(PG8_SA(0, 1), a2 + hstep, voffA);
;             PG8_WAIT_V(8); PG8_WAIT_L(0); PG8_BAR; PG8_MMA(0, 0, At, B0); PG8_MMA(0, 1, At, B1); PG8_BAR; PG8_SCHED;
	s_setprio 1
	s_waitcnt lgkmcnt(0)
	v_mfma_f32_16x16x32_bf16 v[60:63], v[144:147], v[186:189], v[60:63]
	v_mfma_f32_16x16x32_bf16 v[52:55], v[158:161], v[186:189], v[52:55]
	v_mfma_f32_16x16x32_bf16 v[44:47], v[144:147], v[194:197], v[44:47]
	v_mfma_f32_16x16x32_bf16 v[36:39], v[158:161], v[194:197], v[36:39]
	v_mfma_f32_16x16x32_bf16 v[28:31], v[144:147], v[202:205], v[28:31]
	v_mfma_f32_16x16x32_bf16 v[20:23], v[158:161], v[202:205], v[20:23]
	v_mfma_f32_16x16x32_bf16 v[12:15], v[144:147], v[210:213], v[12:15]
	v_mfma_f32_16x16x32_bf16 v[4:7], v[158:161], v[210:213], v[4:7]
	v_mfma_f32_16x16x32_bf16 v[60:63], v[154:157], v[190:193], v[60:63]
	v_mfma_f32_16x16x32_bf16 v[52:55], v[162:165], v[190:193], v[52:55]
	v_mfma_f32_16x16x32_bf16 v[44:47], v[154:157], v[198:201], v[44:47]
	v_mfma_f32_16x16x32_bf16 v[36:39], v[162:165], v[198:201], v[36:39]
	v_mfma_f32_16x16x32_bf16 v[28:31], v[154:157], v[206:209], v[28:31]
	v_mfma_f32_16x16x32_bf16 v[20:23], v[162:165], v[206:209], v[20:23]
	v_mfma_f32_16x16x32_bf16 v[12:15], v[154:157], v[214:217], v[12:15]
	v_mfma_f32_16x16x32_bf16 v[4:7], v[162:165], v[214:217], v[4:7]
	s_setprio 0
	s_setprio 1
	v_mfma_f32_16x16x32_bf16 v[56:59], v[166:169], v[186:189], v[56:59]
	v_mfma_f32_16x16x32_bf16 v[48:51], v[174:177], v[186:189], v[48:51]
	v_mfma_f32_16x16x32_bf16 v[40:43], v[166:169], v[194:197], v[40:43]
	v_mfma_f32_16x16x32_bf16 v[32:35], v[174:177], v[194:197], v[32:35]
	v_mfma_f32_16x16x32_bf16 v[24:27], v[166:169], v[202:205], v[24:27]
	v_mfma_f32_16x16x32_bf16 v[16:19], v[174:177], v[202:205], v[16:19]
	v_mfma_f32_16x16x32_bf16 v[8:11], v[166:169], v[210:213], v[8:11]
	v_mfma_f32_16x16x32_bf16 v[0:3], v[174:177], v[210:213], v[0:3]
	v_mfma_f32_16x16x32_bf16 v[56:59], v[170:173], v[190:193], v[56:59]
	v_mfma_f32_16x16x32_bf16 v[48:51], v[178:181], v[190:193], v[48:51]
	v_mfma_f32_16x16x32_bf16 v[40:43], v[170:173], v[198:201], v[40:43]
	v_mfma_f32_16x16x32_bf16 v[32:35], v[178:181], v[198:201], v[32:35]
	v_mfma_f32_16x16x32_bf16 v[24:27], v[170:173], v[206:209], v[24:27]
	v_mfma_f32_16x16x32_bf16 v[16:19], v[178:181], v[206:209], v[16:19]
	v_mfma_f32_16x16x32_bf16 v[8:11], v[170:173], v[214:217], v[8:11]
	v_mfma_f32_16x16x32_bf16 v[0:3], v[178:181], v[214:217], v[0:3]
	s_setprio 0
	s_barrier
	s_add_i32 s51, 0, 0x18000
	s_add_i32 s52, 0, 0x1c000
	v_add_u32_e32 v162, s51, v149
	v_add_u32_e32 v178, s52, v149
	ds_read_b128 v[144:147], v162
	ds_read_b128 v[154:157], v162 offset:1024
	ds_read_b128 v[158:161], v162 offset:2048
	ds_read_b128 v[162:165], v162 offset:3072
	ds_read_b128 v[166:169], v178
	ds_read_b128 v[170:173], v178 offset:1024
	ds_read_b128 v[174:177], v178 offset:2048
	ds_read_b128 v[178:181], v178 offset:3072
	s_add_u32 s26, s26, 0x40000
	s_addc_u32 s27, s27, 0
	s_mov_b32 m0, s36
	v_lshl_add_u64 v[224:225], s[26:27], 0, v[128:129]
	ds_read_b128 v[186:189], v153 offset:32768
	ds_read_b128 v[190:193], v153 offset:33792
	ds_read_b128 v[194:197], v153 offset:34816
	ds_read_b128 v[198:201], v153 offset:35840
	ds_read_b128 v[202:205], v153 offset:36864
	ds_read_b128 v[206:209], v153 offset:37888
	ds_read_b128 v[210:213], v153 offset:38912
	ds_read_b128 v[214:217], v153 offset:39936
	global_load_lds_dwordx4 v[224:225], off
	v_lshl_add_u64 v[224:225], s[26:27], 0, v[132:133]
	s_mov_b32 m0, s37
	s_nop 0
	global_load_lds_dwordx4 v[224:225], off
	s_waitcnt vmcnt(8)
	s_waitcnt lgkmcnt(0)
	s_barrier
	s_setprio 1
	s_waitcnt lgkmcnt(0)
	v_mfma_f32_16x16x32_bf16 v[124:127], v[144:147], v[186:189], v[124:127]
	v_mfma_f32_16x16x32_bf16 v[116:119], v[158:161], v[186:189], v[116:119]
	v_mfma_f32_16x16x32_bf16 v[108:111], v[144:147], v[194:197], v[108:111]
	v_mfma_f32_16x16x32_bf16 v[100:103], v[158:161], v[194:197], v[100:103]
	v_mfma_f32_16x16x32_bf16 v[92:95], v[144:147], v[202:205], v[92:95]
	v_mfma_f32_16x16x32_bf16 v[84:87], v[158:161], v[202:205], v[84:87]
	v_mfma_f32_16x16x32_bf16 v[76:79], v[144:147], v[210:213], v[76:79]
	v_mfma_f32_16x16x32_bf16 v[68:71], v[158:161], v[210:213], v[68:71]
	v_mfma_f32_16x16x32_bf16 v[124:127], v[154:157], v[190:193], v[124:127]
	v_mfma_f32_16x16x32_bf16 v[116:119], v[162:165], v[190:193], v[116:119]
	v_mfma_f32_16x16x32_bf16 v[108:111], v[154:157], v[198:201], v[108:111]
	v_mfma_f32_16x16x32_bf16 v[100:103], v[162:165], v[198:201], v[100:103]
	v_mfma_f32_16x16x32_bf16 v[92:95], v[154:157], v[206:209], v[92:95]
	v_mfma_f32_16x16x32_bf16 v[84:87], v[162:165], v[206:209], v[84:87]
	v_mfma_f32_16x16x32_bf16 v[76:79], v[154:157], v[214:217], v[76:79]
	v_mfma_f32_16x16x32_bf16 v[68:71], v[162:165], v[214:217], v[68:71]
	s_setprio 0
	s_setprio 1
	v_mfma_f32_16x16x32_bf16 v[120:123], v[166:169], v[186:189], v[120:123]
	v_mfma_f32_16x16x32_bf16 v[112:115], v[174:177], v[186:189], v[112:115]
	v_mfma_f32_16x16x32_bf16 v[104:107], v[166:169], v[194:197], v[104:107]
	v_mfma_f32_16x16x32_bf16 v[96:99], v[174:177], v[194:197], v[96:99]
	v_mfma_f32_16x16x32_bf16 v[88:91], v[166:169], v[202:205], v[88:91]
	v_mfma_f32_16x16x32_bf16 v[80:83], v[174:177], v[202:205], v[80:83]
	v_mfma_f32_16x16x32_bf16 v[72:75], v[166:169], v[210:213], v[72:75]
	v_mfma_f32_16x16x32_bf16 v[64:67], v[174:177], v[210:213], v[64:67]
	v_mfma_f32_16x16x32_bf16 v[120:123], v[170:173], v[190:193], v[120:123]
	v_mfma_f32_16x16x32_bf16 v[112:115], v[178:181], v[190:193], v[112:115]
	v_mfma_f32_16x16x32_bf16 v[104:107], v[170:173], v[198:201], v[104:107]
	v_mfma_f32_16x16x32_bf16 v[96:99], v[178:181], v[198:201], v[96:99]
	v_mfma_f32_16x16x32_bf16 v[88:91], v[170:173], v[206:209], v[88:91]
	v_mfma_f32_16x16x32_bf16 v[80:83], v[178:181], v[206:209], v[80:83]
	v_mfma_f32_16x16x32_bf16 v[72:75], v[170:173], v[214:217], v[72:75]
	v_mfma_f32_16x16x32_bf16 v[64:67], v[178:181], v[214:217], v[64:67]
	s_setprio 0
	s_barrier
; #define PG8_STAGE(bufoff, gbase, voff) do { _Pragma("unroll") for (int _i = 0; _i < 2; ++_i) \
;         __builtin_amdgcn_global_load_lds((const unsigned*)((const char*)(gbase) + (voff)[_i]), (PG8_LAS unsigned*)(lds + (bufoff) + ldsw + _i * 8192), 16, 0, 0); } while (0)
; #define PG8_LDA(dst, b, h) do { _Pragma("unroll") for (int m = 0; m < 4; ++m) _Pragma("unroll") for (int k = 0; k < 2; ++k) dst[m][k] = *(const PG8_LAS bf16x8*)(lds + PG8_SA(b, h) + aoff + m * 2048 + k * 1024); } while (0)
; #define PG8_MMA(ai, bj, At, Bt) do { __builtin_amdgcn_s_setprio(1); _Pragma("unroll") for (int m = 0; m < 4; ++m) _Pragma("unroll") for (int n = 0; n < 2; ++n) _Pragma("unroll") for (int k = 0; k < 2; ++k) \
;         acc[ai][bj][m][n] = __builtin_amdgcn_mfma_f32_16x16x32_bf16(Bt[n][k], At[m][k], acc[ai][bj][m][n], 0, 0, 0); __builtin_amdgcn_s_setprio(0); } while (0)
; #define PG8_WAIT_V(n) asm volatile("s_waitcnt vmcnt(" #n ")" ::: "memory")
; #define PG8_WAIT_L(n) asm volatile("s_waitcnt lgkmcnt(" #n ")" ::: "memory")
; #define PG8_BAR __builtin_amdgcn_s_barrier()
; #define PG8_SCHED __builtin_amdgcn_sched_barrier(0)
; template <class Epi, class Sched, bool ALIGN_EPI = false, bool SP2 = false>
; __device__ __forceinline__ void gemm_phase(PG8_LAS unsigned char* lds, const Gemm g, const Sched& S, const Epi& E) {
;     ...
;         for (int t = 0; t < nt; t += 2) {
;     ...
;             PG8_LDA(At, 1, 1); PG8_STAGE(PG8_SB(1, 0), b3, voffB); PG8_STAGE(PG8_SB(1, 1), b3 + hstep, voffB); PG8_STAGE(PG8_SA(1, 0), a3, voffA);
;             PG8_WAIT_V(8); PG8_WAIT_L(0); PG8_BAR; PG8_MMA(1, 0, At, B0); PG8_MMA(1, 1, At, B1); PG8_BAR; PG8_SCHED;
	s_add_i32 s26, s51, s34
	v_lshl_add_u64 v[182:183], v[182:183], 0, s[8:9]
	s_mov_b32 m0, s26
	ds_read_b128 v[186:189], v153 offset:49152
	ds_read_b128 v[190:193], v153 offset:50176
	ds_read_b128 v[194:197], v153 offset:51200
	ds_read_b128 v[198:201], v153 offset:52224
	ds_read_b128 v[202:205], v153 offset:53248
	ds_read_b128 v[206:209], v153 offset:54272
	ds_read_b128 v[210:213], v153 offset:55296
	ds_read_b128 v[214:217], v153 offset:56320
	global_load_lds_dwordx4 v[182:183], off
	s_add_i32 m0, s26, 0x2000
	s_add_u32 s24, s24, 0x40080
	v_lshl_add_u64 v[182:183], v[218:219], 0, s[8:9]
	s_addc_u32 s25, s25, 0
	s_add_i32 s26, s52, s34
	global_load_lds_dwordx4 v[182:183], off
	v_lshl_add_u64 v[182:183], s[24:25], 0, v[130:131]
	s_mov_b32 m0, s26
	s_nop 0
	global_load_lds_dwordx4 v[182:183], off
	v_lshl_add_u64 v[182:183], s[24:25], 0, v[134:135]
	s_add_i32 m0, s26, 0x2000
	s_nop 0
	global_load_lds_dwordx4 v[182:183], off
	v_lshl_add_u64 v[182:183], v[220:221], 0, s[8:9]
	s_mov_b32 m0, s39
	s_nop 0
	global_load_lds_dwordx4 v[182:183], off
	v_lshl_add_u64 v[182:183], v[222:223], 0, s[8:9]
	s_mov_b32 m0, s40
	s_nop 0
	global_load_lds_dwordx4 v[182:183], off
	s_waitcnt vmcnt(8)
	s_waitcnt lgkmcnt(0)
	s_barrier
	s_setprio 1
	s_waitcnt lgkmcnt(0)
	v_mfma_f32_16x16x32_bf16 v[60:63], v[144:147], v[186:189], v[60:63]
	v_mfma_f32_16x16x32_bf16 v[52:55], v[158:161], v[186:189], v[52:55]
	v_mfma_f32_16x16x32_bf16 v[44:47], v[144:147], v[194:197], v[44:47]
	v_mfma_f32_16x16x32_bf16 v[36:39], v[158:161], v[194:197], v[36:39]
	v_mfma_f32_16x16x32_bf16 v[28:31], v[144:147], v[202:205], v[28:31]
	v_mfma_f32_16x16x32_bf16 v[20:23], v[158:161], v[202:205], v[20:23]
	v_mfma_f32_16x16x32_bf16 v[12:15], v[144:147], v[210:213], v[12:15]
	v_mfma_f32_16x16x32_bf16 v[4:7], v[158:161], v[210:213], v[4:7]
	v_mfma_f32_16x16x32_bf16 v[60:63], v[154:157], v[190:193], v[60:63]
	v_mfma_f32_16x16x32_bf16 v[52:55], v[162:165], v[190:193], v[52:55]
	v_mfma_f32_16x16x32_bf16 v[44:47], v[154:157], v[198:201], v[44:47]
	v_mfma_f32_16x16x32_bf16 v[36:39], v[162:165], v[198:201], v[36:39]
	v_mfma_f32_16x16x32_bf16 v[28:31], v[154:157], v[206:209], v[28:31]
	v_mfma_f32_16x16x32_bf16 v[20:23], v[162:165], v[206:209], v[20:23]
	v_mfma_f32_16x16x32_bf16 v[12:15], v[154:157], v[214:217], v[12:15]
	v_mfma_f32_16x16x32_bf16 v[4:7], v[162:165], v[214:217], v[4:7]
	s_setprio 0
	s_setprio 1
	v_mfma_f32_16x16x32_bf16 v[56:59], v[166:169], v[186:189], v[56:59]
	v_mfma_f32_16x16x32_bf16 v[48:51], v[174:177], v[186:189], v[48:51]
	v_mfma_f32_16x16x32_bf16 v[40:43], v[166:169], v[194:197], v[40:43]
	v_mfma_f32_16x16x32_bf16 v[32:35], v[174:177], v[194:197], v[32:35]
	v_mfma_f32_16x16x32_bf16 v[24:27], v[166:169], v[202:205], v[24:27]
	v_mfma_f32_16x16x32_bf16 v[16:19], v[174:177], v[202:205], v[16:19]
	v_mfma_f32_16x16x32_bf16 v[8:11], v[166:169], v[210:213], v[8:11]
	v_mfma_f32_16x16x32_bf16 v[0:3], v[174:177], v[210:213], v[0:3]
	v_mfma_f32_16x16x32_bf16 v[56:59], v[170:173], v[190:193], v[56:59]
	v_mfma_f32_16x16x32_bf16 v[48:51], v[178:181], v[190:193], v[48:51]
	v_mfma_f32_16x16x32_bf16 v[40:43], v[170:173], v[198:201], v[40:43]
	v_mfma_f32_16x16x32_bf16 v[32:35], v[178:181], v[198:201], v[32:35]
	v_mfma_f32_16x16x32_bf16 v[24:27], v[170:173], v[206:209], v[24:27]
	v_mfma_f32_16x16x32_bf16 v[16:19], v[178:181], v[206:209], v[16:19]
	v_mfma_f32_16x16x32_bf16 v[8:11], v[170:173], v[214:217], v[8:11]
	v_mfma_f32_16x16x32_bf16 v[0:3], v[178:181], v[214:217], v[0:3]
	s_setprio 0
	s_add_i32 s50, s50, 2
	s_add_u32 s48, s48, 0x100
	s_addc_u32 s49, s49, 0
	s_add_u32 s22, s22, 0x100
	s_addc_u32 s23, s23, 0
	s_cmp_gt_u32 s50, 13
	s_barrier
	s_cbranch_scc0 .LBB0_1017
	s_and_b64 vcc, exec, s[10:11]
	s_cbranch_vccz .LBB0_1020
	s_barrier

; #define PG8_STAGE(bufoff, gbase, voff) do { _Pragma("unroll") for (int _i = 0; _i < 2; ++_i) \
;         __builtin_amdgcn_global_load_lds((const unsigned*)((const char*)(gbase) + (voff)[_i]), (PG8_LAS unsigned*)(lds + (bufoff) + ldsw + _i * 8192), 16, 0, 0); } while (0)
; #define PG8_LDA(dst, b, h) do { _Pragma("unroll") for (int m = 0; m < 4; ++m) _Pragma("unroll") for (int k = 0; k < 2; ++k) dst[m][k] = *(const PG8_LAS bf16x8*)(lds + PG8_SA(b, h) + aoff + m * 2048 + k * 1024); } while (0)
; #define PG8_LDB(dst, b, h) do { _Pragma("unroll") for (int n = 0; n < 2; ++n) _Pragma("unroll") for (int k = 0; k < 2; ++k) dst[n][k] = *(const PG8_LAS bf16x8*)(lds + PG8_SB(b, h) + boff + n * 2048 + k * 1024); } while (0)
; #define PG8_MMA(ai, bj, At, Bt) do { __builtin_amdgcn_s_setprio(1); _Pragma("unroll") for (int m = 0; m < 4; ++m) _Pragma("unroll") for (int n = 0; n < 2; ++n) _Pragma("unroll") for (int k = 0; k < 2; ++k) \
;         acc[ai][bj][m][n] = __builtin_amdgcn_mfma_f32_16x16x32_bf16(Bt[n][k], At[m][k], acc[ai][bj][m][n], 0, 0, 0); __builtin_amdgcn_s_setprio(0); } while (0)
; #define PG8_WAIT_V(n) asm volatile("s_waitcnt vmcnt(" #n ")" ::: "memory")
; #define PG8_WAIT_L(n) asm volatile("s_waitcnt lgkmcnt(" #n ")" ::: "memory")
; #define PG8_BAR __builtin_amdgcn_s_barrier()
; #define PG8_SCHED __builtin_amdgcn_sched_barrier(0)
; template <class Epi, class Sched, bool ALIGN_EPI = false, bool SP2 = false>
; __device__ __forceinline__ void gemm_phase(PG8_LAS unsigned char* lds, const Gemm g, const Sched& S, const Epi& E) {
;     ...
;         for (int t = 0; t < nt; t += 2) {
;             const bool last = (t == nt - 2);
;             const char* a1 = cA + (size_t)(t + 1) * kstep;
;             const char* a2 = last ? nA : cA + (size_t)(t + 2) * kstep; const char* b2 = last ? nB : cB + (size_t)(t + 2) * kstep;
;             const char* a3 = a2 + kstep; const char* b3 = b2 + kstep;
;             if (last && has_next) S.a_ready(nxt);
;             if constexpr (SP2) {
;             PG8_LDB(B0, 0, 0); PG8_LDB(B1, 0, 1); PG8_SCHED; PG8_LDA(At, 0, 0); PG8_STAGE(PG8_SA(1, 1), a1 + hstep, voffA);
;             PG8_WAIT_V(8); PG8_WAIT_L(0); PG8_BAR; PG8_MMA(0, 0, At, B0); PG8_MMA(0, 1, At, B1); PG8_BAR; PG8_SCHED;
;             PG8_LDA(At, 0, 1); PG8_STAGE(PG8_SB(0, 0), b2, voffB); PG8_STAGE(PG8_SB(0, 1), b2 + hstep, voffB); PG8_STAGE(PG8_SA(0, 0), a2, voffA);
.LBB0_1089:
	ds_read_b128 v[152:155], v149
	ds_read_b128 v[156:159], v149 offset:1024
	ds_read_b128 v[160:163], v149 offset:2048
	ds_read_b128 v[164:167], v149 offset:3072
	ds_read_b128 v[168:171], v150
	ds_read_b128 v[172:175], v150 offset:1024
	ds_read_b128 v[176:179], v150 offset:2048
	ds_read_b128 v[180:183], v150 offset:3072
	s_add_u32 s24, s22, 0x100
	s_addc_u32 s25, s23, 0
	s_cmp_eq_u32 s57, 40
	s_cselect_b32 s29, s5, s25
	s_cselect_b32 s28, s4, s24
	s_cselect_b32 s27, s21, s56
	s_cselect_b32 s26, s20, s55
	v_lshl_add_u64 v[144:145], s[22:23], 0, v[138:139]
	s_add_i32 m0, s37, 0xc000
	ds_read_b128 v[186:189], v151
	ds_read_b128 v[190:193], v151 offset:1024
	ds_read_b128 v[194:197], v151 offset:2048
	ds_read_b128 v[198:201], v151 offset:3072
	ds_read_b128 v[202:205], v151 offset:4096
	ds_read_b128 v[206:209], v151 offset:5120
	ds_read_b128 v[210:213], v151 offset:6144
	ds_read_b128 v[214:217], v151 offset:7168
	global_load_lds_dwordx4 v[144:145], off
	v_lshl_add_u64 v[144:145], s[22:23], 0, v[136:137]
	s_add_i32 m0, s37, 0xe000
	s_nop 0
	global_load_lds_dwordx4 v[144:145], off
	s_waitcnt vmcnt(8)
	s_waitcnt lgkmcnt(0)
	s_barrier
	s_setprio 1
	s_waitcnt lgkmcnt(0)
	v_mfma_f32_16x16x32_bf16 v[124:127], v[152:155], v[186:189], v[124:127]
	v_mfma_f32_16x16x32_bf16 v[120:123], v[160:163], v[186:189], v[120:123]
	v_mfma_f32_16x16x32_bf16 v[116:119], v[152:155], v[194:197], v[116:119]
	v_mfma_f32_16x16x32_bf16 v[108:111], v[160:163], v[194:197], v[108:111]
	v_mfma_f32_16x16x32_bf16 v[100:103], v[152:155], v[202:205], v[100:103]
	v_mfma_f32_16x16x32_bf16 v[92:95], v[160:163], v[202:205], v[92:95]
	v_mfma_f32_16x16x32_bf16 v[84:87], v[152:155], v[210:213], v[84:87]
	v_mfma_f32_16x16x32_bf16 v[76:79], v[160:163], v[210:213], v[76:79]
	v_mfma_f32_16x16x32_bf16 v[124:127], v[156:159], v[190:193], v[124:127]
	v_mfma_f32_16x16x32_bf16 v[120:123], v[164:167], v[190:193], v[120:123]
	v_mfma_f32_16x16x32_bf16 v[116:119], v[156:159], v[198:201], v[116:119]
	v_mfma_f32_16x16x32_bf16 v[108:111], v[164:167], v[198:201], v[108:111]
	v_mfma_f32_16x16x32_bf16 v[100:103], v[156:159], v[206:209], v[100:103]
	v_mfma_f32_16x16x32_bf16 v[92:95], v[164:167], v[206:209], v[92:95]
	v_mfma_f32_16x16x32_bf16 v[84:87], v[156:159], v[214:217], v[84:87]
	v_mfma_f32_16x16x32_bf16 v[76:79], v[164:167], v[214:217], v[76:79]
	s_setprio 0
	s_setprio 1
	v_mfma_f32_16x16x32_bf16 v[112:115], v[168:171], v[186:189], v[112:115]
	v_mfma_f32_16x16x32_bf16 v[104:107], v[176:179], v[186:189], v[104:107]
	v_mfma_f32_16x16x32_bf16 v[96:99], v[168:171], v[194:197], v[96:99]
	v_mfma_f32_16x16x32_bf16 v[88:91], v[176:179], v[194:197], v[88:91]
	v_mfma_f32_16x16x32_bf16 v[80:83], v[168:171], v[202:205], v[80:83]
	v_mfma_f32_16x16x32_bf16 v[72:75], v[176:179], v[202:205], v[72:75]
	v_mfma_f32_16x16x32_bf16 v[68:71], v[168:171], v[210:213], v[68:71]
	v_mfma_f32_16x16x32_bf16 v[64:67], v[176:179], v[210:213], v[64:67]
	v_mfma_f32_16x16x32_bf16 v[112:115], v[172:175], v[190:193], v[112:115]
	v_mfma_f32_16x16x32_bf16 v[104:107], v[180:183], v[190:193], v[104:107]
	v_mfma_f32_16x16x32_bf16 v[96:99], v[172:175], v[198:201], v[96:99]
	v_mfma_f32_16x16x32_bf16 v[88:91], v[180:183], v[198:201], v[88:91]
	v_mfma_f32_16x16x32_bf16 v[80:83], v[172:175], v[206:209], v[80:83]
	v_mfma_f32_16x16x32_bf16 v[72:75], v[180:183], v[206:209], v[72:75]
	v_mfma_f32_16x16x32_bf16 v[68:71], v[172:175], v[214:217], v[68:71]
	v_mfma_f32_16x16x32_bf16 v[64:67], v[180:183], v[214:217], v[64:67]
	s_setprio 0
	s_barrier
	s_add_i32 s22, s46, s36
	v_lshl_add_u64 v[144:145], s[26:27], 0, v[130:131]
	s_mov_b32 m0, s22
	ds_read_b128 v[186:189], v151 offset:16384
	ds_read_b128 v[190:193], v151 offset:17408
	ds_read_b128 v[194:197], v151 offset:18432
	ds_read_b128 v[198:201], v151 offset:19456
	ds_read_b128 v[202:205], v151 offset:20480
	ds_read_b128 v[206:209], v151 offset:21504
	ds_read_b128 v[210:213], v151 offset:22528
	ds_read_b128 v[214:217], v151 offset:23552
	global_load_lds_dwordx4 v[144:145], off
	s_add_i32 m0, s22, 0x2000
	s_add_u32 s22, s26, 0xb0000
	v_lshl_add_u64 v[218:219], s[26:27], 0, v[134:135]
	s_addc_u32 s23, s27, 0
	s_add_i32 s58, s93, s36
	global_load_lds_dwordx4 v[218:219], off
	v_lshl_add_u64 v[220:221], s[22:23], 0, v[130:131]
	s_mov_b32 m0, s58
	v_lshl_add_u64 v[222:223], s[28:29], 0, v[132:133]
	global_load_lds_dwordx4 v[220:221], off
	v_lshl_add_u64 v[220:221], s[22:23], 0, v[134:135]
	s_add_i32 m0, s58, 0x2000
	s_nop 0
	global_load_lds_dwordx4 v[220:221], off
	v_lshl_add_u64 v[220:221], s[28:29], 0, v[128:129]
	s_mov_b32 m0, s37
	s_nop 0
	global_load_lds_dwordx4 v[220:221], off
	s_mov_b32 m0, s38
	s_nop 0
	global_load_lds_dwordx4 v[222:223], off
	s_waitcnt vmcnt(8)
	s_waitcnt lgkmcnt(0)
	s_barrier
; #define PG8_STAGE(bufoff, gbase, voff) do { _Pragma("unroll") for (int _i = 0; _i < 2; ++_i) \
;         __builtin_amdgcn_global_load_lds((const unsigned*)((const char*)(gbase) + (voff)[_i]), (PG8_LAS unsigned*)(lds + (bufoff) + ldsw + _i * 8192), 16, 0, 0); } while (0)
; #define PG8_LDA(dst, b, h) do { _Pragma("unroll") for (int m = 0; m < 4; ++m) _Pragma("unroll") for (int k = 0; k < 2; ++k) dst[m][k] = *(const PG8_LAS bf16x8*)(lds + PG8_SA(b, h) + aoff + m * 2048 + k * 1024); } while (0)
; #define PG8_LDB(dst, b, h) do { _Pragma("unroll") for (int n = 0; n < 2; ++n) _Pragma("unroll") for (int k = 0; k < 2; ++k) dst[n][k] = *(const PG8_LAS bf16x8*)(lds + PG8_SB(b, h) + boff + n * 2048 + k * 1024); } while (0)
; #define PG8_MMA(ai, bj, At, Bt) do { __builtin_amdgcn_s_setprio(1); _Pragma("unroll") for (int m = 0; m < 4; ++m) _Pragma("unroll") for (int n = 0; n < 2; ++n) _Pragma("unroll") for (int k = 0; k < 2; ++k) \
;         acc[ai][bj][m][n] = __builtin_amdgcn_mfma_f32_16x16x32_bf16(Bt[n][k], At[m][k], acc[ai][bj][m][n], 0, 0, 0); __builtin_amdgcn_s_setprio(0); } while (0)
; #define PG8_WAIT_V(n) asm volatile("s_waitcnt vmcnt(" #n ")" ::: "memory")
; #define PG8_WAIT_L(n) asm volatile("s_waitcnt lgkmcnt(" #n ")" ::: "memory")
; #define PG8_BAR __builtin_amdgcn_s_barrier()
; #define PG8_SCHED __builtin_amdgcn_sched_barrier(0)
; template <class Epi, class Sched, bool ALIGN_EPI = false, bool SP2 = false>
; __device__ __forceinline__ void gemm_phase(PG8_LAS unsigned char* lds, const Gemm g, const Sched& S, const Epi& E) {
;     ...
;             PG8_WAIT_V(8); PG8_WAIT_L(0); PG8_BAR; PG8_MMA(1, 0, At, B0); PG8_MMA(1, 1, At, B1); PG8_BAR; PG8_SCHED;
;             PG8_LDB(B0, 1, 0); PG8_LDB(B1, 1, 1); PG8_SCHED; PG8_LDA(At, 1, 0); PG8_STAGE(PG8_SA(0, 1), a2 + hstep, voffA);
;             PG8_WAIT_V(8); PG8_WAIT_L(0); PG8_BAR; PG8_MMA(0, 0, At, B0); PG8_MMA(0, 1, At, B1); PG8_BAR; PG8_SCHED;
	s_setprio 1
	s_waitcnt lgkmcnt(0)
	v_mfma_f32_16x16x32_bf16 v[60:63], v[152:155], v[186:189], v[60:63]
	v_mfma_f32_16x16x32_bf16 v[56:59], v[160:163], v[186:189], v[56:59]
	v_mfma_f32_16x16x32_bf16 v[52:55], v[152:155], v[194:197], v[52:55]
	v_mfma_f32_16x16x32_bf16 v[44:47], v[160:163], v[194:197], v[44:47]
	v_mfma_f32_16x16x32_bf16 v[36:39], v[152:155], v[202:205], v[36:39]
	v_mfma_f32_16x16x32_bf16 v[28:31], v[160:163], v[202:205], v[28:31]
	v_mfma_f32_16x16x32_bf16 v[20:23], v[152:155], v[210:213], v[20:23]
	v_mfma_f32_16x16x32_bf16 v[12:15], v[160:163], v[210:213], v[12:15]
	v_mfma_f32_16x16x32_bf16 v[60:63], v[156:159], v[190:193], v[60:63]
	v_mfma_f32_16x16x32_bf16 v[56:59], v[164:167], v[190:193], v[56:59]
	v_mfma_f32_16x16x32_bf16 v[52:55], v[156:159], v[198:201], v[52:55]
	v_mfma_f32_16x16x32_bf16 v[44:47], v[164:167], v[198:201], v[44:47]
	v_mfma_f32_16x16x32_bf16 v[36:39], v[156:159], v[206:209], v[36:39]
	v_mfma_f32_16x16x32_bf16 v[28:31], v[164:167], v[206:209], v[28:31]
	v_mfma_f32_16x16x32_bf16 v[20:23], v[156:159], v[214:217], v[20:23]
	v_mfma_f32_16x16x32_bf16 v[12:15], v[164:167], v[214:217], v[12:15]
	s_setprio 0
	s_setprio 1
	v_mfma_f32_16x16x32_bf16 v[48:51], v[168:171], v[186:189], v[48:51]
	v_mfma_f32_16x16x32_bf16 v[40:43], v[176:179], v[186:189], v[40:43]
	v_mfma_f32_16x16x32_bf16 v[32:35], v[168:171], v[194:197], v[32:35]
	v_mfma_f32_16x16x32_bf16 v[24:27], v[176:179], v[194:197], v[24:27]
	v_mfma_f32_16x16x32_bf16 v[16:19], v[168:171], v[202:205], v[16:19]
	v_mfma_f32_16x16x32_bf16 v[8:11], v[176:179], v[202:205], v[8:11]
	v_mfma_f32_16x16x32_bf16 v[4:7], v[168:171], v[210:213], v[4:7]
	v_mfma_f32_16x16x32_bf16 v[0:3], v[176:179], v[210:213], v[0:3]
	v_mfma_f32_16x16x32_bf16 v[48:51], v[172:175], v[190:193], v[48:51]
	v_mfma_f32_16x16x32_bf16 v[40:43], v[180:183], v[190:193], v[40:43]
	v_mfma_f32_16x16x32_bf16 v[32:35], v[172:175], v[198:201], v[32:35]
	v_mfma_f32_16x16x32_bf16 v[24:27], v[180:183], v[198:201], v[24:27]
	v_mfma_f32_16x16x32_bf16 v[16:19], v[172:175], v[206:209], v[16:19]
	v_mfma_f32_16x16x32_bf16 v[8:11], v[180:183], v[206:209], v[8:11]
	v_mfma_f32_16x16x32_bf16 v[4:7], v[172:175], v[214:217], v[4:7]
	v_mfma_f32_16x16x32_bf16 v[0:3], v[180:183], v[214:217], v[0:3]
	s_setprio 0
	s_barrier
	s_add_i32 s58, 0, 0x18000
	s_add_i32 s59, 0, 0x1c000
	v_add_u32_e32 v164, s58, v147
	v_add_u32_e32 v180, s59, v147
	ds_read_b128 v[152:155], v164
	ds_read_b128 v[156:159], v164 offset:1024
	ds_read_b128 v[160:163], v164 offset:2048
	ds_read_b128 v[164:167], v164 offset:3072
	ds_read_b128 v[168:171], v180
	ds_read_b128 v[172:175], v180 offset:1024
	ds_read_b128 v[176:179], v180 offset:2048
	ds_read_b128 v[180:183], v180 offset:3072
	s_add_u32 s22, s28, 0xb0000
	s_addc_u32 s23, s29, 0
	s_mov_b32 m0, s39
	v_lshl_add_u64 v[224:225], s[22:23], 0, v[128:129]
	ds_read_b128 v[186:189], v151 offset:32768
	ds_read_b128 v[190:193], v151 offset:33792
	ds_read_b128 v[194:197], v151 offset:34816
	ds_read_b128 v[198:201], v151 offset:35840
	ds_read_b128 v[202:205], v151 offset:36864
	ds_read_b128 v[206:209], v151 offset:37888
	ds_read_b128 v[210:213], v151 offset:38912
	ds_read_b128 v[214:217], v151 offset:39936
	global_load_lds_dwordx4 v[224:225], off
	v_lshl_add_u64 v[224:225], s[22:23], 0, v[132:133]
	s_mov_b32 m0, s40
	s_nop 0
	global_load_lds_dwordx4 v[224:225], off
	s_waitcnt vmcnt(8)
	s_waitcnt lgkmcnt(0)
	s_barrier
	s_setprio 1
	s_waitcnt lgkmcnt(0)
	v_mfma_f32_16x16x32_bf16 v[124:127], v[152:155], v[186:189], v[124:127]
	v_mfma_f32_16x16x32_bf16 v[120:123], v[160:163], v[186:189], v[120:123]
	v_mfma_f32_16x16x32_bf16 v[116:119], v[152:155], v[194:197], v[116:119]
	v_mfma_f32_16x16x32_bf16 v[108:111], v[160:163], v[194:197], v[108:111]
	v_mfma_f32_16x16x32_bf16 v[100:103], v[152:155], v[202:205], v[100:103]
	v_mfma_f32_16x16x32_bf16 v[92:95], v[160:163], v[202:205], v[92:95]
	v_mfma_f32_16x16x32_bf16 v[84:87], v[152:155], v[210:213], v[84:87]
	v_mfma_f32_16x16x32_bf16 v[76:79], v[160:163], v[210:213], v[76:79]
	v_mfma_f32_16x16x32_bf16 v[124:127], v[156:159], v[190:193], v[124:127]
	v_mfma_f32_16x16x32_bf16 v[120:123], v[164:167], v[190:193], v[120:123]
	v_mfma_f32_16x16x32_bf16 v[116:119], v[156:159], v[198:201], v[116:119]
	v_mfma_f32_16x16x32_bf16 v[108:111], v[164:167], v[198:201], v[108:111]
	v_mfma_f32_16x16x32_bf16 v[100:103], v[156:159], v[206:209], v[100:103]
	v_mfma_f32_16x16x32_bf16 v[92:95], v[164:167], v[206:209], v[92:95]
	v_mfma_f32_16x16x32_bf16 v[84:87], v[156:159], v[214:217], v[84:87]
	v_mfma_f32_16x16x32_bf16 v[76:79], v[164:167], v[214:217], v[76:79]
	s_setprio 0
	s_setprio 1
	v_mfma_f32_16x16x32_bf16 v[112:115], v[168:171], v[186:189], v[112:115]
	v_mfma_f32_16x16x32_bf16 v[104:107], v[176:179], v[186:189], v[104:107]
	v_mfma_f32_16x16x32_bf16 v[96:99], v[168:171], v[194:197], v[96:99]
	v_mfma_f32_16x16x32_bf16 v[88:91], v[176:179], v[194:197], v[88:91]
	v_mfma_f32_16x16x32_bf16 v[80:83], v[168:171], v[202:205], v[80:83]
	v_mfma_f32_16x16x32_bf16 v[72:75], v[176:179], v[202:205], v[72:75]
	v_mfma_f32_16x16x32_bf16 v[68:71], v[168:171], v[210:213], v[68:71]
	v_mfma_f32_16x16x32_bf16 v[64:67], v[176:179], v[210:213], v[64:67]
	v_mfma_f32_16x16x32_bf16 v[112:115], v[172:175], v[190:193], v[112:115]
	v_mfma_f32_16x16x32_bf16 v[104:107], v[180:183], v[190:193], v[104:107]
	v_mfma_f32_16x16x32_bf16 v[96:99], v[172:175], v[198:201], v[96:99]
	v_mfma_f32_16x16x32_bf16 v[88:91], v[180:183], v[198:201], v[88:91]
	v_mfma_f32_16x16x32_bf16 v[80:83], v[172:175], v[206:209], v[80:83]
	v_mfma_f32_16x16x32_bf16 v[72:75], v[180:183], v[206:209], v[72:75]
	v_mfma_f32_16x16x32_bf16 v[68:71], v[172:175], v[214:217], v[68:71]
	v_mfma_f32_16x16x32_bf16 v[64:67], v[180:183], v[214:217], v[64:67]
	s_setprio 0
	s_barrier
; #define PG8_STAGE(bufoff, gbase, voff) do { _Pragma("unroll") for (int _i = 0; _i < 2; ++_i) \
;         __builtin_amdgcn_global_load_lds((const unsigned*)((const char*)(gbase) + (voff)[_i]), (PG8_LAS unsigned*)(lds + (bufoff) + ldsw + _i * 8192), 16, 0, 0); } while (0)
; #define PG8_LDA(dst, b, h) do { _Pragma("unroll") for (int m = 0; m < 4; ++m) _Pragma("unroll") for (int k = 0; k < 2; ++k) dst[m][k] = *(const PG8_LAS bf16x8*)(lds + PG8_SA(b, h) + aoff + m * 2048 + k * 1024); } while (0)
; #define PG8_MMA(ai, bj, At, Bt) do { __builtin_amdgcn_s_setprio(1); _Pragma("unroll") for (int m = 0; m < 4; ++m) _Pragma("unroll") for (int n = 0; n < 2; ++n) _Pragma("unroll") for (int k = 0; k < 2; ++k) \
;         acc[ai][bj][m][n] = __builtin_amdgcn_mfma_f32_16x16x32_bf16(Bt[n][k], At[m][k], acc[ai][bj][m][n], 0, 0, 0); __builtin_amdgcn_s_setprio(0); } while (0)
; #define PG8_WAIT_V(n) asm volatile("s_waitcnt vmcnt(" #n ")" ::: "memory")
; #define PG8_WAIT_L(n) asm volatile("s_waitcnt lgkmcnt(" #n ")" ::: "memory")
; #define PG8_BAR __builtin_amdgcn_s_barrier()
; #define PG8_SCHED __builtin_amdgcn_sched_barrier(0)
; template <class Epi, class Sched, bool ALIGN_EPI = false, bool SP2 = false>
; __device__ __forceinline__ void gemm_phase(PG8_LAS unsigned char* lds, const Gemm g, const Sched& S, const Epi& E) {
;     ...
;         for (int t = 0; t < nt; t += 2) {
;     ...
;             PG8_LDA(At, 1, 1); PG8_STAGE(PG8_SB(1, 0), b3, voffB); PG8_STAGE(PG8_SB(1, 1), b3 + hstep, voffB); PG8_STAGE(PG8_SA(1, 0), a3, voffA);
;             PG8_WAIT_V(8); PG8_WAIT_L(0); PG8_BAR; PG8_MMA(1, 0, At, B0); PG8_MMA(1, 1, At, B1); PG8_BAR; PG8_SCHED;
	s_add_i32 s22, s58, s36
	v_lshl_add_u64 v[144:145], v[144:145], 0, s[8:9]
	s_mov_b32 m0, s22
	ds_read_b128 v[186:189], v151 offset:49152
	ds_read_b128 v[190:193], v151 offset:50176
	ds_read_b128 v[194:197], v151 offset:51200
	ds_read_b128 v[198:201], v151 offset:52224
	ds_read_b128 v[202:205], v151 offset:53248
	ds_read_b128 v[206:209], v151 offset:54272
	ds_read_b128 v[210:213], v151 offset:55296
	ds_read_b128 v[214:217], v151 offset:56320
	global_load_lds_dwordx4 v[144:145], off
	s_add_i32 m0, s22, 0x2000
	s_add_u32 s22, s26, 0xb0080
	v_lshl_add_u64 v[144:145], v[218:219], 0, s[8:9]
	s_addc_u32 s23, s27, 0
	s_add_i32 s26, s59, s36
	global_load_lds_dwordx4 v[144:145], off
	v_lshl_add_u64 v[144:145], s[22:23], 0, v[130:131]
	s_mov_b32 m0, s26
	s_nop 0
	global_load_lds_dwordx4 v[144:145], off
	v_lshl_add_u64 v[144:145], s[22:23], 0, v[134:135]
	s_add_i32 m0, s26, 0x2000
	s_nop 0
	global_load_lds_dwordx4 v[144:145], off
	v_lshl_add_u64 v[144:145], v[220:221], 0, s[8:9]
	s_mov_b32 m0, s42
	s_nop 0
	global_load_lds_dwordx4 v[144:145], off
	v_lshl_add_u64 v[144:145], v[222:223], 0, s[8:9]
	s_mov_b32 m0, s43
	s_nop 0
	global_load_lds_dwordx4 v[144:145], off
	s_waitcnt vmcnt(8)
	s_waitcnt lgkmcnt(0)
	s_barrier
	s_setprio 1
	s_waitcnt lgkmcnt(0)
	v_mfma_f32_16x16x32_bf16 v[60:63], v[152:155], v[186:189], v[60:63]
	v_mfma_f32_16x16x32_bf16 v[56:59], v[160:163], v[186:189], v[56:59]
	v_mfma_f32_16x16x32_bf16 v[52:55], v[152:155], v[194:197], v[52:55]
	v_mfma_f32_16x16x32_bf16 v[44:47], v[160:163], v[194:197], v[44:47]
	v_mfma_f32_16x16x32_bf16 v[36:39], v[152:155], v[202:205], v[36:39]
	v_mfma_f32_16x16x32_bf16 v[28:31], v[160:163], v[202:205], v[28:31]
	v_mfma_f32_16x16x32_bf16 v[20:23], v[152:155], v[210:213], v[20:23]
	v_mfma_f32_16x16x32_bf16 v[12:15], v[160:163], v[210:213], v[12:15]
	v_mfma_f32_16x16x32_bf16 v[60:63], v[156:159], v[190:193], v[60:63]
	v_mfma_f32_16x16x32_bf16 v[56:59], v[164:167], v[190:193], v[56:59]
	v_mfma_f32_16x16x32_bf16 v[52:55], v[156:159], v[198:201], v[52:55]
	v_mfma_f32_16x16x32_bf16 v[44:47], v[164:167], v[198:201], v[44:47]
	v_mfma_f32_16x16x32_bf16 v[36:39], v[156:159], v[206:209], v[36:39]
	v_mfma_f32_16x16x32_bf16 v[28:31], v[164:167], v[206:209], v[28:31]
	v_mfma_f32_16x16x32_bf16 v[20:23], v[156:159], v[214:217], v[20:23]
	v_mfma_f32_16x16x32_bf16 v[12:15], v[164:167], v[214:217], v[12:15]
	s_setprio 0
	s_setprio 1
	v_mfma_f32_16x16x32_bf16 v[48:51], v[168:171], v[186:189], v[48:51]
	v_mfma_f32_16x16x32_bf16 v[40:43], v[176:179], v[186:189], v[40:43]
	v_mfma_f32_16x16x32_bf16 v[32:35], v[168:171], v[194:197], v[32:35]
	v_mfma_f32_16x16x32_bf16 v[24:27], v[176:179], v[194:197], v[24:27]
	v_mfma_f32_16x16x32_bf16 v[16:19], v[168:171], v[202:205], v[16:19]
	v_mfma_f32_16x16x32_bf16 v[8:11], v[176:179], v[202:205], v[8:11]
	v_mfma_f32_16x16x32_bf16 v[4:7], v[168:171], v[210:213], v[4:7]
	v_mfma_f32_16x16x32_bf16 v[0:3], v[176:179], v[210:213], v[0:3]
	v_mfma_f32_16x16x32_bf16 v[48:51], v[172:175], v[190:193], v[48:51]
	v_mfma_f32_16x16x32_bf16 v[40:43], v[180:183], v[190:193], v[40:43]
	v_mfma_f32_16x16x32_bf16 v[32:35], v[172:175], v[198:201], v[32:35]
	v_mfma_f32_16x16x32_bf16 v[24:27], v[180:183], v[198:201], v[24:27]
	v_mfma_f32_16x16x32_bf16 v[16:19], v[172:175], v[206:209], v[16:19]
	v_mfma_f32_16x16x32_bf16 v[8:11], v[180:183], v[206:209], v[8:11]
	v_mfma_f32_16x16x32_bf16 v[4:7], v[172:175], v[214:217], v[4:7]
	v_mfma_f32_16x16x32_bf16 v[0:3], v[180:183], v[214:217], v[0:3]
	s_setprio 0
	s_add_i32 s57, s57, 2
	s_add_u32 s55, s55, 0x100
	s_addc_u32 s56, s56, 0
	s_cmp_gt_u32 s57, 41
	s_mov_b64 s[22:23], s[24:25]
	s_barrier
	s_cbranch_scc0 .LBB0_1089
	s_and_b64 vcc, exec, s[10:11]
	s_cbranch_vccz .LBB0_1092
	s_barrier

; #define PG8_STAGE(bufoff, gbase, voff) do { _Pragma("unroll") for (int _i = 0; _i < 2; ++_i) \
;         __builtin_amdgcn_global_load_lds((const unsigned*)((const char*)(gbase) + (voff)[_i]), (PG8_LAS unsigned*)(lds + (bufoff) + ldsw + _i * 8192), 16, 0, 0); } while (0)
; #define PG8_LDA(dst, b, h) do { _Pragma("unroll") for (int m = 0; m < 4; ++m) _Pragma("unroll") for (int k = 0; k < 2; ++k) dst[m][k] = *(const PG8_LAS bf16x8*)(lds + PG8_SA(b, h) + aoff + m * 2048 + k * 1024); } while (0)
; #define PG8_LDB(dst, b, h) do { _Pragma("unroll") for (int n = 0; n < 2; ++n) _Pragma("unroll") for (int k = 0; k < 2; ++k) dst[n][k] = *(const PG8_LAS bf16x8*)(lds + PG8_SB(b, h) + boff + n * 2048 + k * 1024); } while (0)
; #define PG8_MMA(ai, bj, At, Bt) do { __builtin_amdgcn_s_setprio(1); _Pragma("unroll") for (int m = 0; m < 4; ++m) _Pragma("unroll") for (int n = 0; n < 2; ++n) _Pragma("unroll") for (int k = 0; k < 2; ++k) \
;         acc[ai][bj][m][n] = __builtin_amdgcn_mfma_f32_16x16x32_bf16(Bt[n][k], At[m][k], acc[ai][bj][m][n], 0, 0, 0); __builtin_amdgcn_s_setprio(0); } while (0)
; #define PG8_WAIT_V(n) asm volatile("s_waitcnt vmcnt(" #n ")" ::: "memory")
; #define PG8_WAIT_L(n) asm volatile("s_waitcnt lgkmcnt(" #n ")" ::: "memory")
; #define PG8_BAR __builtin_amdgcn_s_barrier()
; #define PG8_SCHED __builtin_amdgcn_sched_barrier(0)
; template <class Epi, class Sched, bool ALIGN_EPI = false, bool SP2 = false>
; __device__ __forceinline__ void gemm_phase(PG8_LAS unsigned char* lds, const Gemm g, const Sched& S, const Epi& E) {
;     ...
;         for (int t = 0; t < nt; t += 2) {
;             const bool last = (t == nt - 2);
;             const char* a1 = cA + (size_t)(t + 1) * kstep;
;             const char* a2 = last ? nA : cA + (size_t)(t + 2) * kstep; const char* b2 = last ? nB : cB + (size_t)(t + 2) * kstep;
;             const char* a3 = a2 + kstep; const char* b3 = b2 + kstep;
;             if (last && has_next) S.a_ready(nxt);
;             if constexpr (SP2) {
;             PG8_LDB(B0, 0, 0); PG8_LDB(B1, 0, 1); PG8_SCHED; PG8_LDA(At, 0, 0); PG8_STAGE(PG8_SA(1, 1), a1 + hstep, voffA);
;             PG8_WAIT_V(8); PG8_WAIT_L(0); PG8_BAR; PG8_MMA(0, 0, At, B0); PG8_MMA(0, 1, At, B1); PG8_BAR; PG8_SCHED;
;             PG8_LDA(At, 0, 1); PG8_STAGE(PG8_SB(0, 0), b2, voffB); PG8_STAGE(PG8_SB(0, 1), b2 + hstep, voffB); PG8_STAGE(PG8_SA(0, 0), a2, voffA);
.LBB0_1158:
	ds_read_b128 v[148:151], v145
	ds_read_b128 v[152:155], v145 offset:1024
	ds_read_b128 v[156:159], v145 offset:2048
	ds_read_b128 v[160:163], v145 offset:3072
	ds_read_b128 v[164:167], v146
	ds_read_b128 v[168:171], v146 offset:1024
	ds_read_b128 v[172:175], v146 offset:2048
	ds_read_b128 v[176:179], v146 offset:3072
	s_add_u32 s26, s24, 0x100
	s_addc_u32 s27, s25, 0
	s_cmp_eq_u32 s55, 40
	s_cselect_b32 s31, s21, s27
	s_cselect_b32 s30, s20, s26
	s_cselect_b32 s29, s23, s54
	s_cselect_b32 s28, s22, s53
	v_lshl_add_u64 v[140:141], s[24:25], 0, v[138:139]
	s_add_i32 m0, s36, 0xc000
	ds_read_b128 v[180:183], v147
	ds_read_b128 v[186:189], v147 offset:1024
	ds_read_b128 v[190:193], v147 offset:2048
	ds_read_b128 v[194:197], v147 offset:3072
	ds_read_b128 v[198:201], v147 offset:4096
	ds_read_b128 v[202:205], v147 offset:5120
	ds_read_b128 v[206:209], v147 offset:6144
	ds_read_b128 v[210:213], v147 offset:7168
	global_load_lds_dwordx4 v[140:141], off
	v_lshl_add_u64 v[140:141], s[24:25], 0, v[136:137]
	s_add_i32 m0, s36, 0xe000
	s_nop 0
	global_load_lds_dwordx4 v[140:141], off
	s_waitcnt vmcnt(8)
	s_waitcnt lgkmcnt(0)
	s_barrier
	s_setprio 1
	s_waitcnt lgkmcnt(0)
	v_mfma_f32_16x16x32_bf16 v[124:127], v[148:151], v[180:183], v[124:127]
	v_mfma_f32_16x16x32_bf16 v[120:123], v[156:159], v[180:183], v[120:123]
	v_mfma_f32_16x16x32_bf16 v[116:119], v[148:151], v[190:193], v[116:119]
	v_mfma_f32_16x16x32_bf16 v[108:111], v[156:159], v[190:193], v[108:111]
	v_mfma_f32_16x16x32_bf16 v[100:103], v[148:151], v[198:201], v[100:103]
	v_mfma_f32_16x16x32_bf16 v[92:95], v[156:159], v[198:201], v[92:95]
	v_mfma_f32_16x16x32_bf16 v[84:87], v[148:151], v[206:209], v[84:87]
	v_mfma_f32_16x16x32_bf16 v[76:79], v[156:159], v[206:209], v[76:79]
	v_mfma_f32_16x16x32_bf16 v[124:127], v[152:155], v[186:189], v[124:127]
	v_mfma_f32_16x16x32_bf16 v[120:123], v[160:163], v[186:189], v[120:123]
	v_mfma_f32_16x16x32_bf16 v[116:119], v[152:155], v[194:197], v[116:119]
	v_mfma_f32_16x16x32_bf16 v[108:111], v[160:163], v[194:197], v[108:111]
	v_mfma_f32_16x16x32_bf16 v[100:103], v[152:155], v[202:205], v[100:103]
	v_mfma_f32_16x16x32_bf16 v[92:95], v[160:163], v[202:205], v[92:95]
	v_mfma_f32_16x16x32_bf16 v[84:87], v[152:155], v[210:213], v[84:87]
	v_mfma_f32_16x16x32_bf16 v[76:79], v[160:163], v[210:213], v[76:79]
	s_setprio 0
	s_setprio 1
	v_mfma_f32_16x16x32_bf16 v[112:115], v[164:167], v[180:183], v[112:115]
	v_mfma_f32_16x16x32_bf16 v[104:107], v[172:175], v[180:183], v[104:107]
	v_mfma_f32_16x16x32_bf16 v[96:99], v[164:167], v[190:193], v[96:99]
	v_mfma_f32_16x16x32_bf16 v[88:91], v[172:175], v[190:193], v[88:91]
	v_mfma_f32_16x16x32_bf16 v[80:83], v[164:167], v[198:201], v[80:83]
	v_mfma_f32_16x16x32_bf16 v[72:75], v[172:175], v[198:201], v[72:75]
	v_mfma_f32_16x16x32_bf16 v[68:71], v[164:167], v[206:209], v[68:71]
	v_mfma_f32_16x16x32_bf16 v[64:67], v[172:175], v[206:209], v[64:67]
	v_mfma_f32_16x16x32_bf16 v[112:115], v[168:171], v[186:189], v[112:115]
	v_mfma_f32_16x16x32_bf16 v[104:107], v[176:179], v[186:189], v[104:107]
	v_mfma_f32_16x16x32_bf16 v[96:99], v[168:171], v[194:197], v[96:99]
	v_mfma_f32_16x16x32_bf16 v[88:91], v[176:179], v[194:197], v[88:91]
	v_mfma_f32_16x16x32_bf16 v[80:83], v[168:171], v[202:205], v[80:83]
	v_mfma_f32_16x16x32_bf16 v[72:75], v[176:179], v[202:205], v[72:75]
	v_mfma_f32_16x16x32_bf16 v[68:71], v[168:171], v[210:213], v[68:71]
	v_mfma_f32_16x16x32_bf16 v[64:67], v[176:179], v[210:213], v[64:67]
	s_setprio 0
	s_barrier
	s_add_i32 s24, s43, s35
	v_lshl_add_u64 v[140:141], s[28:29], 0, v[130:131]
	s_mov_b32 m0, s24
	ds_read_b128 v[180:183], v147 offset:16384
	ds_read_b128 v[186:189], v147 offset:17408
	ds_read_b128 v[190:193], v147 offset:18432
	ds_read_b128 v[194:197], v147 offset:19456
	ds_read_b128 v[198:201], v147 offset:20480
	ds_read_b128 v[202:205], v147 offset:21504
	ds_read_b128 v[206:209], v147 offset:22528
	ds_read_b128 v[210:213], v147 offset:23552
	global_load_lds_dwordx4 v[140:141], off
	s_add_i32 m0, s24, 0x2000
	s_add_u32 s24, s28, 0xb0000
	v_lshl_add_u64 v[214:215], s[28:29], 0, v[134:135]
	s_addc_u32 s25, s29, 0
	s_add_i32 s56, s93, s35
	global_load_lds_dwordx4 v[214:215], off
	v_lshl_add_u64 v[216:217], s[24:25], 0, v[130:131]
	s_mov_b32 m0, s56
	v_lshl_add_u64 v[218:219], s[30:31], 0, v[132:133]
	global_load_lds_dwordx4 v[216:217], off
	v_lshl_add_u64 v[216:217], s[24:25], 0, v[134:135]
	s_add_i32 m0, s56, 0x2000
	s_nop 0
	global_load_lds_dwordx4 v[216:217], off
	v_lshl_add_u64 v[216:217], s[30:31], 0, v[128:129]
	s_mov_b32 m0, s36
	s_nop 0
	global_load_lds_dwordx4 v[216:217], off
	s_mov_b32 m0, s37
	s_nop 0
	global_load_lds_dwordx4 v[218:219], off
	s_waitcnt vmcnt(8)
	s_waitcnt lgkmcnt(0)
	s_barrier
; #define PG8_STAGE(bufoff, gbase, voff) do { _Pragma("unroll") for (int _i = 0; _i < 2; ++_i) \
;         __builtin_amdgcn_global_load_lds((const unsigned*)((const char*)(gbase) + (voff)[_i]), (PG8_LAS unsigned*)(lds + (bufoff) + ldsw + _i * 8192), 16, 0, 0); } while (0)
; #define PG8_LDA(dst, b, h) do { _Pragma("unroll") for (int m = 0; m < 4; ++m) _Pragma("unroll") for (int k = 0; k < 2; ++k) dst[m][k] = *(const PG8_LAS bf16x8*)(lds + PG8_SA(b, h) + aoff + m * 2048 + k * 1024); } while (0)
; #define PG8_LDB(dst, b, h) do { _Pragma("unroll") for (int n = 0; n < 2; ++n) _Pragma("unroll") for (int k = 0; k < 2; ++k) dst[n][k] = *(const PG8_LAS bf16x8*)(lds + PG8_SB(b, h) + boff + n * 2048 + k * 1024); } while (0)
; #define PG8_MMA(ai, bj, At, Bt) do { __builtin_amdgcn_s_setprio(1); _Pragma("unroll") for (int m = 0; m < 4; ++m) _Pragma("unroll") for (int n = 0; n < 2; ++n) _Pragma("unroll") for (int k = 0; k < 2; ++k) \
;         acc[ai][bj][m][n] = __builtin_amdgcn_mfma_f32_16x16x32_bf16(Bt[n][k], At[m][k], acc[ai][bj][m][n], 0, 0, 0); __builtin_amdgcn_s_setprio(0); } while (0)
; #define PG8_WAIT_V(n) asm volatile("s_waitcnt vmcnt(" #n ")" ::: "memory")
; #define PG8_WAIT_L(n) asm volatile("s_waitcnt lgkmcnt(" #n ")" ::: "memory")
; #define PG8_BAR __builtin_amdgcn_s_barrier()
; #define PG8_SCHED __builtin_amdgcn_sched_barrier(0)
; template <class Epi, class Sched, bool ALIGN_EPI = false, bool SP2 = false>
; __device__ __forceinline__ void gemm_phase(PG8_LAS unsigned char* lds, const Gemm g, const Sched& S, const Epi& E) {
;     ...
;             PG8_WAIT_V(8); PG8_WAIT_L(0); PG8_BAR; PG8_MMA(1, 0, At, B0); PG8_MMA(1, 1, At, B1); PG8_BAR; PG8_SCHED;
;             PG8_LDB(B0, 1, 0); PG8_LDB(B1, 1, 1); PG8_SCHED; PG8_LDA(At, 1, 0); PG8_STAGE(PG8_SA(0, 1), a2 + hstep, voffA);
;             PG8_WAIT_V(8); PG8_WAIT_L(0); PG8_BAR; PG8_MMA(0, 0, At, B0); PG8_MMA(0, 1, At, B1); PG8_BAR; PG8_SCHED;
	s_setprio 1
	s_waitcnt lgkmcnt(0)
	v_mfma_f32_16x16x32_bf16 v[60:63], v[148:151], v[180:183], v[60:63]
	v_mfma_f32_16x16x32_bf16 v[56:59], v[156:159], v[180:183], v[56:59]
	v_mfma_f32_16x16x32_bf16 v[52:55], v[148:151], v[190:193], v[52:55]
	v_mfma_f32_16x16x32_bf16 v[44:47], v[156:159], v[190:193], v[44:47]
	v_mfma_f32_16x16x32_bf16 v[36:39], v[148:151], v[198:201], v[36:39]
	v_mfma_f32_16x16x32_bf16 v[28:31], v[156:159], v[198:201], v[28:31]
	v_mfma_f32_16x16x32_bf16 v[20:23], v[148:151], v[206:209], v[20:23]
	v_mfma_f32_16x16x32_bf16 v[12:15], v[156:159], v[206:209], v[12:15]
	v_mfma_f32_16x16x32_bf16 v[60:63], v[152:155], v[186:189], v[60:63]
	v_mfma_f32_16x16x32_bf16 v[56:59], v[160:163], v[186:189], v[56:59]
	v_mfma_f32_16x16x32_bf16 v[52:55], v[152:155], v[194:197], v[52:55]
	v_mfma_f32_16x16x32_bf16 v[44:47], v[160:163], v[194:197], v[44:47]
	v_mfma_f32_16x16x32_bf16 v[36:39], v[152:155], v[202:205], v[36:39]
	v_mfma_f32_16x16x32_bf16 v[28:31], v[160:163], v[202:205], v[28:31]
	v_mfma_f32_16x16x32_bf16 v[20:23], v[152:155], v[210:213], v[20:23]
	v_mfma_f32_16x16x32_bf16 v[12:15], v[160:163], v[210:213], v[12:15]
	s_setprio 0
	s_setprio 1
	v_mfma_f32_16x16x32_bf16 v[48:51], v[164:167], v[180:183], v[48:51]
	v_mfma_f32_16x16x32_bf16 v[40:43], v[172:175], v[180:183], v[40:43]
	v_mfma_f32_16x16x32_bf16 v[32:35], v[164:167], v[190:193], v[32:35]
	v_mfma_f32_16x16x32_bf16 v[24:27], v[172:175], v[190:193], v[24:27]
	v_mfma_f32_16x16x32_bf16 v[16:19], v[164:167], v[198:201], v[16:19]
	v_mfma_f32_16x16x32_bf16 v[8:11], v[172:175], v[198:201], v[8:11]
	v_mfma_f32_16x16x32_bf16 v[4:7], v[164:167], v[206:209], v[4:7]
	v_mfma_f32_16x16x32_bf16 v[0:3], v[172:175], v[206:209], v[0:3]
	v_mfma_f32_16x16x32_bf16 v[48:51], v[168:171], v[186:189], v[48:51]
	v_mfma_f32_16x16x32_bf16 v[40:43], v[176:179], v[186:189], v[40:43]
	v_mfma_f32_16x16x32_bf16 v[32:35], v[168:171], v[194:197], v[32:35]
	v_mfma_f32_16x16x32_bf16 v[24:27], v[176:179], v[194:197], v[24:27]
	v_mfma_f32_16x16x32_bf16 v[16:19], v[168:171], v[202:205], v[16:19]
	v_mfma_f32_16x16x32_bf16 v[8:11], v[176:179], v[202:205], v[8:11]
	v_mfma_f32_16x16x32_bf16 v[4:7], v[168:171], v[210:213], v[4:7]
	v_mfma_f32_16x16x32_bf16 v[0:3], v[176:179], v[210:213], v[0:3]
	s_setprio 0
	s_barrier
	s_add_i32 s56, 0, 0x18000
	s_add_i32 s57, 0, 0x1c000
	v_add_u32_e32 v160, s56, v143
	v_add_u32_e32 v176, s57, v143
	ds_read_b128 v[148:151], v160
	ds_read_b128 v[152:155], v160 offset:1024
	ds_read_b128 v[156:159], v160 offset:2048
	ds_read_b128 v[160:163], v160 offset:3072
	ds_read_b128 v[164:167], v176
	ds_read_b128 v[168:171], v176 offset:1024
	ds_read_b128 v[172:175], v176 offset:2048
	ds_read_b128 v[176:179], v176 offset:3072
	s_add_u32 s24, s30, 0xb0000
	s_addc_u32 s25, s31, 0
	s_mov_b32 m0, s38
	v_lshl_add_u64 v[220:221], s[24:25], 0, v[128:129]
	ds_read_b128 v[180:183], v147 offset:32768
	ds_read_b128 v[186:189], v147 offset:33792
	ds_read_b128 v[190:193], v147 offset:34816
	ds_read_b128 v[194:197], v147 offset:35840
	ds_read_b128 v[198:201], v147 offset:36864
	ds_read_b128 v[202:205], v147 offset:37888
	ds_read_b128 v[206:209], v147 offset:38912
	ds_read_b128 v[210:213], v147 offset:39936
	global_load_lds_dwordx4 v[220:221], off
	v_lshl_add_u64 v[220:221], s[24:25], 0, v[132:133]
	s_mov_b32 m0, s39
	s_nop 0
	global_load_lds_dwordx4 v[220:221], off
	s_waitcnt vmcnt(8)
	s_waitcnt lgkmcnt(0)
	s_barrier
	s_setprio 1
	s_waitcnt lgkmcnt(0)
	v_mfma_f32_16x16x32_bf16 v[124:127], v[148:151], v[180:183], v[124:127]
	v_mfma_f32_16x16x32_bf16 v[120:123], v[156:159], v[180:183], v[120:123]
	v_mfma_f32_16x16x32_bf16 v[116:119], v[148:151], v[190:193], v[116:119]
	v_mfma_f32_16x16x32_bf16 v[108:111], v[156:159], v[190:193], v[108:111]
	v_mfma_f32_16x16x32_bf16 v[100:103], v[148:151], v[198:201], v[100:103]
	v_mfma_f32_16x16x32_bf16 v[92:95], v[156:159], v[198:201], v[92:95]
	v_mfma_f32_16x16x32_bf16 v[84:87], v[148:151], v[206:209], v[84:87]
	v_mfma_f32_16x16x32_bf16 v[76:79], v[156:159], v[206:209], v[76:79]
	v_mfma_f32_16x16x32_bf16 v[124:127], v[152:155], v[186:189], v[124:127]
	v_mfma_f32_16x16x32_bf16 v[120:123], v[160:163], v[186:189], v[120:123]
	v_mfma_f32_16x16x32_bf16 v[116:119], v[152:155], v[194:197], v[116:119]
	v_mfma_f32_16x16x32_bf16 v[108:111], v[160:163], v[194:197], v[108:111]
	v_mfma_f32_16x16x32_bf16 v[100:103], v[152:155], v[202:205], v[100:103]
	v_mfma_f32_16x16x32_bf16 v[92:95], v[160:163], v[202:205], v[92:95]
	v_mfma_f32_16x16x32_bf16 v[84:87], v[152:155], v[210:213], v[84:87]
	v_mfma_f32_16x16x32_bf16 v[76:79], v[160:163], v[210:213], v[76:79]
	s_setprio 0
	s_setprio 1
	v_mfma_f32_16x16x32_bf16 v[112:115], v[164:167], v[180:183], v[112:115]
	v_mfma_f32_16x16x32_bf16 v[104:107], v[172:175], v[180:183], v[104:107]
	v_mfma_f32_16x16x32_bf16 v[96:99], v[164:167], v[190:193], v[96:99]
	v_mfma_f32_16x16x32_bf16 v[88:91], v[172:175], v[190:193], v[88:91]
	v_mfma_f32_16x16x32_bf16 v[80:83], v[164:167], v[198:201], v[80:83]
	v_mfma_f32_16x16x32_bf16 v[72:75], v[172:175], v[198:201], v[72:75]
	v_mfma_f32_16x16x32_bf16 v[68:71], v[164:167], v[206:209], v[68:71]
	v_mfma_f32_16x16x32_bf16 v[64:67], v[172:175], v[206:209], v[64:67]
	v_mfma_f32_16x16x32_bf16 v[112:115], v[168:171], v[186:189], v[112:115]
	v_mfma_f32_16x16x32_bf16 v[104:107], v[176:179], v[186:189], v[104:107]
	v_mfma_f32_16x16x32_bf16 v[96:99], v[168:171], v[194:197], v[96:99]
	v_mfma_f32_16x16x32_bf16 v[88:91], v[176:179], v[194:197], v[88:91]
	v_mfma_f32_16x16x32_bf16 v[80:83], v[168:171], v[202:205], v[80:83]
	v_mfma_f32_16x16x32_bf16 v[72:75], v[176:179], v[202:205], v[72:75]
	v_mfma_f32_16x16x32_bf16 v[68:71], v[168:171], v[210:213], v[68:71]
	v_mfma_f32_16x16x32_bf16 v[64:67], v[176:179], v[210:213], v[64:67]
	s_setprio 0
	s_barrier
; #define PG8_STAGE(bufoff, gbase, voff) do { _Pragma("unroll") for (int _i = 0; _i < 2; ++_i) \
;         __builtin_amdgcn_global_load_lds((const unsigned*)((const char*)(gbase) + (voff)[_i]), (PG8_LAS unsigned*)(lds + (bufoff) + ldsw + _i * 8192), 16, 0, 0); } while (0)
; #define PG8_LDA(dst, b, h) do { _Pragma("unroll") for (int m = 0; m < 4; ++m) _Pragma("unroll") for (int k = 0; k < 2; ++k) dst[m][k] = *(const PG8_LAS bf16x8*)(lds + PG8_SA(b, h) + aoff + m * 2048 + k * 1024); } while (0)
; #define PG8_MMA(ai, bj, At, Bt) do { __builtin_amdgcn_s_setprio(1); _Pragma("unroll") for (int m = 0; m < 4; ++m) _Pragma("unroll") for (int n = 0; n < 2; ++n) _Pragma("unroll") for (int k = 0; k < 2; ++k) \
;         acc[ai][bj][m][n] = __builtin_amdgcn_mfma_f32_16x16x32_bf16(Bt[n][k], At[m][k], acc[ai][bj][m][n], 0, 0, 0); __builtin_amdgcn_s_setprio(0); } while (0)
; #define PG8_WAIT_V(n) asm volatile("s_waitcnt vmcnt(" #n ")" ::: "memory")
; #define PG8_WAIT_L(n) asm volatile("s_waitcnt lgkmcnt(" #n ")" ::: "memory")
; #define PG8_BAR __builtin_amdgcn_s_barrier()
; #define PG8_SCHED __builtin_amdgcn_sched_barrier(0)
; template <class Epi, class Sched, bool ALIGN_EPI = false, bool SP2 = false>
; __device__ __forceinline__ void gemm_phase(PG8_LAS unsigned char* lds, const Gemm g, const Sched& S, const Epi& E) {
;     ...
;         for (int t = 0; t < nt; t += 2) {
;     ...
;             PG8_LDA(At, 1, 1); PG8_STAGE(PG8_SB(1, 0), b3, voffB); PG8_STAGE(PG8_SB(1, 1), b3 + hstep, voffB); PG8_STAGE(PG8_SA(1, 0), a3, voffA);
;             PG8_WAIT_V(8); PG8_WAIT_L(0); PG8_BAR; PG8_MMA(1, 0, At, B0); PG8_MMA(1, 1, At, B1); PG8_BAR; PG8_SCHED;
	s_add_i32 s24, s56, s35
	v_lshl_add_u64 v[140:141], v[140:141], 0, s[8:9]
	s_mov_b32 m0, s24
	ds_read_b128 v[180:183], v147 offset:49152
	ds_read_b128 v[186:189], v147 offset:50176
	ds_read_b128 v[190:193], v147 offset:51200
	ds_read_b128 v[194:197], v147 offset:52224
	ds_read_b128 v[198:201], v147 offset:53248
	ds_read_b128 v[202:205], v147 offset:54272
	ds_read_b128 v[206:209], v147 offset:55296
	ds_read_b128 v[210:213], v147 offset:56320
	global_load_lds_dwordx4 v[140:141], off
	s_add_i32 m0, s24, 0x2000
	s_add_u32 s24, s28, 0xb0080
	v_lshl_add_u64 v[140:141], v[214:215], 0, s[8:9]
	s_addc_u32 s25, s29, 0
	s_add_i32 s28, s57, s35
	global_load_lds_dwordx4 v[140:141], off
	v_lshl_add_u64 v[140:141], s[24:25], 0, v[130:131]
	s_mov_b32 m0, s28
	s_nop 0
	global_load_lds_dwordx4 v[140:141], off
	v_lshl_add_u64 v[140:141], s[24:25], 0, v[134:135]
	s_add_i32 m0, s28, 0x2000
	s_nop 0
	global_load_lds_dwordx4 v[140:141], off
	v_lshl_add_u64 v[140:141], v[216:217], 0, s[8:9]
	s_mov_b32 m0, s40
	s_nop 0
	global_load_lds_dwordx4 v[140:141], off
	v_lshl_add_u64 v[140:141], v[218:219], 0, s[8:9]
	s_mov_b32 m0, s41
	s_nop 0
	global_load_lds_dwordx4 v[140:141], off
	s_waitcnt vmcnt(8)
	s_waitcnt lgkmcnt(0)
	s_barrier
	s_setprio 1
	s_waitcnt lgkmcnt(0)
	v_mfma_f32_16x16x32_bf16 v[60:63], v[148:151], v[180:183], v[60:63]
	v_mfma_f32_16x16x32_bf16 v[56:59], v[156:159], v[180:183], v[56:59]
	v_mfma_f32_16x16x32_bf16 v[52:55], v[148:151], v[190:193], v[52:55]
	v_mfma_f32_16x16x32_bf16 v[44:47], v[156:159], v[190:193], v[44:47]
	v_mfma_f32_16x16x32_bf16 v[36:39], v[148:151], v[198:201], v[36:39]
	v_mfma_f32_16x16x32_bf16 v[28:31], v[156:159], v[198:201], v[28:31]
	v_mfma_f32_16x16x32_bf16 v[20:23], v[148:151], v[206:209], v[20:23]
	v_mfma_f32_16x16x32_bf16 v[12:15], v[156:159], v[206:209], v[12:15]
	v_mfma_f32_16x16x32_bf16 v[60:63], v[152:155], v[186:189], v[60:63]
	v_mfma_f32_16x16x32_bf16 v[56:59], v[160:163], v[186:189], v[56:59]
	v_mfma_f32_16x16x32_bf16 v[52:55], v[152:155], v[194:197], v[52:55]
	v_mfma_f32_16x16x32_bf16 v[44:47], v[160:163], v[194:197], v[44:47]
	v_mfma_f32_16x16x32_bf16 v[36:39], v[152:155], v[202:205], v[36:39]
	v_mfma_f32_16x16x32_bf16 v[28:31], v[160:163], v[202:205], v[28:31]
	v_mfma_f32_16x16x32_bf16 v[20:23], v[152:155], v[210:213], v[20:23]
	v_mfma_f32_16x16x32_bf16 v[12:15], v[160:163], v[210:213], v[12:15]
	s_setprio 0
	s_setprio 1
	v_mfma_f32_16x16x32_bf16 v[48:51], v[164:167], v[180:183], v[48:51]
	v_mfma_f32_16x16x32_bf16 v[40:43], v[172:175], v[180:183], v[40:43]
	v_mfma_f32_16x16x32_bf16 v[32:35], v[164:167], v[190:193], v[32:35]
	v_mfma_f32_16x16x32_bf16 v[24:27], v[172:175], v[190:193], v[24:27]
	v_mfma_f32_16x16x32_bf16 v[16:19], v[164:167], v[198:201], v[16:19]
	v_mfma_f32_16x16x32_bf16 v[8:11], v[172:175], v[198:201], v[8:11]
	v_mfma_f32_16x16x32_bf16 v[4:7], v[164:167], v[206:209], v[4:7]
	v_mfma_f32_16x16x32_bf16 v[0:3], v[172:175], v[206:209], v[0:3]
	v_mfma_f32_16x16x32_bf16 v[48:51], v[168:171], v[186:189], v[48:51]
	v_mfma_f32_16x16x32_bf16 v[40:43], v[176:179], v[186:189], v[40:43]
	v_mfma_f32_16x16x32_bf16 v[32:35], v[168:171], v[194:197], v[32:35]
	v_mfma_f32_16x16x32_bf16 v[24:27], v[176:179], v[194:197], v[24:27]
	v_mfma_f32_16x16x32_bf16 v[16:19], v[168:171], v[202:205], v[16:19]
	v_mfma_f32_16x16x32_bf16 v[8:11], v[176:179], v[202:205], v[8:11]
	v_mfma_f32_16x16x32_bf16 v[4:7], v[168:171], v[210:213], v[4:7]
	v_mfma_f32_16x16x32_bf16 v[0:3], v[176:179], v[210:213], v[0:3]
	s_setprio 0
	s_add_i32 s55, s55, 2
	s_add_u32 s53, s53, 0x100
	s_addc_u32 s54, s54, 0
	s_cmp_gt_u32 s55, 41
	s_mov_b64 s[24:25], s[26:27]
	s_barrier
	s_cbranch_scc0 .LBB0_1158
	s_and_b64 vcc, exec, s[10:11]
	s_cbranch_vccz .LBB0_1161
	s_barrier
